# K-loops: all 16 LDS-DMA pieces per iteration use SGPR bases (t+3 bases kept in s98-s101, no VALU left in load segments except the LDS base add), s_setprio flips moved out of the MFMA segments; plus at
# speedup vs baseline: 1.0052x; 1.0052x over previous
; #define PG8_STAGE(bufoff, gbase, voff) do { _Pragma("unroll") for (int _i = 0; _i < 2; ++_i) \
;         __builtin_amdgcn_global_load_lds((const unsigned*)((const char*)(gbase) + (voff)[_i]), (PG8_LAS unsigned*)(lds + (bufoff) + ldsw + _i * 8192), 16, 0, 0); } while (0)
; #define PG8_LDA(dst, b, h) do { _Pragma("unroll") for (int m = 0; m < 4; ++m) _Pragma("unroll") for (int k = 0; k < 2; ++k) dst[m][k] = *(const PG8_LAS bf16x8*)(lds + PG8_SA(b, h) + aoff + m * 2048 + k * 1024); } while (0)
; #define PG8_LDB(dst, b, h) do { _Pragma("unroll") for (int n = 0; n < 2; ++n) _Pragma("unroll") for (int k = 0; k < 2; ++k) dst[n][k] = *(const PG8_LAS bf16x8*)(lds + PG8_SB(b, h) + boff + n * 2048 + k * 1024); } while (0)
; #define PG8_MMA(ai, bj, At, Bt) do { __builtin_amdgcn_s_setprio(1); _Pragma("unroll") for (int m = 0; m < 4; ++m) _Pragma("unroll") for (int n = 0; n < 2; ++n) _Pragma("unroll") for (int k = 0; k < 2; ++k) \
;         acc[ai][bj][m][n] = __builtin_amdgcn_mfma_f32_16x16x32_bf16(Bt[n][k], At[m][k], acc[ai][bj][m][n], 0, 0, 0); __builtin_amdgcn_s_setprio(0); } while (0)
; #define PG8_WAIT_V(n) asm volatile("s_waitcnt vmcnt(" #n ")" ::: "memory")
; #define PG8_WAIT_L(n) asm volatile("s_waitcnt lgkmcnt(" #n ")" ::: "memory")
; #define PG8_BAR __builtin_amdgcn_s_barrier()
; #define PG8_SCHED __builtin_amdgcn_sched_barrier(0)
; template <class Epi, class Sched, bool ALIGN_EPI = false, bool SP2 = false>
; __device__ __forceinline__ void gemm_phase(PG8_LAS unsigned char* lds, const Gemm g, const Sched& S, const Epi& E) {
;     ...
;             PG8_LDB(B0, 0, 0); PG8_LDB(B1, 0, 1); PG8_SCHED; PG8_LDA(At, 0, 0); PG8_STAGE(PG8_SA(1, 1), a1 + hstepA, voffA);
;             PG8_WAIT_V(8); PG8_WAIT_L(0); PG8_BAR; PG8_MMA(0, 0, At, B0); PG8_MMA(0, 1, At, B1); PG8_BAR; PG8_SCHED;
;             PG8_LDA(At, 0, 1); PG8_STAGE(PG8_SB(0, 0), b2, voffB); PG8_STAGE(PG8_SB(0, 1), b2 + hstepB, voffB); PG8_STAGE(PG8_SA(0, 0), a2, voffA);
;             PG8_WAIT_V(8); PG8_WAIT_L(0); PG8_BAR; PG8_MMA(1, 0, At, B0); PG8_MMA(1, 1, At, B1); PG8_BAR; PG8_SCHED;
.LBB0_311:
	ds_read_b128 v[148:151], v176
	ds_read_b128 v[152:155], v176 offset:1024
	ds_read_b128 v[156:159], v176 offset:2048
	ds_read_b128 v[180:183], v176 offset:3072
	ds_read_b128 v[184:187], v177
	ds_read_b128 v[188:191], v177 offset:1024
	ds_read_b128 v[192:195], v177 offset:2048
	ds_read_b128 v[196:199], v177 offset:3072
	s_add_u32 s68, s6, 0xfff80080
	s_addc_u32 s69, s7, -1
	s_cmp_eq_u32 s78, 28
	s_cselect_b32 s71, s20, s69
	s_cselect_b32 s70, s33, s68
	s_cselect_b32 s69, s55, s77
	s_cselect_b32 s68, s61, s76
	s_add_i32 m0, s9, 0xc000
	ds_read_b128 v[200:203], v178
	ds_read_b128 v[204:207], v178 offset:1024
	ds_read_b128 v[208:211], v178 offset:2048
	ds_read_b128 v[212:215], v178 offset:3072
	ds_read_b128 v[216:219], v178 offset:4096
	ds_read_b128 v[220:223], v178 offset:5120
	ds_read_b128 v[224:227], v178 offset:6144
	ds_read_b128 v[228:231], v178 offset:7168
	global_load_lds_dwordx4 v140, s[6:7]
	s_add_i32 m0, s9, 0xe000
	s_nop 0
	global_load_lds_dwordx4 v142, s[6:7]
	s_waitcnt vmcnt(8)
	s_waitcnt lgkmcnt(0)
	s_setprio 0
	s_barrier
	v_mfma_f32_16x16x32_bf16 v[124:127], v[148:151], v[200:203], v[124:127]
	v_mfma_f32_16x16x32_bf16 v[120:123], v[156:159], v[200:203], v[120:123]
	v_mfma_f32_16x16x32_bf16 v[108:111], v[148:151], v[208:211], v[108:111]
	v_mfma_f32_16x16x32_bf16 v[104:107], v[156:159], v[208:211], v[104:107]
	v_mfma_f32_16x16x32_bf16 v[92:95], v[148:151], v[216:219], v[92:95]
	v_mfma_f32_16x16x32_bf16 v[88:91], v[156:159], v[216:219], v[88:91]
	v_mfma_f32_16x16x32_bf16 v[76:79], v[148:151], v[224:227], v[76:79]
	v_mfma_f32_16x16x32_bf16 v[72:75], v[156:159], v[224:227], v[72:75]
	v_mfma_f32_16x16x32_bf16 v[124:127], v[152:155], v[204:207], v[124:127]
	v_mfma_f32_16x16x32_bf16 v[120:123], v[180:183], v[204:207], v[120:123]
	v_mfma_f32_16x16x32_bf16 v[108:111], v[152:155], v[212:215], v[108:111]
	v_mfma_f32_16x16x32_bf16 v[104:107], v[180:183], v[212:215], v[104:107]
	v_mfma_f32_16x16x32_bf16 v[92:95], v[152:155], v[220:223], v[92:95]
	v_mfma_f32_16x16x32_bf16 v[88:91], v[180:183], v[220:223], v[88:91]
	v_mfma_f32_16x16x32_bf16 v[76:79], v[152:155], v[228:231], v[76:79]
	v_mfma_f32_16x16x32_bf16 v[72:75], v[180:183], v[228:231], v[72:75]
	v_mfma_f32_16x16x32_bf16 v[116:119], v[184:187], v[200:203], v[116:119]
	v_mfma_f32_16x16x32_bf16 v[112:115], v[192:195], v[200:203], v[112:115]
	v_mfma_f32_16x16x32_bf16 v[100:103], v[184:187], v[208:211], v[100:103]
	v_mfma_f32_16x16x32_bf16 v[96:99], v[192:195], v[208:211], v[96:99]
	v_mfma_f32_16x16x32_bf16 v[84:87], v[184:187], v[216:219], v[84:87]
	v_mfma_f32_16x16x32_bf16 v[80:83], v[192:195], v[216:219], v[80:83]
	v_mfma_f32_16x16x32_bf16 v[68:71], v[184:187], v[224:227], v[68:71]
	v_mfma_f32_16x16x32_bf16 v[64:67], v[192:195], v[224:227], v[64:67]
	v_mfma_f32_16x16x32_bf16 v[116:119], v[188:191], v[204:207], v[116:119]
	v_mfma_f32_16x16x32_bf16 v[112:115], v[196:199], v[204:207], v[112:115]
	v_mfma_f32_16x16x32_bf16 v[100:103], v[188:191], v[212:215], v[100:103]
	v_mfma_f32_16x16x32_bf16 v[96:99], v[196:199], v[212:215], v[96:99]
	v_mfma_f32_16x16x32_bf16 v[84:87], v[188:191], v[220:223], v[84:87]
	v_mfma_f32_16x16x32_bf16 v[80:83], v[196:199], v[220:223], v[80:83]
	v_mfma_f32_16x16x32_bf16 v[68:71], v[188:191], v[228:231], v[68:71]
	v_mfma_f32_16x16x32_bf16 v[64:67], v[196:199], v[228:231], v[64:67]
	s_barrier
	s_setprio 1
	s_add_u32 s98, s68, s46
	s_addc_u32 s99, s69, s47
	s_add_u32 s100, s70, s46
	s_addc_u32 s101, s71, s47
	s_add_i32 s79, s72, s28
	s_mov_b32 m0, s79
	ds_read_b128 v[200:203], v178 offset:16384
	ds_read_b128 v[204:207], v178 offset:17408
	ds_read_b128 v[208:211], v178 offset:18432
	ds_read_b128 v[212:215], v178 offset:19456
	ds_read_b128 v[216:219], v178 offset:20480
	ds_read_b128 v[220:223], v178 offset:21504
	ds_read_b128 v[224:227], v178 offset:22528
	ds_read_b128 v[228:231], v178 offset:23552
	global_load_lds_dwordx4 v130, s[68:69]
	s_add_i32 m0, s79, 0x2000
	s_add_u32 s80, s68, 0x80000
	s_addc_u32 s81, s69, 0
	s_add_i32 s79, s73, s28
	global_load_lds_dwordx4 v134, s[68:69]
	s_mov_b32 m0, s79
	s_nop 0
	global_load_lds_dwordx4 v130, s[80:81]
	s_add_i32 m0, s79, 0x2000
	s_nop 0
	global_load_lds_dwordx4 v134, s[80:81]
	s_mov_b32 m0, s9
	s_nop 0
	global_load_lds_dwordx4 v128, s[70:71]
	s_mov_b32 m0, s19
	s_nop 0
	global_load_lds_dwordx4 v132, s[70:71]
	s_waitcnt vmcnt(8)
	s_waitcnt lgkmcnt(0)
	s_setprio 0
	s_barrier
	v_mfma_f32_16x16x32_bf16 v[60:63], v[148:151], v[200:203], v[60:63]
	v_mfma_f32_16x16x32_bf16 v[56:59], v[156:159], v[200:203], v[56:59]
	v_mfma_f32_16x16x32_bf16 v[44:47], v[148:151], v[208:211], v[44:47]
	v_mfma_f32_16x16x32_bf16 v[40:43], v[156:159], v[208:211], v[40:43]
	v_mfma_f32_16x16x32_bf16 v[28:31], v[148:151], v[216:219], v[28:31]
	v_mfma_f32_16x16x32_bf16 v[24:27], v[156:159], v[216:219], v[24:27]
	v_mfma_f32_16x16x32_bf16 v[12:15], v[148:151], v[224:227], v[12:15]
	v_mfma_f32_16x16x32_bf16 v[8:11], v[156:159], v[224:227], v[8:11]
	v_mfma_f32_16x16x32_bf16 v[60:63], v[152:155], v[204:207], v[60:63]
	v_mfma_f32_16x16x32_bf16 v[56:59], v[180:183], v[204:207], v[56:59]
	v_mfma_f32_16x16x32_bf16 v[44:47], v[152:155], v[212:215], v[44:47]
	v_mfma_f32_16x16x32_bf16 v[40:43], v[180:183], v[212:215], v[40:43]
	v_mfma_f32_16x16x32_bf16 v[28:31], v[152:155], v[220:223], v[28:31]
	v_mfma_f32_16x16x32_bf16 v[24:27], v[180:183], v[220:223], v[24:27]
	v_mfma_f32_16x16x32_bf16 v[12:15], v[152:155], v[228:231], v[12:15]
	v_mfma_f32_16x16x32_bf16 v[8:11], v[180:183], v[228:231], v[8:11]
	v_mfma_f32_16x16x32_bf16 v[52:55], v[184:187], v[200:203], v[52:55]
	v_mfma_f32_16x16x32_bf16 v[48:51], v[192:195], v[200:203], v[48:51]
	v_mfma_f32_16x16x32_bf16 v[36:39], v[184:187], v[208:211], v[36:39]
	v_mfma_f32_16x16x32_bf16 v[32:35], v[192:195], v[208:211], v[32:35]
	v_mfma_f32_16x16x32_bf16 v[20:23], v[184:187], v[216:219], v[20:23]
	v_mfma_f32_16x16x32_bf16 v[16:19], v[192:195], v[216:219], v[16:19]
	v_mfma_f32_16x16x32_bf16 v[4:7], v[184:187], v[224:227], v[4:7]
	v_mfma_f32_16x16x32_bf16 v[0:3], v[192:195], v[224:227], v[0:3]
	v_mfma_f32_16x16x32_bf16 v[52:55], v[188:191], v[204:207], v[52:55]
	v_mfma_f32_16x16x32_bf16 v[48:51], v[196:199], v[204:207], v[48:51]
	v_mfma_f32_16x16x32_bf16 v[36:39], v[188:191], v[212:215], v[36:39]
	v_mfma_f32_16x16x32_bf16 v[32:35], v[196:199], v[212:215], v[32:35]
	v_mfma_f32_16x16x32_bf16 v[20:23], v[188:191], v[220:223], v[20:23]
	v_mfma_f32_16x16x32_bf16 v[16:19], v[196:199], v[220:223], v[16:19]
	v_mfma_f32_16x16x32_bf16 v[4:7], v[188:191], v[228:231], v[4:7]
	v_mfma_f32_16x16x32_bf16 v[0:3], v[196:199], v[228:231], v[0:3]
	s_barrier
; #define PG8_STAGE(bufoff, gbase, voff) do { _Pragma("unroll") for (int _i = 0; _i < 2; ++_i) \
;         __builtin_amdgcn_global_load_lds((const unsigned*)((const char*)(gbase) + (voff)[_i]), (PG8_LAS unsigned*)(lds + (bufoff) + ldsw + _i * 8192), 16, 0, 0); } while (0)
; #define PG8_LDA(dst, b, h) do { _Pragma("unroll") for (int m = 0; m < 4; ++m) _Pragma("unroll") for (int k = 0; k < 2; ++k) dst[m][k] = *(const PG8_LAS bf16x8*)(lds + PG8_SA(b, h) + aoff + m * 2048 + k * 1024); } while (0)
; #define PG8_LDB(dst, b, h) do { _Pragma("unroll") for (int n = 0; n < 2; ++n) _Pragma("unroll") for (int k = 0; k < 2; ++k) dst[n][k] = *(const PG8_LAS bf16x8*)(lds + PG8_SB(b, h) + boff + n * 2048 + k * 1024); } while (0)
; #define PG8_MMA(ai, bj, At, Bt) do { __builtin_amdgcn_s_setprio(1); _Pragma("unroll") for (int m = 0; m < 4; ++m) _Pragma("unroll") for (int n = 0; n < 2; ++n) _Pragma("unroll") for (int k = 0; k < 2; ++k) \
;         acc[ai][bj][m][n] = __builtin_amdgcn_mfma_f32_16x16x32_bf16(Bt[n][k], At[m][k], acc[ai][bj][m][n], 0, 0, 0); __builtin_amdgcn_s_setprio(0); } while (0)
; #define PG8_WAIT_V(n) asm volatile("s_waitcnt vmcnt(" #n ")" ::: "memory")
; #define PG8_WAIT_L(n) asm volatile("s_waitcnt lgkmcnt(" #n ")" ::: "memory")
; #define PG8_BAR __builtin_amdgcn_s_barrier()
; #define PG8_SCHED __builtin_amdgcn_sched_barrier(0)
; template <class Epi, class Sched, bool ALIGN_EPI = false, bool SP2 = false>
; __device__ __forceinline__ void gemm_phase(PG8_LAS unsigned char* lds, const Gemm g, const Sched& S, const Epi& E) {
;     ...
;             PG8_LDB(B0, 1, 0); PG8_LDB(B1, 1, 1); PG8_SCHED; PG8_LDA(At, 1, 0); PG8_STAGE(PG8_SA(0, 1), a2 + hstepA, voffA);
;             PG8_WAIT_V(8); PG8_WAIT_L(0); PG8_BAR; PG8_MMA(0, 0, At, B0); PG8_MMA(0, 1, At, B1); PG8_BAR; PG8_SCHED;
;             PG8_LDA(At, 1, 1); PG8_STAGE(PG8_SB(1, 0), b3, voffB); PG8_STAGE(PG8_SB(1, 1), b3 + hstepB, voffB); PG8_STAGE(PG8_SA(1, 0), a3, voffA);
;             PG8_WAIT_V(8); PG8_WAIT_L(0); PG8_BAR; PG8_MMA(1, 0, At, B0); PG8_MMA(1, 1, At, B1); PG8_BAR; PG8_SCHED;
;     ...
;         if constexpr (ALIGN_EPI) { if (wr == 0) PG8_BAR; }
	s_setprio 1
	s_add_i32 s79, 0, 0x18000
	v_add_u32_e32 v138, s79, v174
	s_add_i32 s80, 0, 0x1c000
	ds_read_b128 v[148:151], v138
	ds_read_b128 v[152:155], v138 offset:1024
	ds_read_b128 v[156:159], v138 offset:2048
	ds_read_b128 v[180:183], v138 offset:3072
	v_add_u32_e32 v138, s80, v174
	ds_read_b128 v[184:187], v138
	ds_read_b128 v[188:191], v138 offset:1024
	ds_read_b128 v[192:195], v138 offset:2048
	ds_read_b128 v[196:199], v138 offset:3072
	s_add_u32 s70, s70, 0x80000
	s_addc_u32 s71, s71, 0
	s_mov_b32 m0, s29
	ds_read_b128 v[200:203], v178 offset:32768
	ds_read_b128 v[204:207], v178 offset:33792
	ds_read_b128 v[208:211], v178 offset:34816
	ds_read_b128 v[212:215], v178 offset:35840
	ds_read_b128 v[216:219], v178 offset:36864
	ds_read_b128 v[220:223], v178 offset:37888
	ds_read_b128 v[224:227], v178 offset:38912
	ds_read_b128 v[228:231], v178 offset:39936
	global_load_lds_dwordx4 v128, s[70:71]
	s_mov_b32 m0, s30
	s_nop 0
	global_load_lds_dwordx4 v132, s[70:71]
	s_waitcnt vmcnt(8)
	s_waitcnt lgkmcnt(0)
	s_setprio 0
	s_barrier
	v_mfma_f32_16x16x32_bf16 v[124:127], v[148:151], v[200:203], v[124:127]
	v_mfma_f32_16x16x32_bf16 v[120:123], v[156:159], v[200:203], v[120:123]
	v_mfma_f32_16x16x32_bf16 v[108:111], v[148:151], v[208:211], v[108:111]
	v_mfma_f32_16x16x32_bf16 v[104:107], v[156:159], v[208:211], v[104:107]
	v_mfma_f32_16x16x32_bf16 v[92:95], v[148:151], v[216:219], v[92:95]
	v_mfma_f32_16x16x32_bf16 v[88:91], v[156:159], v[216:219], v[88:91]
	v_mfma_f32_16x16x32_bf16 v[76:79], v[148:151], v[224:227], v[76:79]
	v_mfma_f32_16x16x32_bf16 v[72:75], v[156:159], v[224:227], v[72:75]
	v_mfma_f32_16x16x32_bf16 v[124:127], v[152:155], v[204:207], v[124:127]
	v_mfma_f32_16x16x32_bf16 v[120:123], v[180:183], v[204:207], v[120:123]
	v_mfma_f32_16x16x32_bf16 v[108:111], v[152:155], v[212:215], v[108:111]
	v_mfma_f32_16x16x32_bf16 v[104:107], v[180:183], v[212:215], v[104:107]
	v_mfma_f32_16x16x32_bf16 v[92:95], v[152:155], v[220:223], v[92:95]
	v_mfma_f32_16x16x32_bf16 v[88:91], v[180:183], v[220:223], v[88:91]
	v_mfma_f32_16x16x32_bf16 v[76:79], v[152:155], v[228:231], v[76:79]
	v_mfma_f32_16x16x32_bf16 v[72:75], v[180:183], v[228:231], v[72:75]
	v_mfma_f32_16x16x32_bf16 v[116:119], v[184:187], v[200:203], v[116:119]
	v_mfma_f32_16x16x32_bf16 v[112:115], v[192:195], v[200:203], v[112:115]
	v_mfma_f32_16x16x32_bf16 v[100:103], v[184:187], v[208:211], v[100:103]
	v_mfma_f32_16x16x32_bf16 v[96:99], v[192:195], v[208:211], v[96:99]
	v_mfma_f32_16x16x32_bf16 v[84:87], v[184:187], v[216:219], v[84:87]
	v_mfma_f32_16x16x32_bf16 v[80:83], v[192:195], v[216:219], v[80:83]
	v_mfma_f32_16x16x32_bf16 v[68:71], v[184:187], v[224:227], v[68:71]
	v_mfma_f32_16x16x32_bf16 v[64:67], v[192:195], v[224:227], v[64:67]
	v_mfma_f32_16x16x32_bf16 v[116:119], v[188:191], v[204:207], v[116:119]
	v_mfma_f32_16x16x32_bf16 v[112:115], v[196:199], v[204:207], v[112:115]
	v_mfma_f32_16x16x32_bf16 v[100:103], v[188:191], v[212:215], v[100:103]
	v_mfma_f32_16x16x32_bf16 v[96:99], v[196:199], v[212:215], v[96:99]
	v_mfma_f32_16x16x32_bf16 v[84:87], v[188:191], v[220:223], v[84:87]
	v_mfma_f32_16x16x32_bf16 v[80:83], v[196:199], v[220:223], v[80:83]
	v_mfma_f32_16x16x32_bf16 v[68:71], v[188:191], v[228:231], v[68:71]
	v_mfma_f32_16x16x32_bf16 v[64:67], v[196:199], v[228:231], v[64:67]
	s_barrier
	s_setprio 1
	s_add_i32 s70, s79, s28
	s_mov_b32 m0, s70
	ds_read_b128 v[200:203], v178 offset:49152
	ds_read_b128 v[204:207], v178 offset:50176
	ds_read_b128 v[208:211], v178 offset:51200
	ds_read_b128 v[212:215], v178 offset:52224
	ds_read_b128 v[216:219], v178 offset:53248
	ds_read_b128 v[220:223], v178 offset:54272
	ds_read_b128 v[224:227], v178 offset:55296
	ds_read_b128 v[228:231], v178 offset:56320
	global_load_lds_dwordx4 v130, s[98:99]
	s_add_i32 m0, s70, 0x2000
	s_add_u32 s68, s68, 0x80080
	s_addc_u32 s69, s69, 0
	s_add_i32 s70, s80, s28
	global_load_lds_dwordx4 v134, s[98:99]
	s_mov_b32 m0, s70
	s_nop 0
	global_load_lds_dwordx4 v130, s[68:69]
	s_add_i32 m0, s70, 0x2000
	s_nop 0
	global_load_lds_dwordx4 v134, s[68:69]
	s_mov_b32 m0, s34
	s_nop 0
	global_load_lds_dwordx4 v128, s[100:101]
	s_mov_b32 m0, s35
	s_nop 0
	global_load_lds_dwordx4 v132, s[100:101]
	s_waitcnt vmcnt(8)
	s_waitcnt lgkmcnt(0)
	s_setprio 0
	s_barrier
	v_mfma_f32_16x16x32_bf16 v[60:63], v[148:151], v[200:203], v[60:63]
	v_mfma_f32_16x16x32_bf16 v[56:59], v[156:159], v[200:203], v[56:59]
	v_mfma_f32_16x16x32_bf16 v[44:47], v[148:151], v[208:211], v[44:47]
	v_mfma_f32_16x16x32_bf16 v[40:43], v[156:159], v[208:211], v[40:43]
	v_mfma_f32_16x16x32_bf16 v[28:31], v[148:151], v[216:219], v[28:31]
	v_mfma_f32_16x16x32_bf16 v[24:27], v[156:159], v[216:219], v[24:27]
	v_mfma_f32_16x16x32_bf16 v[12:15], v[148:151], v[224:227], v[12:15]
	v_mfma_f32_16x16x32_bf16 v[8:11], v[156:159], v[224:227], v[8:11]
	v_mfma_f32_16x16x32_bf16 v[60:63], v[152:155], v[204:207], v[60:63]
	v_mfma_f32_16x16x32_bf16 v[56:59], v[180:183], v[204:207], v[56:59]
	v_mfma_f32_16x16x32_bf16 v[44:47], v[152:155], v[212:215], v[44:47]
	v_mfma_f32_16x16x32_bf16 v[40:43], v[180:183], v[212:215], v[40:43]
	v_mfma_f32_16x16x32_bf16 v[28:31], v[152:155], v[220:223], v[28:31]
	v_mfma_f32_16x16x32_bf16 v[24:27], v[180:183], v[220:223], v[24:27]
	v_mfma_f32_16x16x32_bf16 v[12:15], v[152:155], v[228:231], v[12:15]
	v_mfma_f32_16x16x32_bf16 v[8:11], v[180:183], v[228:231], v[8:11]
	v_mfma_f32_16x16x32_bf16 v[52:55], v[184:187], v[200:203], v[52:55]
	v_mfma_f32_16x16x32_bf16 v[48:51], v[192:195], v[200:203], v[48:51]
	v_mfma_f32_16x16x32_bf16 v[36:39], v[184:187], v[208:211], v[36:39]
	v_mfma_f32_16x16x32_bf16 v[32:35], v[192:195], v[208:211], v[32:35]
	v_mfma_f32_16x16x32_bf16 v[20:23], v[184:187], v[216:219], v[20:23]
	v_mfma_f32_16x16x32_bf16 v[16:19], v[192:195], v[216:219], v[16:19]
	v_mfma_f32_16x16x32_bf16 v[4:7], v[184:187], v[224:227], v[4:7]
	v_mfma_f32_16x16x32_bf16 v[0:3], v[192:195], v[224:227], v[0:3]
	v_mfma_f32_16x16x32_bf16 v[52:55], v[188:191], v[204:207], v[52:55]
	v_mfma_f32_16x16x32_bf16 v[48:51], v[196:199], v[204:207], v[48:51]
	v_mfma_f32_16x16x32_bf16 v[36:39], v[188:191], v[212:215], v[36:39]
	v_mfma_f32_16x16x32_bf16 v[32:35], v[196:199], v[212:215], v[32:35]
	v_mfma_f32_16x16x32_bf16 v[20:23], v[188:191], v[220:223], v[20:23]
	v_mfma_f32_16x16x32_bf16 v[16:19], v[196:199], v[220:223], v[16:19]
	v_mfma_f32_16x16x32_bf16 v[4:7], v[188:191], v[228:231], v[4:7]
	v_mfma_f32_16x16x32_bf16 v[0:3], v[196:199], v[228:231], v[0:3]
	s_barrier
	s_setprio 1
	s_add_i32 s78, s78, 2
	s_add_u32 s6, s6, 0x100
	s_addc_u32 s7, s7, 0
	s_add_u32 s76, s76, 0x100
	s_addc_u32 s77, s77, 0
	s_cmp_gt_u32 s78, 29
	s_cbranch_scc0 .LBB0_311
	s_and_b64 vcc, exec, s[48:49]
	s_cbranch_vccz .LBB0_314
	s_barrier

; #define PG8_STAGE(bufoff, gbase, voff) do { _Pragma("unroll") for (int _i = 0; _i < 2; ++_i) \
;         __builtin_amdgcn_global_load_lds((const unsigned*)((const char*)(gbase) + (voff)[_i]), (PG8_LAS unsigned*)(lds + (bufoff) + ldsw + _i * 8192), 16, 0, 0); } while (0)
; #define PG8_LDA(dst, b, h) do { _Pragma("unroll") for (int m = 0; m < 4; ++m) _Pragma("unroll") for (int k = 0; k < 2; ++k) dst[m][k] = *(const PG8_LAS bf16x8*)(lds + PG8_SA(b, h) + aoff + m * 2048 + k * 1024); } while (0)
; #define PG8_LDB(dst, b, h) do { _Pragma("unroll") for (int n = 0; n < 2; ++n) _Pragma("unroll") for (int k = 0; k < 2; ++k) dst[n][k] = *(const PG8_LAS bf16x8*)(lds + PG8_SB(b, h) + boff + n * 2048 + k * 1024); } while (0)
; #define PG8_MMA(ai, bj, At, Bt) do { __builtin_amdgcn_s_setprio(1); _Pragma("unroll") for (int m = 0; m < 4; ++m) _Pragma("unroll") for (int n = 0; n < 2; ++n) _Pragma("unroll") for (int k = 0; k < 2; ++k) \
;         acc[ai][bj][m][n] = __builtin_amdgcn_mfma_f32_16x16x32_bf16(Bt[n][k], At[m][k], acc[ai][bj][m][n], 0, 0, 0); __builtin_amdgcn_s_setprio(0); } while (0)
; #define PG8_WAIT_V(n) asm volatile("s_waitcnt vmcnt(" #n ")" ::: "memory")
; #define PG8_WAIT_L(n) asm volatile("s_waitcnt lgkmcnt(" #n ")" ::: "memory")
; #define PG8_BAR __builtin_amdgcn_s_barrier()
; #define PG8_SCHED __builtin_amdgcn_sched_barrier(0)
; template <class Epi, class Sched, bool ALIGN_EPI = false, bool SP2 = false>
; __device__ __forceinline__ void gemm_phase(PG8_LAS unsigned char* lds, const Gemm g, const Sched& S, const Epi& E) {
;     ...
;             PG8_LDB(B0, 0, 0); PG8_LDB(B1, 0, 1); PG8_SCHED; PG8_LDA(At, 0, 0); PG8_STAGE(PG8_SA(1, 1), a1 + hstepA, voffA);
;             PG8_WAIT_V(8); PG8_WAIT_L(0); PG8_BAR; PG8_MMA(0, 0, At, B0); PG8_MMA(0, 1, At, B1); PG8_BAR; PG8_SCHED;
;             PG8_LDA(At, 0, 1); PG8_STAGE(PG8_SB(0, 0), b2, voffB); PG8_STAGE(PG8_SB(0, 1), b2 + hstepB, voffB); PG8_STAGE(PG8_SA(0, 0), a2, voffA);
;             PG8_WAIT_V(8); PG8_WAIT_L(0); PG8_BAR; PG8_MMA(1, 0, At, B0); PG8_MMA(1, 1, At, B1); PG8_BAR; PG8_SCHED;
.LBB0_497:
	ds_read_b128 v[146:149], v155
	ds_read_b128 v[158:161], v155 offset:1024
	ds_read_b128 v[168:171], v155 offset:2048
	ds_read_b128 v[172:175], v155 offset:3072
	ds_read_b128 v[176:179], v156
	ds_read_b128 v[180:183], v156 offset:1024
	ds_read_b128 v[184:187], v156 offset:2048
	ds_read_b128 v[188:191], v156 offset:3072
	s_add_u32 s41, s54, 0xfff80080
	s_addc_u32 s43, s55, -1
	s_cmp_eq_u32 s34, 28
	s_cselect_b32 s63, s7, s43
	s_cselect_b32 s62, s28, s41
	s_cselect_b32 s61, s29, s33
	s_cselect_b32 s60, s30, s31
	s_add_i32 m0, s69, 0xc000
	ds_read_b128 v[192:195], v157
	ds_read_b128 v[196:199], v157 offset:1024
	ds_read_b128 v[200:203], v157 offset:2048
	ds_read_b128 v[204:207], v157 offset:3072
	ds_read_b128 v[208:211], v157 offset:4096
	ds_read_b128 v[212:215], v157 offset:5120
	ds_read_b128 v[216:219], v157 offset:6144
	ds_read_b128 v[220:223], v157 offset:7168
	global_load_lds_dwordx4 v138, s[54:55]
	s_add_i32 m0, s69, 0xe000
	s_nop 0
	global_load_lds_dwordx4 v140, s[54:55]
	s_waitcnt vmcnt(8)
	s_waitcnt lgkmcnt(0)
	s_setprio 0
	s_barrier
	v_mfma_f32_16x16x32_bf16 v[124:127], v[146:149], v[192:195], v[124:127]
	v_mfma_f32_16x16x32_bf16 v[120:123], v[168:171], v[192:195], v[120:123]
	v_mfma_f32_16x16x32_bf16 v[108:111], v[146:149], v[200:203], v[108:111]
	v_mfma_f32_16x16x32_bf16 v[104:107], v[168:171], v[200:203], v[104:107]
	v_mfma_f32_16x16x32_bf16 v[92:95], v[146:149], v[208:211], v[92:95]
	v_mfma_f32_16x16x32_bf16 v[88:91], v[168:171], v[208:211], v[88:91]
	v_mfma_f32_16x16x32_bf16 v[76:79], v[146:149], v[216:219], v[76:79]
	v_mfma_f32_16x16x32_bf16 v[72:75], v[168:171], v[216:219], v[72:75]
	v_mfma_f32_16x16x32_bf16 v[124:127], v[158:161], v[196:199], v[124:127]
	v_mfma_f32_16x16x32_bf16 v[120:123], v[172:175], v[196:199], v[120:123]
	v_mfma_f32_16x16x32_bf16 v[108:111], v[158:161], v[204:207], v[108:111]
	v_mfma_f32_16x16x32_bf16 v[104:107], v[172:175], v[204:207], v[104:107]
	v_mfma_f32_16x16x32_bf16 v[92:95], v[158:161], v[212:215], v[92:95]
	v_mfma_f32_16x16x32_bf16 v[88:91], v[172:175], v[212:215], v[88:91]
	v_mfma_f32_16x16x32_bf16 v[76:79], v[158:161], v[220:223], v[76:79]
	v_mfma_f32_16x16x32_bf16 v[72:75], v[172:175], v[220:223], v[72:75]
	v_mfma_f32_16x16x32_bf16 v[116:119], v[176:179], v[192:195], v[116:119]
	v_mfma_f32_16x16x32_bf16 v[112:115], v[184:187], v[192:195], v[112:115]
	v_mfma_f32_16x16x32_bf16 v[100:103], v[176:179], v[200:203], v[100:103]
	v_mfma_f32_16x16x32_bf16 v[96:99], v[184:187], v[200:203], v[96:99]
	v_mfma_f32_16x16x32_bf16 v[84:87], v[176:179], v[208:211], v[84:87]
	v_mfma_f32_16x16x32_bf16 v[80:83], v[184:187], v[208:211], v[80:83]
	v_mfma_f32_16x16x32_bf16 v[68:71], v[176:179], v[216:219], v[68:71]
	v_mfma_f32_16x16x32_bf16 v[64:67], v[184:187], v[216:219], v[64:67]
	v_mfma_f32_16x16x32_bf16 v[116:119], v[180:183], v[196:199], v[116:119]
	v_mfma_f32_16x16x32_bf16 v[112:115], v[188:191], v[196:199], v[112:115]
	v_mfma_f32_16x16x32_bf16 v[100:103], v[180:183], v[204:207], v[100:103]
	v_mfma_f32_16x16x32_bf16 v[96:99], v[188:191], v[204:207], v[96:99]
	v_mfma_f32_16x16x32_bf16 v[84:87], v[180:183], v[212:215], v[84:87]
	v_mfma_f32_16x16x32_bf16 v[80:83], v[188:191], v[212:215], v[80:83]
	v_mfma_f32_16x16x32_bf16 v[68:71], v[180:183], v[220:223], v[68:71]
	v_mfma_f32_16x16x32_bf16 v[64:67], v[188:191], v[220:223], v[64:67]
	s_barrier
	s_setprio 1
	s_add_u32 s98, s60, s20
	s_addc_u32 s99, s61, s21
	s_add_u32 s100, s62, s20
	s_addc_u32 s101, s63, s21
	s_add_i32 s41, s81, s68
	s_mov_b32 m0, s41
	ds_read_b128 v[192:195], v157 offset:16384
	ds_read_b128 v[196:199], v157 offset:17408
	ds_read_b128 v[200:203], v157 offset:18432
	ds_read_b128 v[204:207], v157 offset:19456
	ds_read_b128 v[208:211], v157 offset:20480
	ds_read_b128 v[212:215], v157 offset:21504
	ds_read_b128 v[216:219], v157 offset:22528
	ds_read_b128 v[220:223], v157 offset:23552
	global_load_lds_dwordx4 v130, s[60:61]
	s_add_i32 m0, s41, 0x2000
	s_add_u32 s84, s60, 0x80000
	s_addc_u32 s85, s61, 0
	s_add_i32 s41, s82, s68
	global_load_lds_dwordx4 v134, s[60:61]
	s_mov_b32 m0, s41
	s_nop 0
	global_load_lds_dwordx4 v130, s[84:85]
	s_add_i32 m0, s41, 0x2000
	s_nop 0
	global_load_lds_dwordx4 v134, s[84:85]
	s_mov_b32 m0, s69
	s_nop 0
	global_load_lds_dwordx4 v128, s[62:63]
	s_mov_b32 m0, s70
	s_nop 0
	global_load_lds_dwordx4 v132, s[62:63]
	s_waitcnt vmcnt(8)
	s_waitcnt lgkmcnt(0)
	s_setprio 0
	s_barrier
	v_mfma_f32_16x16x32_bf16 v[60:63], v[146:149], v[192:195], v[60:63]
	v_mfma_f32_16x16x32_bf16 v[56:59], v[168:171], v[192:195], v[56:59]
	v_mfma_f32_16x16x32_bf16 v[44:47], v[146:149], v[200:203], v[44:47]
	v_mfma_f32_16x16x32_bf16 v[40:43], v[168:171], v[200:203], v[40:43]
	v_mfma_f32_16x16x32_bf16 v[28:31], v[146:149], v[208:211], v[28:31]
	v_mfma_f32_16x16x32_bf16 v[24:27], v[168:171], v[208:211], v[24:27]
	v_mfma_f32_16x16x32_bf16 v[12:15], v[146:149], v[216:219], v[12:15]
	v_mfma_f32_16x16x32_bf16 v[8:11], v[168:171], v[216:219], v[8:11]
	v_mfma_f32_16x16x32_bf16 v[60:63], v[158:161], v[196:199], v[60:63]
	v_mfma_f32_16x16x32_bf16 v[56:59], v[172:175], v[196:199], v[56:59]
	v_mfma_f32_16x16x32_bf16 v[44:47], v[158:161], v[204:207], v[44:47]
	v_mfma_f32_16x16x32_bf16 v[40:43], v[172:175], v[204:207], v[40:43]
	v_mfma_f32_16x16x32_bf16 v[28:31], v[158:161], v[212:215], v[28:31]
	v_mfma_f32_16x16x32_bf16 v[24:27], v[172:175], v[212:215], v[24:27]
	v_mfma_f32_16x16x32_bf16 v[12:15], v[158:161], v[220:223], v[12:15]
	v_mfma_f32_16x16x32_bf16 v[8:11], v[172:175], v[220:223], v[8:11]
	v_mfma_f32_16x16x32_bf16 v[52:55], v[176:179], v[192:195], v[52:55]
	v_mfma_f32_16x16x32_bf16 v[48:51], v[184:187], v[192:195], v[48:51]
	v_mfma_f32_16x16x32_bf16 v[36:39], v[176:179], v[200:203], v[36:39]
	v_mfma_f32_16x16x32_bf16 v[32:35], v[184:187], v[200:203], v[32:35]
	v_mfma_f32_16x16x32_bf16 v[20:23], v[176:179], v[208:211], v[20:23]
	v_mfma_f32_16x16x32_bf16 v[16:19], v[184:187], v[208:211], v[16:19]
	v_mfma_f32_16x16x32_bf16 v[4:7], v[176:179], v[216:219], v[4:7]
	v_mfma_f32_16x16x32_bf16 v[0:3], v[184:187], v[216:219], v[0:3]
	v_mfma_f32_16x16x32_bf16 v[52:55], v[180:183], v[196:199], v[52:55]
	v_mfma_f32_16x16x32_bf16 v[48:51], v[188:191], v[196:199], v[48:51]
	v_mfma_f32_16x16x32_bf16 v[36:39], v[180:183], v[204:207], v[36:39]
	v_mfma_f32_16x16x32_bf16 v[32:35], v[188:191], v[204:207], v[32:35]
	v_mfma_f32_16x16x32_bf16 v[20:23], v[180:183], v[212:215], v[20:23]
	v_mfma_f32_16x16x32_bf16 v[16:19], v[188:191], v[212:215], v[16:19]
	v_mfma_f32_16x16x32_bf16 v[4:7], v[180:183], v[220:223], v[4:7]
	v_mfma_f32_16x16x32_bf16 v[0:3], v[188:191], v[220:223], v[0:3]
	s_barrier
; #define PG8_STAGE(bufoff, gbase, voff) do { _Pragma("unroll") for (int _i = 0; _i < 2; ++_i) \
;         __builtin_amdgcn_global_load_lds((const unsigned*)((const char*)(gbase) + (voff)[_i]), (PG8_LAS unsigned*)(lds + (bufoff) + ldsw + _i * 8192), 16, 0, 0); } while (0)
; #define PG8_LDA(dst, b, h) do { _Pragma("unroll") for (int m = 0; m < 4; ++m) _Pragma("unroll") for (int k = 0; k < 2; ++k) dst[m][k] = *(const PG8_LAS bf16x8*)(lds + PG8_SA(b, h) + aoff + m * 2048 + k * 1024); } while (0)
; #define PG8_LDB(dst, b, h) do { _Pragma("unroll") for (int n = 0; n < 2; ++n) _Pragma("unroll") for (int k = 0; k < 2; ++k) dst[n][k] = *(const PG8_LAS bf16x8*)(lds + PG8_SB(b, h) + boff + n * 2048 + k * 1024); } while (0)
; #define PG8_MMA(ai, bj, At, Bt) do { __builtin_amdgcn_s_setprio(1); _Pragma("unroll") for (int m = 0; m < 4; ++m) _Pragma("unroll") for (int n = 0; n < 2; ++n) _Pragma("unroll") for (int k = 0; k < 2; ++k) \
;         acc[ai][bj][m][n] = __builtin_amdgcn_mfma_f32_16x16x32_bf16(Bt[n][k], At[m][k], acc[ai][bj][m][n], 0, 0, 0); __builtin_amdgcn_s_setprio(0); } while (0)
; #define PG8_WAIT_V(n) asm volatile("s_waitcnt vmcnt(" #n ")" ::: "memory")
; #define PG8_WAIT_L(n) asm volatile("s_waitcnt lgkmcnt(" #n ")" ::: "memory")
; #define PG8_BAR __builtin_amdgcn_s_barrier()
; #define PG8_SCHED __builtin_amdgcn_sched_barrier(0)
; template <class Epi, class Sched, bool ALIGN_EPI = false, bool SP2 = false>
; __device__ __forceinline__ void gemm_phase(PG8_LAS unsigned char* lds, const Gemm g, const Sched& S, const Epi& E) {
;     ...
;             PG8_LDB(B0, 1, 0); PG8_LDB(B1, 1, 1); PG8_SCHED; PG8_LDA(At, 1, 0); PG8_STAGE(PG8_SA(0, 1), a2 + hstepA, voffA);
;             PG8_WAIT_V(8); PG8_WAIT_L(0); PG8_BAR; PG8_MMA(0, 0, At, B0); PG8_MMA(0, 1, At, B1); PG8_BAR; PG8_SCHED;
;             PG8_LDA(At, 1, 1); PG8_STAGE(PG8_SB(1, 0), b3, voffB); PG8_STAGE(PG8_SB(1, 1), b3 + hstepB, voffB); PG8_STAGE(PG8_SA(1, 0), a3, voffA);
;             PG8_WAIT_V(8); PG8_WAIT_L(0); PG8_BAR; PG8_MMA(1, 0, At, B0); PG8_MMA(1, 1, At, B1); PG8_BAR; PG8_SCHED;
;     ...
;         if constexpr (ALIGN_EPI) { if (wr == 0) PG8_BAR; }
	s_setprio 1
	s_add_i32 s41, 0, 0x18000
	v_add_u32_e32 v136, s41, v153
	s_add_i32 s43, 0, 0x1c000
	ds_read_b128 v[146:149], v136
	ds_read_b128 v[158:161], v136 offset:1024
	ds_read_b128 v[168:171], v136 offset:2048
	ds_read_b128 v[172:175], v136 offset:3072
	v_add_u32_e32 v136, s43, v153
	ds_read_b128 v[176:179], v136
	ds_read_b128 v[180:183], v136 offset:1024
	ds_read_b128 v[184:187], v136 offset:2048
	ds_read_b128 v[188:191], v136 offset:3072
	s_add_u32 s62, s62, 0x80000
	s_addc_u32 s63, s63, 0
	s_mov_b32 m0, s71
	ds_read_b128 v[192:195], v157 offset:32768
	ds_read_b128 v[196:199], v157 offset:33792
	ds_read_b128 v[200:203], v157 offset:34816
	ds_read_b128 v[204:207], v157 offset:35840
	ds_read_b128 v[208:211], v157 offset:36864
	ds_read_b128 v[212:215], v157 offset:37888
	ds_read_b128 v[216:219], v157 offset:38912
	ds_read_b128 v[220:223], v157 offset:39936
	global_load_lds_dwordx4 v128, s[62:63]
	s_mov_b32 m0, s72
	s_nop 0
	global_load_lds_dwordx4 v132, s[62:63]
	s_waitcnt vmcnt(8)
	s_waitcnt lgkmcnt(0)
	s_setprio 0
	s_barrier
	v_mfma_f32_16x16x32_bf16 v[124:127], v[146:149], v[192:195], v[124:127]
	v_mfma_f32_16x16x32_bf16 v[120:123], v[168:171], v[192:195], v[120:123]
	v_mfma_f32_16x16x32_bf16 v[108:111], v[146:149], v[200:203], v[108:111]
	v_mfma_f32_16x16x32_bf16 v[104:107], v[168:171], v[200:203], v[104:107]
	v_mfma_f32_16x16x32_bf16 v[92:95], v[146:149], v[208:211], v[92:95]
	v_mfma_f32_16x16x32_bf16 v[88:91], v[168:171], v[208:211], v[88:91]
	v_mfma_f32_16x16x32_bf16 v[76:79], v[146:149], v[216:219], v[76:79]
	v_mfma_f32_16x16x32_bf16 v[72:75], v[168:171], v[216:219], v[72:75]
	v_mfma_f32_16x16x32_bf16 v[124:127], v[158:161], v[196:199], v[124:127]
	v_mfma_f32_16x16x32_bf16 v[120:123], v[172:175], v[196:199], v[120:123]
	v_mfma_f32_16x16x32_bf16 v[108:111], v[158:161], v[204:207], v[108:111]
	v_mfma_f32_16x16x32_bf16 v[104:107], v[172:175], v[204:207], v[104:107]
	v_mfma_f32_16x16x32_bf16 v[92:95], v[158:161], v[212:215], v[92:95]
	v_mfma_f32_16x16x32_bf16 v[88:91], v[172:175], v[212:215], v[88:91]
	v_mfma_f32_16x16x32_bf16 v[76:79], v[158:161], v[220:223], v[76:79]
	v_mfma_f32_16x16x32_bf16 v[72:75], v[172:175], v[220:223], v[72:75]
	v_mfma_f32_16x16x32_bf16 v[116:119], v[176:179], v[192:195], v[116:119]
	v_mfma_f32_16x16x32_bf16 v[112:115], v[184:187], v[192:195], v[112:115]
	v_mfma_f32_16x16x32_bf16 v[100:103], v[176:179], v[200:203], v[100:103]
	v_mfma_f32_16x16x32_bf16 v[96:99], v[184:187], v[200:203], v[96:99]
	v_mfma_f32_16x16x32_bf16 v[84:87], v[176:179], v[208:211], v[84:87]
	v_mfma_f32_16x16x32_bf16 v[80:83], v[184:187], v[208:211], v[80:83]
	v_mfma_f32_16x16x32_bf16 v[68:71], v[176:179], v[216:219], v[68:71]
	v_mfma_f32_16x16x32_bf16 v[64:67], v[184:187], v[216:219], v[64:67]
	v_mfma_f32_16x16x32_bf16 v[116:119], v[180:183], v[196:199], v[116:119]
	v_mfma_f32_16x16x32_bf16 v[112:115], v[188:191], v[196:199], v[112:115]
	v_mfma_f32_16x16x32_bf16 v[100:103], v[180:183], v[204:207], v[100:103]
	v_mfma_f32_16x16x32_bf16 v[96:99], v[188:191], v[204:207], v[96:99]
	v_mfma_f32_16x16x32_bf16 v[84:87], v[180:183], v[212:215], v[84:87]
	v_mfma_f32_16x16x32_bf16 v[80:83], v[188:191], v[212:215], v[80:83]
	v_mfma_f32_16x16x32_bf16 v[68:71], v[180:183], v[220:223], v[68:71]
	v_mfma_f32_16x16x32_bf16 v[64:67], v[188:191], v[220:223], v[64:67]
	s_barrier
	s_setprio 1
	s_add_i32 s41, s41, s68
	s_mov_b32 m0, s41
	ds_read_b128 v[192:195], v157 offset:49152
	ds_read_b128 v[196:199], v157 offset:50176
	ds_read_b128 v[200:203], v157 offset:51200
	ds_read_b128 v[204:207], v157 offset:52224
	ds_read_b128 v[208:211], v157 offset:53248
	ds_read_b128 v[212:215], v157 offset:54272
	ds_read_b128 v[216:219], v157 offset:55296
	ds_read_b128 v[220:223], v157 offset:56320
	global_load_lds_dwordx4 v130, s[98:99]
	s_add_i32 m0, s41, 0x2000
	s_add_u32 s60, s60, 0x80080
	s_addc_u32 s61, s61, 0
	s_add_i32 s41, s43, s68
	global_load_lds_dwordx4 v134, s[98:99]
	s_mov_b32 m0, s41
	s_nop 0
	global_load_lds_dwordx4 v130, s[60:61]
	s_add_i32 m0, s41, 0x2000
	s_nop 0
	global_load_lds_dwordx4 v134, s[60:61]
	s_mov_b32 m0, s78
	s_nop 0
	global_load_lds_dwordx4 v128, s[100:101]
	s_mov_b32 m0, s79
	s_nop 0
	global_load_lds_dwordx4 v132, s[100:101]
	s_waitcnt vmcnt(8)
	s_waitcnt lgkmcnt(0)
	s_setprio 0
	s_barrier
	v_mfma_f32_16x16x32_bf16 v[60:63], v[146:149], v[192:195], v[60:63]
	v_mfma_f32_16x16x32_bf16 v[56:59], v[168:171], v[192:195], v[56:59]
	v_mfma_f32_16x16x32_bf16 v[44:47], v[146:149], v[200:203], v[44:47]
	v_mfma_f32_16x16x32_bf16 v[40:43], v[168:171], v[200:203], v[40:43]
	v_mfma_f32_16x16x32_bf16 v[28:31], v[146:149], v[208:211], v[28:31]
	v_mfma_f32_16x16x32_bf16 v[24:27], v[168:171], v[208:211], v[24:27]
	v_mfma_f32_16x16x32_bf16 v[12:15], v[146:149], v[216:219], v[12:15]
	v_mfma_f32_16x16x32_bf16 v[8:11], v[168:171], v[216:219], v[8:11]
	v_mfma_f32_16x16x32_bf16 v[60:63], v[158:161], v[196:199], v[60:63]
	v_mfma_f32_16x16x32_bf16 v[56:59], v[172:175], v[196:199], v[56:59]
	v_mfma_f32_16x16x32_bf16 v[44:47], v[158:161], v[204:207], v[44:47]
	v_mfma_f32_16x16x32_bf16 v[40:43], v[172:175], v[204:207], v[40:43]
	v_mfma_f32_16x16x32_bf16 v[28:31], v[158:161], v[212:215], v[28:31]
	v_mfma_f32_16x16x32_bf16 v[24:27], v[172:175], v[212:215], v[24:27]
	v_mfma_f32_16x16x32_bf16 v[12:15], v[158:161], v[220:223], v[12:15]
	v_mfma_f32_16x16x32_bf16 v[8:11], v[172:175], v[220:223], v[8:11]
	v_mfma_f32_16x16x32_bf16 v[52:55], v[176:179], v[192:195], v[52:55]
	v_mfma_f32_16x16x32_bf16 v[48:51], v[184:187], v[192:195], v[48:51]
	v_mfma_f32_16x16x32_bf16 v[36:39], v[176:179], v[200:203], v[36:39]
	v_mfma_f32_16x16x32_bf16 v[32:35], v[184:187], v[200:203], v[32:35]
	v_mfma_f32_16x16x32_bf16 v[20:23], v[176:179], v[208:211], v[20:23]
	v_mfma_f32_16x16x32_bf16 v[16:19], v[184:187], v[208:211], v[16:19]
	v_mfma_f32_16x16x32_bf16 v[4:7], v[176:179], v[216:219], v[4:7]
	v_mfma_f32_16x16x32_bf16 v[0:3], v[184:187], v[216:219], v[0:3]
	v_mfma_f32_16x16x32_bf16 v[52:55], v[180:183], v[196:199], v[52:55]
	v_mfma_f32_16x16x32_bf16 v[48:51], v[188:191], v[196:199], v[48:51]
	v_mfma_f32_16x16x32_bf16 v[36:39], v[180:183], v[204:207], v[36:39]
	v_mfma_f32_16x16x32_bf16 v[32:35], v[188:191], v[204:207], v[32:35]
	v_mfma_f32_16x16x32_bf16 v[20:23], v[180:183], v[212:215], v[20:23]
	v_mfma_f32_16x16x32_bf16 v[16:19], v[188:191], v[212:215], v[16:19]
	v_mfma_f32_16x16x32_bf16 v[4:7], v[180:183], v[220:223], v[4:7]
	v_mfma_f32_16x16x32_bf16 v[0:3], v[188:191], v[220:223], v[0:3]
	s_barrier
	s_setprio 1
	s_add_i32 s34, s34, 2
	s_add_u32 s54, s54, 0x100
	s_addc_u32 s55, s55, 0
	s_add_u32 s31, s31, 0x100
	s_addc_u32 s33, s33, 0
	s_cmp_gt_u32 s34, 29
	s_cbranch_scc0 .LBB0_497
	s_and_b64 vcc, exec, s[22:23]
	s_cbranch_vccz .LBB0_500
	s_barrier

; #define PG8_STAGE(bufoff, gbase, voff) do { _Pragma("unroll") for (int _i = 0; _i < 2; ++_i) \
;         __builtin_amdgcn_global_load_lds((const unsigned*)((const char*)(gbase) + (voff)[_i]), (PG8_LAS unsigned*)(lds + (bufoff) + ldsw + _i * 8192), 16, 0, 0); } while (0)
; #define PG8_LDA(dst, b, h) do { _Pragma("unroll") for (int m = 0; m < 4; ++m) _Pragma("unroll") for (int k = 0; k < 2; ++k) dst[m][k] = *(const PG8_LAS bf16x8*)(lds + PG8_SA(b, h) + aoff + m * 2048 + k * 1024); } while (0)
; #define PG8_LDB(dst, b, h) do { _Pragma("unroll") for (int n = 0; n < 2; ++n) _Pragma("unroll") for (int k = 0; k < 2; ++k) dst[n][k] = *(const PG8_LAS bf16x8*)(lds + PG8_SB(b, h) + boff + n * 2048 + k * 1024); } while (0)
; #define PG8_MMA(ai, bj, At, Bt) do { __builtin_amdgcn_s_setprio(1); _Pragma("unroll") for (int m = 0; m < 4; ++m) _Pragma("unroll") for (int n = 0; n < 2; ++n) _Pragma("unroll") for (int k = 0; k < 2; ++k) \
;         acc[ai][bj][m][n] = __builtin_amdgcn_mfma_f32_16x16x32_bf16(Bt[n][k], At[m][k], acc[ai][bj][m][n], 0, 0, 0); __builtin_amdgcn_s_setprio(0); } while (0)
; #define PG8_WAIT_V(n) asm volatile("s_waitcnt vmcnt(" #n ")" ::: "memory")
; #define PG8_WAIT_L(n) asm volatile("s_waitcnt lgkmcnt(" #n ")" ::: "memory")
; #define PG8_BAR __builtin_amdgcn_s_barrier()
; #define PG8_SCHED __builtin_amdgcn_sched_barrier(0)
; template <class Epi, class Sched, bool ALIGN_EPI = false, bool SP2 = false>
; __device__ __forceinline__ void gemm_phase(PG8_LAS unsigned char* lds, const Gemm g, const Sched& S, const Epi& E) {
;     ...
;             PG8_LDB(B0, 0, 0); PG8_LDB(B1, 0, 1); PG8_SCHED; PG8_LDA(At, 0, 0); PG8_STAGE(PG8_SA(1, 1), a1 + hstepA, voffA);
;             PG8_WAIT_V(8); PG8_WAIT_L(0); PG8_BAR; PG8_MMA(0, 0, At, B0); PG8_MMA(0, 1, At, B1); PG8_BAR; PG8_SCHED;
;             PG8_LDA(At, 0, 1); PG8_STAGE(PG8_SB(0, 0), b2, voffB); PG8_STAGE(PG8_SB(0, 1), b2 + hstepB, voffB); PG8_STAGE(PG8_SA(0, 0), a2, voffA);
;             PG8_WAIT_V(8); PG8_WAIT_L(0); PG8_BAR; PG8_MMA(1, 0, At, B0); PG8_MMA(1, 1, At, B1); PG8_BAR; PG8_SCHED;
.LBB0_829:
	ds_read_b128 v[144:147], v153
	ds_read_b128 v[158:161], v153 offset:1024
	ds_read_b128 v[166:169], v153 offset:2048
	ds_read_b128 v[170:173], v153 offset:3072
	ds_read_b128 v[174:177], v154
	ds_read_b128 v[178:181], v154 offset:1024
	ds_read_b128 v[182:185], v154 offset:2048
	ds_read_b128 v[186:189], v154 offset:3072
	s_add_u32 s40, s0, 0xffdc0080
	s_addc_u32 s41, s1, -1
	s_cmp_eq_u32 s58, 12
	s_cselect_b32 s43, s21, s41
	s_cselect_b32 s42, s20, s40
	s_cselect_b32 s41, s19, s57
	s_cselect_b32 s40, s55, s56
	s_add_i32 m0, s33, 0xc000
	ds_read_b128 v[190:193], v155
	ds_read_b128 v[194:197], v155 offset:1024
	ds_read_b128 v[198:201], v155 offset:2048
	ds_read_b128 v[202:205], v155 offset:3072
	ds_read_b128 v[206:209], v155 offset:4096
	ds_read_b128 v[210:213], v155 offset:5120
	ds_read_b128 v[214:217], v155 offset:6144
	ds_read_b128 v[218:221], v155 offset:7168
	global_load_lds_dwordx4 v136, s[0:1]
	s_add_i32 m0, s33, 0xe000
	s_nop 0
	global_load_lds_dwordx4 v138, s[0:1]
	s_waitcnt vmcnt(8)
	s_waitcnt lgkmcnt(0)
	s_setprio 0
	s_barrier
	v_mfma_f32_16x16x32_bf16 v[124:127], v[144:147], v[190:193], v[124:127]
	v_mfma_f32_16x16x32_bf16 v[120:123], v[166:169], v[190:193], v[120:123]
	v_mfma_f32_16x16x32_bf16 v[108:111], v[144:147], v[198:201], v[108:111]
	v_mfma_f32_16x16x32_bf16 v[104:107], v[166:169], v[198:201], v[104:107]
	v_mfma_f32_16x16x32_bf16 v[92:95], v[144:147], v[206:209], v[92:95]
	v_mfma_f32_16x16x32_bf16 v[88:91], v[166:169], v[206:209], v[88:91]
	v_mfma_f32_16x16x32_bf16 v[76:79], v[144:147], v[214:217], v[76:79]
	v_mfma_f32_16x16x32_bf16 v[72:75], v[166:169], v[214:217], v[72:75]
	v_mfma_f32_16x16x32_bf16 v[124:127], v[158:161], v[194:197], v[124:127]
	v_mfma_f32_16x16x32_bf16 v[120:123], v[170:173], v[194:197], v[120:123]
	v_mfma_f32_16x16x32_bf16 v[108:111], v[158:161], v[202:205], v[108:111]
	v_mfma_f32_16x16x32_bf16 v[104:107], v[170:173], v[202:205], v[104:107]
	v_mfma_f32_16x16x32_bf16 v[92:95], v[158:161], v[210:213], v[92:95]
	v_mfma_f32_16x16x32_bf16 v[88:91], v[170:173], v[210:213], v[88:91]
	v_mfma_f32_16x16x32_bf16 v[76:79], v[158:161], v[218:221], v[76:79]
	v_mfma_f32_16x16x32_bf16 v[72:75], v[170:173], v[218:221], v[72:75]
	v_mfma_f32_16x16x32_bf16 v[116:119], v[174:177], v[190:193], v[116:119]
	v_mfma_f32_16x16x32_bf16 v[112:115], v[182:185], v[190:193], v[112:115]
	v_mfma_f32_16x16x32_bf16 v[100:103], v[174:177], v[198:201], v[100:103]
	v_mfma_f32_16x16x32_bf16 v[96:99], v[182:185], v[198:201], v[96:99]
	v_mfma_f32_16x16x32_bf16 v[84:87], v[174:177], v[206:209], v[84:87]
	v_mfma_f32_16x16x32_bf16 v[80:83], v[182:185], v[206:209], v[80:83]
	v_mfma_f32_16x16x32_bf16 v[68:71], v[174:177], v[214:217], v[68:71]
	v_mfma_f32_16x16x32_bf16 v[64:67], v[182:185], v[214:217], v[64:67]
	v_mfma_f32_16x16x32_bf16 v[116:119], v[178:181], v[194:197], v[116:119]
	v_mfma_f32_16x16x32_bf16 v[112:115], v[186:189], v[194:197], v[112:115]
	v_mfma_f32_16x16x32_bf16 v[100:103], v[178:181], v[202:205], v[100:103]
	v_mfma_f32_16x16x32_bf16 v[96:99], v[186:189], v[202:205], v[96:99]
	v_mfma_f32_16x16x32_bf16 v[84:87], v[178:181], v[210:213], v[84:87]
	v_mfma_f32_16x16x32_bf16 v[80:83], v[186:189], v[210:213], v[80:83]
	v_mfma_f32_16x16x32_bf16 v[68:71], v[178:181], v[218:221], v[68:71]
	v_mfma_f32_16x16x32_bf16 v[64:67], v[186:189], v[218:221], v[64:67]
	s_barrier
	s_setprio 1
	s_add_u32 s98, s40, s10
	s_addc_u32 s99, s41, s11
	s_add_u32 s100, s42, s10
	s_addc_u32 s101, s43, s11
	s_add_i32 s59, s49, s30
	s_mov_b32 m0, s59
	ds_read_b128 v[190:193], v155 offset:16384
	ds_read_b128 v[194:197], v155 offset:17408
	ds_read_b128 v[198:201], v155 offset:18432
	ds_read_b128 v[202:205], v155 offset:19456
	ds_read_b128 v[206:209], v155 offset:20480
	ds_read_b128 v[210:213], v155 offset:21504
	ds_read_b128 v[214:217], v155 offset:22528
	ds_read_b128 v[218:221], v155 offset:23552
	global_load_lds_dwordx4 v132, s[40:41]
	s_add_i32 m0, s59, 0x2000
	s_add_u32 s60, s40, 0x40000
	s_addc_u32 s61, s41, 0
	s_add_i32 s59, s50, s30
	global_load_lds_dwordx4 v128, s[40:41]
	s_mov_b32 m0, s59
	s_nop 0
	global_load_lds_dwordx4 v132, s[60:61]
	s_add_i32 m0, s59, 0x2000
	s_nop 0
	global_load_lds_dwordx4 v128, s[60:61]
	s_mov_b32 m0, s33
	s_nop 0
	global_load_lds_dwordx4 v134, s[42:43]
	s_mov_b32 m0, s34
	s_nop 0
	global_load_lds_dwordx4 v130, s[42:43]
	s_waitcnt vmcnt(8)
	s_waitcnt lgkmcnt(0)
	s_setprio 0
	s_barrier
	v_mfma_f32_16x16x32_bf16 v[60:63], v[144:147], v[190:193], v[60:63]
	v_mfma_f32_16x16x32_bf16 v[56:59], v[166:169], v[190:193], v[56:59]
	v_mfma_f32_16x16x32_bf16 v[44:47], v[144:147], v[198:201], v[44:47]
	v_mfma_f32_16x16x32_bf16 v[40:43], v[166:169], v[198:201], v[40:43]
	v_mfma_f32_16x16x32_bf16 v[28:31], v[144:147], v[206:209], v[28:31]
	v_mfma_f32_16x16x32_bf16 v[24:27], v[166:169], v[206:209], v[24:27]
	v_mfma_f32_16x16x32_bf16 v[12:15], v[144:147], v[214:217], v[12:15]
	v_mfma_f32_16x16x32_bf16 v[8:11], v[166:169], v[214:217], v[8:11]
	v_mfma_f32_16x16x32_bf16 v[60:63], v[158:161], v[194:197], v[60:63]
	v_mfma_f32_16x16x32_bf16 v[56:59], v[170:173], v[194:197], v[56:59]
	v_mfma_f32_16x16x32_bf16 v[44:47], v[158:161], v[202:205], v[44:47]
	v_mfma_f32_16x16x32_bf16 v[40:43], v[170:173], v[202:205], v[40:43]
	v_mfma_f32_16x16x32_bf16 v[28:31], v[158:161], v[210:213], v[28:31]
	v_mfma_f32_16x16x32_bf16 v[24:27], v[170:173], v[210:213], v[24:27]
	v_mfma_f32_16x16x32_bf16 v[12:15], v[158:161], v[218:221], v[12:15]
	v_mfma_f32_16x16x32_bf16 v[8:11], v[170:173], v[218:221], v[8:11]
	v_mfma_f32_16x16x32_bf16 v[52:55], v[174:177], v[190:193], v[52:55]
	v_mfma_f32_16x16x32_bf16 v[48:51], v[182:185], v[190:193], v[48:51]
	v_mfma_f32_16x16x32_bf16 v[36:39], v[174:177], v[198:201], v[36:39]
	v_mfma_f32_16x16x32_bf16 v[32:35], v[182:185], v[198:201], v[32:35]
	v_mfma_f32_16x16x32_bf16 v[20:23], v[174:177], v[206:209], v[20:23]
	v_mfma_f32_16x16x32_bf16 v[16:19], v[182:185], v[206:209], v[16:19]
	v_mfma_f32_16x16x32_bf16 v[4:7], v[174:177], v[214:217], v[4:7]
	v_mfma_f32_16x16x32_bf16 v[0:3], v[182:185], v[214:217], v[0:3]
	v_mfma_f32_16x16x32_bf16 v[52:55], v[178:181], v[194:197], v[52:55]
	v_mfma_f32_16x16x32_bf16 v[48:51], v[186:189], v[194:197], v[48:51]
	v_mfma_f32_16x16x32_bf16 v[36:39], v[178:181], v[202:205], v[36:39]
	v_mfma_f32_16x16x32_bf16 v[32:35], v[186:189], v[202:205], v[32:35]
	v_mfma_f32_16x16x32_bf16 v[20:23], v[178:181], v[210:213], v[20:23]
	v_mfma_f32_16x16x32_bf16 v[16:19], v[186:189], v[210:213], v[16:19]
	v_mfma_f32_16x16x32_bf16 v[4:7], v[178:181], v[218:221], v[4:7]
	v_mfma_f32_16x16x32_bf16 v[0:3], v[186:189], v[218:221], v[0:3]
	s_barrier
; #define PG8_STAGE(bufoff, gbase, voff) do { _Pragma("unroll") for (int _i = 0; _i < 2; ++_i) \
;         __builtin_amdgcn_global_load_lds((const unsigned*)((const char*)(gbase) + (voff)[_i]), (PG8_LAS unsigned*)(lds + (bufoff) + ldsw + _i * 8192), 16, 0, 0); } while (0)
; #define PG8_LDA(dst, b, h) do { _Pragma("unroll") for (int m = 0; m < 4; ++m) _Pragma("unroll") for (int k = 0; k < 2; ++k) dst[m][k] = *(const PG8_LAS bf16x8*)(lds + PG8_SA(b, h) + aoff + m * 2048 + k * 1024); } while (0)
; #define PG8_LDB(dst, b, h) do { _Pragma("unroll") for (int n = 0; n < 2; ++n) _Pragma("unroll") for (int k = 0; k < 2; ++k) dst[n][k] = *(const PG8_LAS bf16x8*)(lds + PG8_SB(b, h) + boff + n * 2048 + k * 1024); } while (0)
; #define PG8_MMA(ai, bj, At, Bt) do { __builtin_amdgcn_s_setprio(1); _Pragma("unroll") for (int m = 0; m < 4; ++m) _Pragma("unroll") for (int n = 0; n < 2; ++n) _Pragma("unroll") for (int k = 0; k < 2; ++k) \
;         acc[ai][bj][m][n] = __builtin_amdgcn_mfma_f32_16x16x32_bf16(Bt[n][k], At[m][k], acc[ai][bj][m][n], 0, 0, 0); __builtin_amdgcn_s_setprio(0); } while (0)
; #define PG8_WAIT_V(n) asm volatile("s_waitcnt vmcnt(" #n ")" ::: "memory")
; #define PG8_WAIT_L(n) asm volatile("s_waitcnt lgkmcnt(" #n ")" ::: "memory")
; #define PG8_BAR __builtin_amdgcn_s_barrier()
; #define PG8_SCHED __builtin_amdgcn_sched_barrier(0)
; template <class Epi, class Sched, bool ALIGN_EPI = false, bool SP2 = false>
; __device__ __forceinline__ void gemm_phase(PG8_LAS unsigned char* lds, const Gemm g, const Sched& S, const Epi& E) {
;     ...
;             PG8_LDB(B0, 1, 0); PG8_LDB(B1, 1, 1); PG8_SCHED; PG8_LDA(At, 1, 0); PG8_STAGE(PG8_SA(0, 1), a2 + hstepA, voffA);
;             PG8_WAIT_V(8); PG8_WAIT_L(0); PG8_BAR; PG8_MMA(0, 0, At, B0); PG8_MMA(0, 1, At, B1); PG8_BAR; PG8_SCHED;
;             PG8_LDA(At, 1, 1); PG8_STAGE(PG8_SB(1, 0), b3, voffB); PG8_STAGE(PG8_SB(1, 1), b3 + hstepB, voffB); PG8_STAGE(PG8_SA(1, 0), a3, voffA);
;             PG8_WAIT_V(8); PG8_WAIT_L(0); PG8_BAR; PG8_MMA(1, 0, At, B0); PG8_MMA(1, 1, At, B1); PG8_BAR; PG8_SCHED;
;     ...
;         if constexpr (ALIGN_EPI) { if (wr == 0) PG8_BAR; }
	s_setprio 1
	s_add_i32 s59, 0, 0x18000
	v_add_u32_e32 v157, s59, v151
	s_add_i32 s60, 0, 0x1c000
	ds_read_b128 v[144:147], v157
	ds_read_b128 v[158:161], v157 offset:1024
	ds_read_b128 v[166:169], v157 offset:2048
	ds_read_b128 v[170:173], v157 offset:3072
	v_add_u32_e32 v157, s60, v151
	ds_read_b128 v[174:177], v157
	ds_read_b128 v[178:181], v157 offset:1024
	ds_read_b128 v[182:185], v157 offset:2048
	ds_read_b128 v[186:189], v157 offset:3072
	s_add_u32 s42, s42, 0x240000
	s_addc_u32 s43, s43, 0
	s_mov_b32 m0, s35
	ds_read_b128 v[190:193], v155 offset:32768
	ds_read_b128 v[194:197], v155 offset:33792
	ds_read_b128 v[198:201], v155 offset:34816
	ds_read_b128 v[202:205], v155 offset:35840
	ds_read_b128 v[206:209], v155 offset:36864
	ds_read_b128 v[210:213], v155 offset:37888
	ds_read_b128 v[214:217], v155 offset:38912
	ds_read_b128 v[218:221], v155 offset:39936
	global_load_lds_dwordx4 v134, s[42:43]
	s_mov_b32 m0, s44
	s_nop 0
	global_load_lds_dwordx4 v130, s[42:43]
	s_waitcnt vmcnt(8)
	s_waitcnt lgkmcnt(0)
	s_setprio 0
	s_barrier
	v_mfma_f32_16x16x32_bf16 v[124:127], v[144:147], v[190:193], v[124:127]
	v_mfma_f32_16x16x32_bf16 v[120:123], v[166:169], v[190:193], v[120:123]
	v_mfma_f32_16x16x32_bf16 v[108:111], v[144:147], v[198:201], v[108:111]
	v_mfma_f32_16x16x32_bf16 v[104:107], v[166:169], v[198:201], v[104:107]
	v_mfma_f32_16x16x32_bf16 v[92:95], v[144:147], v[206:209], v[92:95]
	v_mfma_f32_16x16x32_bf16 v[88:91], v[166:169], v[206:209], v[88:91]
	v_mfma_f32_16x16x32_bf16 v[76:79], v[144:147], v[214:217], v[76:79]
	v_mfma_f32_16x16x32_bf16 v[72:75], v[166:169], v[214:217], v[72:75]
	v_mfma_f32_16x16x32_bf16 v[124:127], v[158:161], v[194:197], v[124:127]
	v_mfma_f32_16x16x32_bf16 v[120:123], v[170:173], v[194:197], v[120:123]
	v_mfma_f32_16x16x32_bf16 v[108:111], v[158:161], v[202:205], v[108:111]
	v_mfma_f32_16x16x32_bf16 v[104:107], v[170:173], v[202:205], v[104:107]
	v_mfma_f32_16x16x32_bf16 v[92:95], v[158:161], v[210:213], v[92:95]
	v_mfma_f32_16x16x32_bf16 v[88:91], v[170:173], v[210:213], v[88:91]
	v_mfma_f32_16x16x32_bf16 v[76:79], v[158:161], v[218:221], v[76:79]
	v_mfma_f32_16x16x32_bf16 v[72:75], v[170:173], v[218:221], v[72:75]
	v_mfma_f32_16x16x32_bf16 v[116:119], v[174:177], v[190:193], v[116:119]
	v_mfma_f32_16x16x32_bf16 v[112:115], v[182:185], v[190:193], v[112:115]
	v_mfma_f32_16x16x32_bf16 v[100:103], v[174:177], v[198:201], v[100:103]
	v_mfma_f32_16x16x32_bf16 v[96:99], v[182:185], v[198:201], v[96:99]
	v_mfma_f32_16x16x32_bf16 v[84:87], v[174:177], v[206:209], v[84:87]
	v_mfma_f32_16x16x32_bf16 v[80:83], v[182:185], v[206:209], v[80:83]
	v_mfma_f32_16x16x32_bf16 v[68:71], v[174:177], v[214:217], v[68:71]
	v_mfma_f32_16x16x32_bf16 v[64:67], v[182:185], v[214:217], v[64:67]
	v_mfma_f32_16x16x32_bf16 v[116:119], v[178:181], v[194:197], v[116:119]
	v_mfma_f32_16x16x32_bf16 v[112:115], v[186:189], v[194:197], v[112:115]
	v_mfma_f32_16x16x32_bf16 v[100:103], v[178:181], v[202:205], v[100:103]
	v_mfma_f32_16x16x32_bf16 v[96:99], v[186:189], v[202:205], v[96:99]
	v_mfma_f32_16x16x32_bf16 v[84:87], v[178:181], v[210:213], v[84:87]
	v_mfma_f32_16x16x32_bf16 v[80:83], v[186:189], v[210:213], v[80:83]
	v_mfma_f32_16x16x32_bf16 v[68:71], v[178:181], v[218:221], v[68:71]
	v_mfma_f32_16x16x32_bf16 v[64:67], v[186:189], v[218:221], v[64:67]
	s_barrier
	s_setprio 1
	s_add_i32 s42, s59, s30
	s_mov_b32 m0, s42
	ds_read_b128 v[190:193], v155 offset:49152
	ds_read_b128 v[194:197], v155 offset:50176
	ds_read_b128 v[198:201], v155 offset:51200
	ds_read_b128 v[202:205], v155 offset:52224
	ds_read_b128 v[206:209], v155 offset:53248
	ds_read_b128 v[210:213], v155 offset:54272
	ds_read_b128 v[214:217], v155 offset:55296
	ds_read_b128 v[218:221], v155 offset:56320
	global_load_lds_dwordx4 v132, s[98:99]
	s_add_i32 m0, s42, 0x2000
	s_add_u32 s40, s40, 0x40080
	s_addc_u32 s41, s41, 0
	s_add_i32 s42, s60, s30
	global_load_lds_dwordx4 v128, s[98:99]
	s_mov_b32 m0, s42
	s_nop 0
	global_load_lds_dwordx4 v132, s[40:41]
	s_add_i32 m0, s42, 0x2000
	s_nop 0
	global_load_lds_dwordx4 v128, s[40:41]
	s_mov_b32 m0, s47
	s_nop 0
	global_load_lds_dwordx4 v134, s[100:101]
	s_mov_b32 m0, s48
	s_nop 0
	global_load_lds_dwordx4 v130, s[100:101]
	s_waitcnt vmcnt(8)
	s_waitcnt lgkmcnt(0)
	s_setprio 0
	s_barrier
	v_mfma_f32_16x16x32_bf16 v[60:63], v[144:147], v[190:193], v[60:63]
	v_mfma_f32_16x16x32_bf16 v[56:59], v[166:169], v[190:193], v[56:59]
	v_mfma_f32_16x16x32_bf16 v[44:47], v[144:147], v[198:201], v[44:47]
	v_mfma_f32_16x16x32_bf16 v[40:43], v[166:169], v[198:201], v[40:43]
	v_mfma_f32_16x16x32_bf16 v[28:31], v[144:147], v[206:209], v[28:31]
	v_mfma_f32_16x16x32_bf16 v[24:27], v[166:169], v[206:209], v[24:27]
	v_mfma_f32_16x16x32_bf16 v[12:15], v[144:147], v[214:217], v[12:15]
	v_mfma_f32_16x16x32_bf16 v[8:11], v[166:169], v[214:217], v[8:11]
	v_mfma_f32_16x16x32_bf16 v[60:63], v[158:161], v[194:197], v[60:63]
	v_mfma_f32_16x16x32_bf16 v[56:59], v[170:173], v[194:197], v[56:59]
	v_mfma_f32_16x16x32_bf16 v[44:47], v[158:161], v[202:205], v[44:47]
	v_mfma_f32_16x16x32_bf16 v[40:43], v[170:173], v[202:205], v[40:43]
	v_mfma_f32_16x16x32_bf16 v[28:31], v[158:161], v[210:213], v[28:31]
	v_mfma_f32_16x16x32_bf16 v[24:27], v[170:173], v[210:213], v[24:27]
	v_mfma_f32_16x16x32_bf16 v[12:15], v[158:161], v[218:221], v[12:15]
	v_mfma_f32_16x16x32_bf16 v[8:11], v[170:173], v[218:221], v[8:11]
	v_mfma_f32_16x16x32_bf16 v[52:55], v[174:177], v[190:193], v[52:55]
	v_mfma_f32_16x16x32_bf16 v[48:51], v[182:185], v[190:193], v[48:51]
	v_mfma_f32_16x16x32_bf16 v[36:39], v[174:177], v[198:201], v[36:39]
	v_mfma_f32_16x16x32_bf16 v[32:35], v[182:185], v[198:201], v[32:35]
	v_mfma_f32_16x16x32_bf16 v[20:23], v[174:177], v[206:209], v[20:23]
	v_mfma_f32_16x16x32_bf16 v[16:19], v[182:185], v[206:209], v[16:19]
	v_mfma_f32_16x16x32_bf16 v[4:7], v[174:177], v[214:217], v[4:7]
	v_mfma_f32_16x16x32_bf16 v[0:3], v[182:185], v[214:217], v[0:3]
	v_mfma_f32_16x16x32_bf16 v[52:55], v[178:181], v[194:197], v[52:55]
	v_mfma_f32_16x16x32_bf16 v[48:51], v[186:189], v[194:197], v[48:51]
	v_mfma_f32_16x16x32_bf16 v[36:39], v[178:181], v[202:205], v[36:39]
	v_mfma_f32_16x16x32_bf16 v[32:35], v[186:189], v[202:205], v[32:35]
	v_mfma_f32_16x16x32_bf16 v[20:23], v[178:181], v[210:213], v[20:23]
	v_mfma_f32_16x16x32_bf16 v[16:19], v[186:189], v[210:213], v[16:19]
	v_mfma_f32_16x16x32_bf16 v[4:7], v[178:181], v[218:221], v[4:7]
	v_mfma_f32_16x16x32_bf16 v[0:3], v[186:189], v[218:221], v[0:3]
	s_barrier
	s_setprio 1
	s_add_i32 s58, s58, 2
	s_add_u32 s0, s0, 0x100
	s_addc_u32 s1, s1, 0
	s_add_u32 s56, s56, 0x100
	s_addc_u32 s57, s57, 0
	s_cmp_gt_u32 s58, 13
	s_cbranch_scc0 .LBB0_829
	s_and_b64 vcc, exec, s[16:17]
	s_cbranch_vccz .LBB0_832
	s_barrier

; #define PG8_STAGE(bufoff, gbase, voff) do { _Pragma("unroll") for (int _i = 0; _i < 2; ++_i) \
;         __builtin_amdgcn_global_load_lds((const unsigned*)((const char*)(gbase) + (voff)[_i]), (PG8_LAS unsigned*)(lds + (bufoff) + ldsw + _i * 8192), 16, 0, 0); } while (0)
; #define PG8_LDA(dst, b, h) do { _Pragma("unroll") for (int m = 0; m < 4; ++m) _Pragma("unroll") for (int k = 0; k < 2; ++k) dst[m][k] = *(const PG8_LAS bf16x8*)(lds + PG8_SA(b, h) + aoff + m * 2048 + k * 1024); } while (0)
; #define PG8_LDB(dst, b, h) do { _Pragma("unroll") for (int n = 0; n < 2; ++n) _Pragma("unroll") for (int k = 0; k < 2; ++k) dst[n][k] = *(const PG8_LAS bf16x8*)(lds + PG8_SB(b, h) + boff + n * 2048 + k * 1024); } while (0)
; #define PG8_MMA(ai, bj, At, Bt) do { __builtin_amdgcn_s_setprio(1); _Pragma("unroll") for (int m = 0; m < 4; ++m) _Pragma("unroll") for (int n = 0; n < 2; ++n) _Pragma("unroll") for (int k = 0; k < 2; ++k) \
;         acc[ai][bj][m][n] = __builtin_amdgcn_mfma_f32_16x16x32_bf16(Bt[n][k], At[m][k], acc[ai][bj][m][n], 0, 0, 0); __builtin_amdgcn_s_setprio(0); } while (0)
; #define PG8_WAIT_V(n) asm volatile("s_waitcnt vmcnt(" #n ")" ::: "memory")
; #define PG8_WAIT_L(n) asm volatile("s_waitcnt lgkmcnt(" #n ")" ::: "memory")
; #define PG8_BAR __builtin_amdgcn_s_barrier()
; #define PG8_SCHED __builtin_amdgcn_sched_barrier(0)
; template <class Epi, class Sched, bool ALIGN_EPI = false, bool SP2 = false>
; __device__ __forceinline__ void gemm_phase(PG8_LAS unsigned char* lds, const Gemm g, const Sched& S, const Epi& E) {
;     ...
;             PG8_LDB(B0, 0, 0); PG8_LDB(B1, 0, 1); PG8_SCHED; PG8_LDA(At, 0, 0); PG8_STAGE(PG8_SA(1, 1), a1 + hstepA, voffA);
;             PG8_WAIT_V(8); PG8_WAIT_L(0); PG8_BAR; PG8_MMA(0, 0, At, B0); PG8_MMA(0, 1, At, B1); PG8_BAR; PG8_SCHED;
;             PG8_LDA(At, 0, 1); PG8_STAGE(PG8_SB(0, 0), b2, voffB); PG8_STAGE(PG8_SB(0, 1), b2 + hstepB, voffB); PG8_STAGE(PG8_SA(0, 0), a2, voffA);
;             PG8_WAIT_V(8); PG8_WAIT_L(0); PG8_BAR; PG8_MMA(1, 0, At, B0); PG8_MMA(1, 1, At, B1); PG8_BAR; PG8_SCHED;
.LBB0_848:
	ds_read_b128 v[144:147], v155
	ds_read_b128 v[148:151], v155 offset:1024
	ds_read_b128 v[166:169], v155 offset:2048
	ds_read_b128 v[170:173], v155 offset:3072
	ds_read_b128 v[174:177], v156
	ds_read_b128 v[178:181], v156 offset:1024
	ds_read_b128 v[182:185], v156 offset:2048
	ds_read_b128 v[186:189], v156 offset:3072
	s_add_u32 s42, s0, 0xffdc0080
	s_addc_u32 s43, s1, -1
	s_cmp_eq_u32 s58, 12
	s_cselect_b32 s45, s23, s43
	s_cselect_b32 s44, s22, s42
	s_cselect_b32 s43, s21, s34
	s_cselect_b32 s42, s30, s31
	s_add_i32 m0, s46, 0xc000
	ds_read_b128 v[190:193], v157
	ds_read_b128 v[194:197], v157 offset:1024
	ds_read_b128 v[198:201], v157 offset:2048
	ds_read_b128 v[202:205], v157 offset:3072
	ds_read_b128 v[206:209], v157 offset:4096
	ds_read_b128 v[210:213], v157 offset:5120
	ds_read_b128 v[214:217], v157 offset:6144
	ds_read_b128 v[218:221], v157 offset:7168
	global_load_lds_dwordx4 v136, s[0:1]
	s_add_i32 m0, s46, 0xe000
	s_nop 0
	global_load_lds_dwordx4 v138, s[0:1]
	s_waitcnt vmcnt(8)
	s_waitcnt lgkmcnt(0)
	s_setprio 0
	s_barrier
	v_mfma_f32_16x16x32_bf16 v[124:127], v[144:147], v[190:193], v[124:127]
	v_mfma_f32_16x16x32_bf16 v[120:123], v[166:169], v[190:193], v[120:123]
	v_mfma_f32_16x16x32_bf16 v[108:111], v[144:147], v[198:201], v[108:111]
	v_mfma_f32_16x16x32_bf16 v[104:107], v[166:169], v[198:201], v[104:107]
	v_mfma_f32_16x16x32_bf16 v[92:95], v[144:147], v[206:209], v[92:95]
	v_mfma_f32_16x16x32_bf16 v[88:91], v[166:169], v[206:209], v[88:91]
	v_mfma_f32_16x16x32_bf16 v[76:79], v[144:147], v[214:217], v[76:79]
	v_mfma_f32_16x16x32_bf16 v[72:75], v[166:169], v[214:217], v[72:75]
	v_mfma_f32_16x16x32_bf16 v[124:127], v[148:151], v[194:197], v[124:127]
	v_mfma_f32_16x16x32_bf16 v[120:123], v[170:173], v[194:197], v[120:123]
	v_mfma_f32_16x16x32_bf16 v[108:111], v[148:151], v[202:205], v[108:111]
	v_mfma_f32_16x16x32_bf16 v[104:107], v[170:173], v[202:205], v[104:107]
	v_mfma_f32_16x16x32_bf16 v[92:95], v[148:151], v[210:213], v[92:95]
	v_mfma_f32_16x16x32_bf16 v[88:91], v[170:173], v[210:213], v[88:91]
	v_mfma_f32_16x16x32_bf16 v[76:79], v[148:151], v[218:221], v[76:79]
	v_mfma_f32_16x16x32_bf16 v[72:75], v[170:173], v[218:221], v[72:75]
	v_mfma_f32_16x16x32_bf16 v[116:119], v[174:177], v[190:193], v[116:119]
	v_mfma_f32_16x16x32_bf16 v[112:115], v[182:185], v[190:193], v[112:115]
	v_mfma_f32_16x16x32_bf16 v[100:103], v[174:177], v[198:201], v[100:103]
	v_mfma_f32_16x16x32_bf16 v[96:99], v[182:185], v[198:201], v[96:99]
	v_mfma_f32_16x16x32_bf16 v[84:87], v[174:177], v[206:209], v[84:87]
	v_mfma_f32_16x16x32_bf16 v[80:83], v[182:185], v[206:209], v[80:83]
	v_mfma_f32_16x16x32_bf16 v[68:71], v[174:177], v[214:217], v[68:71]
	v_mfma_f32_16x16x32_bf16 v[64:67], v[182:185], v[214:217], v[64:67]
	v_mfma_f32_16x16x32_bf16 v[116:119], v[178:181], v[194:197], v[116:119]
	v_mfma_f32_16x16x32_bf16 v[112:115], v[186:189], v[194:197], v[112:115]
	v_mfma_f32_16x16x32_bf16 v[100:103], v[178:181], v[202:205], v[100:103]
	v_mfma_f32_16x16x32_bf16 v[96:99], v[186:189], v[202:205], v[96:99]
	v_mfma_f32_16x16x32_bf16 v[84:87], v[178:181], v[210:213], v[84:87]
	v_mfma_f32_16x16x32_bf16 v[80:83], v[186:189], v[210:213], v[80:83]
	v_mfma_f32_16x16x32_bf16 v[68:71], v[178:181], v[218:221], v[68:71]
	v_mfma_f32_16x16x32_bf16 v[64:67], v[186:189], v[218:221], v[64:67]
	s_barrier
	s_setprio 1
	s_add_u32 s98, s42, s16
	s_addc_u32 s99, s43, s17
	s_add_u32 s100, s44, s16
	s_addc_u32 s101, s45, s17
	s_add_i32 s59, s54, s33
	s_mov_b32 m0, s59
	ds_read_b128 v[190:193], v157 offset:16384
	ds_read_b128 v[194:197], v157 offset:17408
	ds_read_b128 v[198:201], v157 offset:18432
	ds_read_b128 v[202:205], v157 offset:19456
	ds_read_b128 v[206:209], v157 offset:20480
	ds_read_b128 v[210:213], v157 offset:21504
	ds_read_b128 v[214:217], v157 offset:22528
	ds_read_b128 v[218:221], v157 offset:23552
	global_load_lds_dwordx4 v132, s[42:43]
	s_add_i32 m0, s59, 0x2000
	s_add_u32 s60, s42, 0x40000
	s_addc_u32 s61, s43, 0
	s_add_i32 s59, s55, s33
	global_load_lds_dwordx4 v128, s[42:43]
	s_mov_b32 m0, s59
	s_nop 0
	global_load_lds_dwordx4 v132, s[60:61]
	s_add_i32 m0, s59, 0x2000
	s_nop 0
	global_load_lds_dwordx4 v128, s[60:61]
	s_mov_b32 m0, s46
	s_nop 0
	global_load_lds_dwordx4 v134, s[44:45]
	s_mov_b32 m0, s47
	s_nop 0
	global_load_lds_dwordx4 v130, s[44:45]
	s_waitcnt vmcnt(8)
	s_waitcnt lgkmcnt(0)
	s_setprio 0
	s_barrier
	v_mfma_f32_16x16x32_bf16 v[60:63], v[144:147], v[190:193], v[60:63]
	v_mfma_f32_16x16x32_bf16 v[56:59], v[166:169], v[190:193], v[56:59]
	v_mfma_f32_16x16x32_bf16 v[44:47], v[144:147], v[198:201], v[44:47]
	v_mfma_f32_16x16x32_bf16 v[40:43], v[166:169], v[198:201], v[40:43]
	v_mfma_f32_16x16x32_bf16 v[28:31], v[144:147], v[206:209], v[28:31]
	v_mfma_f32_16x16x32_bf16 v[24:27], v[166:169], v[206:209], v[24:27]
	v_mfma_f32_16x16x32_bf16 v[12:15], v[144:147], v[214:217], v[12:15]
	v_mfma_f32_16x16x32_bf16 v[8:11], v[166:169], v[214:217], v[8:11]
	v_mfma_f32_16x16x32_bf16 v[60:63], v[148:151], v[194:197], v[60:63]
	v_mfma_f32_16x16x32_bf16 v[56:59], v[170:173], v[194:197], v[56:59]
	v_mfma_f32_16x16x32_bf16 v[44:47], v[148:151], v[202:205], v[44:47]
	v_mfma_f32_16x16x32_bf16 v[40:43], v[170:173], v[202:205], v[40:43]
	v_mfma_f32_16x16x32_bf16 v[28:31], v[148:151], v[210:213], v[28:31]
	v_mfma_f32_16x16x32_bf16 v[24:27], v[170:173], v[210:213], v[24:27]
	v_mfma_f32_16x16x32_bf16 v[12:15], v[148:151], v[218:221], v[12:15]
	v_mfma_f32_16x16x32_bf16 v[8:11], v[170:173], v[218:221], v[8:11]
	v_mfma_f32_16x16x32_bf16 v[52:55], v[174:177], v[190:193], v[52:55]
	v_mfma_f32_16x16x32_bf16 v[48:51], v[182:185], v[190:193], v[48:51]
	v_mfma_f32_16x16x32_bf16 v[36:39], v[174:177], v[198:201], v[36:39]
	v_mfma_f32_16x16x32_bf16 v[32:35], v[182:185], v[198:201], v[32:35]
	v_mfma_f32_16x16x32_bf16 v[20:23], v[174:177], v[206:209], v[20:23]
	v_mfma_f32_16x16x32_bf16 v[16:19], v[182:185], v[206:209], v[16:19]
	v_mfma_f32_16x16x32_bf16 v[4:7], v[174:177], v[214:217], v[4:7]
	v_mfma_f32_16x16x32_bf16 v[0:3], v[182:185], v[214:217], v[0:3]
	v_mfma_f32_16x16x32_bf16 v[52:55], v[178:181], v[194:197], v[52:55]
	v_mfma_f32_16x16x32_bf16 v[48:51], v[186:189], v[194:197], v[48:51]
	v_mfma_f32_16x16x32_bf16 v[36:39], v[178:181], v[202:205], v[36:39]
	v_mfma_f32_16x16x32_bf16 v[32:35], v[186:189], v[202:205], v[32:35]
	v_mfma_f32_16x16x32_bf16 v[20:23], v[178:181], v[210:213], v[20:23]
	v_mfma_f32_16x16x32_bf16 v[16:19], v[186:189], v[210:213], v[16:19]
	v_mfma_f32_16x16x32_bf16 v[4:7], v[178:181], v[218:221], v[4:7]
	v_mfma_f32_16x16x32_bf16 v[0:3], v[186:189], v[218:221], v[0:3]
	s_barrier
; #define PG8_STAGE(bufoff, gbase, voff) do { _Pragma("unroll") for (int _i = 0; _i < 2; ++_i) \
;         __builtin_amdgcn_global_load_lds((const unsigned*)((const char*)(gbase) + (voff)[_i]), (PG8_LAS unsigned*)(lds + (bufoff) + ldsw + _i * 8192), 16, 0, 0); } while (0)
; #define PG8_LDA(dst, b, h) do { _Pragma("unroll") for (int m = 0; m < 4; ++m) _Pragma("unroll") for (int k = 0; k < 2; ++k) dst[m][k] = *(const PG8_LAS bf16x8*)(lds + PG8_SA(b, h) + aoff + m * 2048 + k * 1024); } while (0)
; #define PG8_LDB(dst, b, h) do { _Pragma("unroll") for (int n = 0; n < 2; ++n) _Pragma("unroll") for (int k = 0; k < 2; ++k) dst[n][k] = *(const PG8_LAS bf16x8*)(lds + PG8_SB(b, h) + boff + n * 2048 + k * 1024); } while (0)
; #define PG8_MMA(ai, bj, At, Bt) do { __builtin_amdgcn_s_setprio(1); _Pragma("unroll") for (int m = 0; m < 4; ++m) _Pragma("unroll") for (int n = 0; n < 2; ++n) _Pragma("unroll") for (int k = 0; k < 2; ++k) \
;         acc[ai][bj][m][n] = __builtin_amdgcn_mfma_f32_16x16x32_bf16(Bt[n][k], At[m][k], acc[ai][bj][m][n], 0, 0, 0); __builtin_amdgcn_s_setprio(0); } while (0)
; #define PG8_WAIT_V(n) asm volatile("s_waitcnt vmcnt(" #n ")" ::: "memory")
; #define PG8_WAIT_L(n) asm volatile("s_waitcnt lgkmcnt(" #n ")" ::: "memory")
; #define PG8_BAR __builtin_amdgcn_s_barrier()
; #define PG8_SCHED __builtin_amdgcn_sched_barrier(0)
; template <class Epi, class Sched, bool ALIGN_EPI = false, bool SP2 = false>
; __device__ __forceinline__ void gemm_phase(PG8_LAS unsigned char* lds, const Gemm g, const Sched& S, const Epi& E) {
;     ...
;             PG8_LDB(B0, 1, 0); PG8_LDB(B1, 1, 1); PG8_SCHED; PG8_LDA(At, 1, 0); PG8_STAGE(PG8_SA(0, 1), a2 + hstepA, voffA);
;             PG8_WAIT_V(8); PG8_WAIT_L(0); PG8_BAR; PG8_MMA(0, 0, At, B0); PG8_MMA(0, 1, At, B1); PG8_BAR; PG8_SCHED;
;             PG8_LDA(At, 1, 1); PG8_STAGE(PG8_SB(1, 0), b3, voffB); PG8_STAGE(PG8_SB(1, 1), b3 + hstepB, voffB); PG8_STAGE(PG8_SA(1, 0), a3, voffA);
;             PG8_WAIT_V(8); PG8_WAIT_L(0); PG8_BAR; PG8_MMA(1, 0, At, B0); PG8_MMA(1, 1, At, B1); PG8_BAR; PG8_SCHED;
;     ...
;         if constexpr (ALIGN_EPI) { if (wr == 0) PG8_BAR; }
	s_setprio 1
	s_add_i32 s59, 0, 0x18000
	v_add_u32_e32 v159, s59, v153
	s_add_i32 s60, 0, 0x1c000
	ds_read_b128 v[144:147], v159
	ds_read_b128 v[148:151], v159 offset:1024
	ds_read_b128 v[166:169], v159 offset:2048
	ds_read_b128 v[170:173], v159 offset:3072
	v_add_u32_e32 v159, s60, v153
	ds_read_b128 v[174:177], v159
	ds_read_b128 v[178:181], v159 offset:1024
	ds_read_b128 v[182:185], v159 offset:2048
	ds_read_b128 v[186:189], v159 offset:3072
	s_add_u32 s44, s44, 0x240000
	s_addc_u32 s45, s45, 0
	s_mov_b32 m0, s48
	ds_read_b128 v[190:193], v157 offset:32768
	ds_read_b128 v[194:197], v157 offset:33792
	ds_read_b128 v[198:201], v157 offset:34816
	ds_read_b128 v[202:205], v157 offset:35840
	ds_read_b128 v[206:209], v157 offset:36864
	ds_read_b128 v[210:213], v157 offset:37888
	ds_read_b128 v[214:217], v157 offset:38912
	ds_read_b128 v[218:221], v157 offset:39936
	global_load_lds_dwordx4 v134, s[44:45]
	s_mov_b32 m0, s49
	s_nop 0
	global_load_lds_dwordx4 v130, s[44:45]
	s_waitcnt vmcnt(8)
	s_waitcnt lgkmcnt(0)
	s_setprio 0
	s_barrier
	v_mfma_f32_16x16x32_bf16 v[124:127], v[144:147], v[190:193], v[124:127]
	v_mfma_f32_16x16x32_bf16 v[120:123], v[166:169], v[190:193], v[120:123]
	v_mfma_f32_16x16x32_bf16 v[108:111], v[144:147], v[198:201], v[108:111]
	v_mfma_f32_16x16x32_bf16 v[104:107], v[166:169], v[198:201], v[104:107]
	v_mfma_f32_16x16x32_bf16 v[92:95], v[144:147], v[206:209], v[92:95]
	v_mfma_f32_16x16x32_bf16 v[88:91], v[166:169], v[206:209], v[88:91]
	v_mfma_f32_16x16x32_bf16 v[76:79], v[144:147], v[214:217], v[76:79]
	v_mfma_f32_16x16x32_bf16 v[72:75], v[166:169], v[214:217], v[72:75]
	v_mfma_f32_16x16x32_bf16 v[124:127], v[148:151], v[194:197], v[124:127]
	v_mfma_f32_16x16x32_bf16 v[120:123], v[170:173], v[194:197], v[120:123]
	v_mfma_f32_16x16x32_bf16 v[108:111], v[148:151], v[202:205], v[108:111]
	v_mfma_f32_16x16x32_bf16 v[104:107], v[170:173], v[202:205], v[104:107]
	v_mfma_f32_16x16x32_bf16 v[92:95], v[148:151], v[210:213], v[92:95]
	v_mfma_f32_16x16x32_bf16 v[88:91], v[170:173], v[210:213], v[88:91]
	v_mfma_f32_16x16x32_bf16 v[76:79], v[148:151], v[218:221], v[76:79]
	v_mfma_f32_16x16x32_bf16 v[72:75], v[170:173], v[218:221], v[72:75]
	v_mfma_f32_16x16x32_bf16 v[116:119], v[174:177], v[190:193], v[116:119]
	v_mfma_f32_16x16x32_bf16 v[112:115], v[182:185], v[190:193], v[112:115]
	v_mfma_f32_16x16x32_bf16 v[100:103], v[174:177], v[198:201], v[100:103]
	v_mfma_f32_16x16x32_bf16 v[96:99], v[182:185], v[198:201], v[96:99]
	v_mfma_f32_16x16x32_bf16 v[84:87], v[174:177], v[206:209], v[84:87]
	v_mfma_f32_16x16x32_bf16 v[80:83], v[182:185], v[206:209], v[80:83]
	v_mfma_f32_16x16x32_bf16 v[68:71], v[174:177], v[214:217], v[68:71]
	v_mfma_f32_16x16x32_bf16 v[64:67], v[182:185], v[214:217], v[64:67]
	v_mfma_f32_16x16x32_bf16 v[116:119], v[178:181], v[194:197], v[116:119]
	v_mfma_f32_16x16x32_bf16 v[112:115], v[186:189], v[194:197], v[112:115]
	v_mfma_f32_16x16x32_bf16 v[100:103], v[178:181], v[202:205], v[100:103]
	v_mfma_f32_16x16x32_bf16 v[96:99], v[186:189], v[202:205], v[96:99]
	v_mfma_f32_16x16x32_bf16 v[84:87], v[178:181], v[210:213], v[84:87]
	v_mfma_f32_16x16x32_bf16 v[80:83], v[186:189], v[210:213], v[80:83]
	v_mfma_f32_16x16x32_bf16 v[68:71], v[178:181], v[218:221], v[68:71]
	v_mfma_f32_16x16x32_bf16 v[64:67], v[186:189], v[218:221], v[64:67]
	s_barrier
	s_setprio 1
	s_add_i32 s44, s59, s33
	s_mov_b32 m0, s44
	ds_read_b128 v[190:193], v157 offset:49152
	ds_read_b128 v[194:197], v157 offset:50176
	ds_read_b128 v[198:201], v157 offset:51200
	ds_read_b128 v[202:205], v157 offset:52224
	ds_read_b128 v[206:209], v157 offset:53248
	ds_read_b128 v[210:213], v157 offset:54272
	ds_read_b128 v[214:217], v157 offset:55296
	ds_read_b128 v[218:221], v157 offset:56320
	global_load_lds_dwordx4 v132, s[98:99]
	s_add_i32 m0, s44, 0x2000
	s_add_u32 s42, s42, 0x40080
	s_addc_u32 s43, s43, 0
	s_add_i32 s44, s60, s33
	global_load_lds_dwordx4 v128, s[98:99]
	s_mov_b32 m0, s44
	s_nop 0
	global_load_lds_dwordx4 v132, s[42:43]
	s_add_i32 m0, s44, 0x2000
	s_nop 0
	global_load_lds_dwordx4 v128, s[42:43]
	s_mov_b32 m0, s52
	s_nop 0
	global_load_lds_dwordx4 v134, s[100:101]
	s_mov_b32 m0, s53
	s_nop 0
	global_load_lds_dwordx4 v130, s[100:101]
	s_waitcnt vmcnt(8)
	s_waitcnt lgkmcnt(0)
	s_setprio 0
	s_barrier
	v_mfma_f32_16x16x32_bf16 v[60:63], v[144:147], v[190:193], v[60:63]
	v_mfma_f32_16x16x32_bf16 v[56:59], v[166:169], v[190:193], v[56:59]
	v_mfma_f32_16x16x32_bf16 v[44:47], v[144:147], v[198:201], v[44:47]
	v_mfma_f32_16x16x32_bf16 v[40:43], v[166:169], v[198:201], v[40:43]
	v_mfma_f32_16x16x32_bf16 v[28:31], v[144:147], v[206:209], v[28:31]
	v_mfma_f32_16x16x32_bf16 v[24:27], v[166:169], v[206:209], v[24:27]
	v_mfma_f32_16x16x32_bf16 v[12:15], v[144:147], v[214:217], v[12:15]
	v_mfma_f32_16x16x32_bf16 v[8:11], v[166:169], v[214:217], v[8:11]
	v_mfma_f32_16x16x32_bf16 v[60:63], v[148:151], v[194:197], v[60:63]
	v_mfma_f32_16x16x32_bf16 v[56:59], v[170:173], v[194:197], v[56:59]
	v_mfma_f32_16x16x32_bf16 v[44:47], v[148:151], v[202:205], v[44:47]
	v_mfma_f32_16x16x32_bf16 v[40:43], v[170:173], v[202:205], v[40:43]
	v_mfma_f32_16x16x32_bf16 v[28:31], v[148:151], v[210:213], v[28:31]
	v_mfma_f32_16x16x32_bf16 v[24:27], v[170:173], v[210:213], v[24:27]
	v_mfma_f32_16x16x32_bf16 v[12:15], v[148:151], v[218:221], v[12:15]
	v_mfma_f32_16x16x32_bf16 v[8:11], v[170:173], v[218:221], v[8:11]
	v_mfma_f32_16x16x32_bf16 v[52:55], v[174:177], v[190:193], v[52:55]
	v_mfma_f32_16x16x32_bf16 v[48:51], v[182:185], v[190:193], v[48:51]
	v_mfma_f32_16x16x32_bf16 v[36:39], v[174:177], v[198:201], v[36:39]
	v_mfma_f32_16x16x32_bf16 v[32:35], v[182:185], v[198:201], v[32:35]
	v_mfma_f32_16x16x32_bf16 v[20:23], v[174:177], v[206:209], v[20:23]
	v_mfma_f32_16x16x32_bf16 v[16:19], v[182:185], v[206:209], v[16:19]
	v_mfma_f32_16x16x32_bf16 v[4:7], v[174:177], v[214:217], v[4:7]
	v_mfma_f32_16x16x32_bf16 v[0:3], v[182:185], v[214:217], v[0:3]
	v_mfma_f32_16x16x32_bf16 v[52:55], v[178:181], v[194:197], v[52:55]
	v_mfma_f32_16x16x32_bf16 v[48:51], v[186:189], v[194:197], v[48:51]
	v_mfma_f32_16x16x32_bf16 v[36:39], v[178:181], v[202:205], v[36:39]
	v_mfma_f32_16x16x32_bf16 v[32:35], v[186:189], v[202:205], v[32:35]
	v_mfma_f32_16x16x32_bf16 v[20:23], v[178:181], v[210:213], v[20:23]
	v_mfma_f32_16x16x32_bf16 v[16:19], v[186:189], v[210:213], v[16:19]
	v_mfma_f32_16x16x32_bf16 v[4:7], v[178:181], v[218:221], v[4:7]
	v_mfma_f32_16x16x32_bf16 v[0:3], v[186:189], v[218:221], v[0:3]
	s_barrier
	s_setprio 1
	s_add_i32 s58, s58, 2
	s_add_u32 s0, s0, 0x100
	s_addc_u32 s1, s1, 0
	s_add_u32 s31, s31, 0x100
	s_addc_u32 s34, s34, 0
	s_cmp_gt_u32 s58, 13
	s_cbranch_scc0 .LBB0_848
	s_and_b64 vcc, exec, s[18:19]
	s_cbranch_vccz .LBB0_851
	s_barrier

; #define PG8_STAGE(bufoff, gbase, voff) do { _Pragma("unroll") for (int _i = 0; _i < 2; ++_i) \
;         __builtin_amdgcn_global_load_lds((const unsigned*)((const char*)(gbase) + (voff)[_i]), (PG8_LAS unsigned*)(lds + (bufoff) + ldsw + _i * 8192), 16, 0, 0); } while (0)
; #define PG8_LDA(dst, b, h) do { _Pragma("unroll") for (int m = 0; m < 4; ++m) _Pragma("unroll") for (int k = 0; k < 2; ++k) dst[m][k] = *(const PG8_LAS bf16x8*)(lds + PG8_SA(b, h) + aoff + m * 2048 + k * 1024); } while (0)
; #define PG8_LDB(dst, b, h) do { _Pragma("unroll") for (int n = 0; n < 2; ++n) _Pragma("unroll") for (int k = 0; k < 2; ++k) dst[n][k] = *(const PG8_LAS bf16x8*)(lds + PG8_SB(b, h) + boff + n * 2048 + k * 1024); } while (0)
; #define PG8_MMA(ai, bj, At, Bt) do { __builtin_amdgcn_s_setprio(1); _Pragma("unroll") for (int m = 0; m < 4; ++m) _Pragma("unroll") for (int n = 0; n < 2; ++n) _Pragma("unroll") for (int k = 0; k < 2; ++k) \
;         acc[ai][bj][m][n] = __builtin_amdgcn_mfma_f32_16x16x32_bf16(Bt[n][k], At[m][k], acc[ai][bj][m][n], 0, 0, 0); __builtin_amdgcn_s_setprio(0); } while (0)
; #define PG8_WAIT_V(n) asm volatile("s_waitcnt vmcnt(" #n ")" ::: "memory")
; #define PG8_WAIT_L(n) asm volatile("s_waitcnt lgkmcnt(" #n ")" ::: "memory")
; #define PG8_BAR __builtin_amdgcn_s_barrier()
; #define PG8_SCHED __builtin_amdgcn_sched_barrier(0)
; template <class Epi, class Sched, bool ALIGN_EPI = false, bool SP2 = false>
; __device__ __forceinline__ void gemm_phase(PG8_LAS unsigned char* lds, const Gemm g, const Sched& S, const Epi& E) {
;     ...
;             PG8_LDB(B0, 0, 0); PG8_LDB(B1, 0, 1); PG8_SCHED; PG8_LDA(At, 0, 0); PG8_STAGE(PG8_SA(1, 1), a1 + hstepA, voffA);
;             PG8_WAIT_V(8); PG8_WAIT_L(0); PG8_BAR; PG8_MMA(0, 0, At, B0); PG8_MMA(0, 1, At, B1); PG8_BAR; PG8_SCHED;
;             PG8_LDA(At, 0, 1); PG8_STAGE(PG8_SB(0, 0), b2, voffB); PG8_STAGE(PG8_SB(0, 1), b2 + hstepB, voffB); PG8_STAGE(PG8_SA(0, 0), a2, voffA);
;             PG8_WAIT_V(8); PG8_WAIT_L(0); PG8_BAR; PG8_MMA(1, 0, At, B0); PG8_MMA(1, 1, At, B1); PG8_BAR; PG8_SCHED;
.LBB0_927:
	ds_read_b128 v[156:159], v153
	ds_read_b128 v[166:169], v153 offset:1024
	ds_read_b128 v[170:173], v153 offset:2048
	ds_read_b128 v[174:177], v153 offset:3072
	ds_read_b128 v[178:181], v154
	ds_read_b128 v[182:185], v154 offset:1024
	ds_read_b128 v[186:189], v154 offset:2048
	ds_read_b128 v[190:193], v154 offset:3072
	s_add_u32 s54, s52, 0xfff80080
	s_addc_u32 s55, s53, -1
	s_cmp_eq_u32 s71, 28
	s_cselect_b32 s57, s45, s55
	s_cselect_b32 s56, s65, s54
	s_cselect_b32 s55, s43, s70
	s_cselect_b32 s54, s68, s69
	s_add_i32 m0, s29, 0xc000
	ds_read_b128 v[194:197], v155
	ds_read_b128 v[198:201], v155 offset:1024
	ds_read_b128 v[202:205], v155 offset:2048
	ds_read_b128 v[206:209], v155 offset:3072
	ds_read_b128 v[210:213], v155 offset:4096
	ds_read_b128 v[214:217], v155 offset:5120
	ds_read_b128 v[218:221], v155 offset:6144
	ds_read_b128 v[222:225], v155 offset:7168
	global_load_lds_dwordx4 v136, s[52:53]
	s_add_i32 m0, s29, 0xe000
	s_nop 0
	global_load_lds_dwordx4 v138, s[52:53]
	s_waitcnt vmcnt(8)
	s_waitcnt lgkmcnt(0)
	s_setprio 0
	s_barrier
	v_mfma_f32_16x16x32_bf16 v[124:127], v[156:159], v[194:197], v[124:127]
	v_mfma_f32_16x16x32_bf16 v[120:123], v[170:173], v[194:197], v[120:123]
	v_mfma_f32_16x16x32_bf16 v[116:119], v[156:159], v[202:205], v[116:119]
	v_mfma_f32_16x16x32_bf16 v[108:111], v[170:173], v[202:205], v[108:111]
	v_mfma_f32_16x16x32_bf16 v[100:103], v[156:159], v[210:213], v[100:103]
	v_mfma_f32_16x16x32_bf16 v[92:95], v[170:173], v[210:213], v[92:95]
	v_mfma_f32_16x16x32_bf16 v[84:87], v[156:159], v[218:221], v[84:87]
	v_mfma_f32_16x16x32_bf16 v[76:79], v[170:173], v[218:221], v[76:79]
	v_mfma_f32_16x16x32_bf16 v[124:127], v[166:169], v[198:201], v[124:127]
	v_mfma_f32_16x16x32_bf16 v[120:123], v[174:177], v[198:201], v[120:123]
	v_mfma_f32_16x16x32_bf16 v[116:119], v[166:169], v[206:209], v[116:119]
	v_mfma_f32_16x16x32_bf16 v[108:111], v[174:177], v[206:209], v[108:111]
	v_mfma_f32_16x16x32_bf16 v[100:103], v[166:169], v[214:217], v[100:103]
	v_mfma_f32_16x16x32_bf16 v[92:95], v[174:177], v[214:217], v[92:95]
	v_mfma_f32_16x16x32_bf16 v[84:87], v[166:169], v[222:225], v[84:87]
	v_mfma_f32_16x16x32_bf16 v[76:79], v[174:177], v[222:225], v[76:79]
	v_mfma_f32_16x16x32_bf16 v[112:115], v[178:181], v[194:197], v[112:115]
	v_mfma_f32_16x16x32_bf16 v[104:107], v[186:189], v[194:197], v[104:107]
	v_mfma_f32_16x16x32_bf16 v[96:99], v[178:181], v[202:205], v[96:99]
	v_mfma_f32_16x16x32_bf16 v[88:91], v[186:189], v[202:205], v[88:91]
	v_mfma_f32_16x16x32_bf16 v[80:83], v[178:181], v[210:213], v[80:83]
	v_mfma_f32_16x16x32_bf16 v[72:75], v[186:189], v[210:213], v[72:75]
	v_mfma_f32_16x16x32_bf16 v[68:71], v[178:181], v[218:221], v[68:71]
	v_mfma_f32_16x16x32_bf16 v[64:67], v[186:189], v[218:221], v[64:67]
	v_mfma_f32_16x16x32_bf16 v[112:115], v[182:185], v[198:201], v[112:115]
	v_mfma_f32_16x16x32_bf16 v[104:107], v[190:193], v[198:201], v[104:107]
	v_mfma_f32_16x16x32_bf16 v[96:99], v[182:185], v[206:209], v[96:99]
	v_mfma_f32_16x16x32_bf16 v[88:91], v[190:193], v[206:209], v[88:91]
	v_mfma_f32_16x16x32_bf16 v[80:83], v[182:185], v[214:217], v[80:83]
	v_mfma_f32_16x16x32_bf16 v[72:75], v[190:193], v[214:217], v[72:75]
	v_mfma_f32_16x16x32_bf16 v[68:71], v[182:185], v[222:225], v[68:71]
	v_mfma_f32_16x16x32_bf16 v[64:67], v[190:193], v[222:225], v[64:67]
	s_barrier
	s_setprio 1
	s_add_u32 s98, s54, s16
	s_addc_u32 s99, s55, s17
	s_add_u32 s100, s56, s16
	s_addc_u32 s101, s57, s17
	s_add_i32 s72, s58, s28
	s_mov_b32 m0, s72
	ds_read_b128 v[194:197], v155 offset:16384
	ds_read_b128 v[198:201], v155 offset:17408
	ds_read_b128 v[202:205], v155 offset:18432
	ds_read_b128 v[206:209], v155 offset:19456
	ds_read_b128 v[210:213], v155 offset:20480
	ds_read_b128 v[214:217], v155 offset:21504
	ds_read_b128 v[218:221], v155 offset:22528
	ds_read_b128 v[222:225], v155 offset:23552
	global_load_lds_dwordx4 v130, s[54:55]
	s_add_i32 m0, s72, 0x2000
	s_add_u32 s72, s54, 0x80000
	s_addc_u32 s73, s55, 0
	s_add_i32 s74, s59, s28
	global_load_lds_dwordx4 v134, s[54:55]
	s_mov_b32 m0, s74
	s_nop 0
	global_load_lds_dwordx4 v130, s[72:73]
	s_add_i32 m0, s74, 0x2000
	s_nop 0
	global_load_lds_dwordx4 v134, s[72:73]
	s_mov_b32 m0, s29
	s_nop 0
	global_load_lds_dwordx4 v128, s[56:57]
	s_mov_b32 m0, s30
	s_nop 0
	global_load_lds_dwordx4 v132, s[56:57]
	s_waitcnt vmcnt(8)
	s_waitcnt lgkmcnt(0)
	s_setprio 0
	s_barrier
	v_mfma_f32_16x16x32_bf16 v[60:63], v[156:159], v[194:197], v[60:63]
	v_mfma_f32_16x16x32_bf16 v[56:59], v[170:173], v[194:197], v[56:59]
	v_mfma_f32_16x16x32_bf16 v[52:55], v[156:159], v[202:205], v[52:55]
	v_mfma_f32_16x16x32_bf16 v[44:47], v[170:173], v[202:205], v[44:47]
	v_mfma_f32_16x16x32_bf16 v[36:39], v[156:159], v[210:213], v[36:39]
	v_mfma_f32_16x16x32_bf16 v[28:31], v[170:173], v[210:213], v[28:31]
	v_mfma_f32_16x16x32_bf16 v[20:23], v[156:159], v[218:221], v[20:23]
	v_mfma_f32_16x16x32_bf16 v[12:15], v[170:173], v[218:221], v[12:15]
	v_mfma_f32_16x16x32_bf16 v[60:63], v[166:169], v[198:201], v[60:63]
	v_mfma_f32_16x16x32_bf16 v[56:59], v[174:177], v[198:201], v[56:59]
	v_mfma_f32_16x16x32_bf16 v[52:55], v[166:169], v[206:209], v[52:55]
	v_mfma_f32_16x16x32_bf16 v[44:47], v[174:177], v[206:209], v[44:47]
	v_mfma_f32_16x16x32_bf16 v[36:39], v[166:169], v[214:217], v[36:39]
	v_mfma_f32_16x16x32_bf16 v[28:31], v[174:177], v[214:217], v[28:31]
	v_mfma_f32_16x16x32_bf16 v[20:23], v[166:169], v[222:225], v[20:23]
	v_mfma_f32_16x16x32_bf16 v[12:15], v[174:177], v[222:225], v[12:15]
	v_mfma_f32_16x16x32_bf16 v[48:51], v[178:181], v[194:197], v[48:51]
	v_mfma_f32_16x16x32_bf16 v[40:43], v[186:189], v[194:197], v[40:43]
	v_mfma_f32_16x16x32_bf16 v[32:35], v[178:181], v[202:205], v[32:35]
	v_mfma_f32_16x16x32_bf16 v[24:27], v[186:189], v[202:205], v[24:27]
	v_mfma_f32_16x16x32_bf16 v[16:19], v[178:181], v[210:213], v[16:19]
	v_mfma_f32_16x16x32_bf16 v[8:11], v[186:189], v[210:213], v[8:11]
	v_mfma_f32_16x16x32_bf16 v[4:7], v[178:181], v[218:221], v[4:7]
	v_mfma_f32_16x16x32_bf16 v[0:3], v[186:189], v[218:221], v[0:3]
	v_mfma_f32_16x16x32_bf16 v[48:51], v[182:185], v[198:201], v[48:51]
	v_mfma_f32_16x16x32_bf16 v[40:43], v[190:193], v[198:201], v[40:43]
	v_mfma_f32_16x16x32_bf16 v[32:35], v[182:185], v[206:209], v[32:35]
	v_mfma_f32_16x16x32_bf16 v[24:27], v[190:193], v[206:209], v[24:27]
	v_mfma_f32_16x16x32_bf16 v[16:19], v[182:185], v[214:217], v[16:19]
	v_mfma_f32_16x16x32_bf16 v[8:11], v[190:193], v[214:217], v[8:11]
	v_mfma_f32_16x16x32_bf16 v[4:7], v[182:185], v[222:225], v[4:7]
	v_mfma_f32_16x16x32_bf16 v[0:3], v[190:193], v[222:225], v[0:3]
	s_barrier
; #define PG8_STAGE(bufoff, gbase, voff) do { _Pragma("unroll") for (int _i = 0; _i < 2; ++_i) \
;         __builtin_amdgcn_global_load_lds((const unsigned*)((const char*)(gbase) + (voff)[_i]), (PG8_LAS unsigned*)(lds + (bufoff) + ldsw + _i * 8192), 16, 0, 0); } while (0)
; #define PG8_LDA(dst, b, h) do { _Pragma("unroll") for (int m = 0; m < 4; ++m) _Pragma("unroll") for (int k = 0; k < 2; ++k) dst[m][k] = *(const PG8_LAS bf16x8*)(lds + PG8_SA(b, h) + aoff + m * 2048 + k * 1024); } while (0)
; #define PG8_LDB(dst, b, h) do { _Pragma("unroll") for (int n = 0; n < 2; ++n) _Pragma("unroll") for (int k = 0; k < 2; ++k) dst[n][k] = *(const PG8_LAS bf16x8*)(lds + PG8_SB(b, h) + boff + n * 2048 + k * 1024); } while (0)
; #define PG8_MMA(ai, bj, At, Bt) do { __builtin_amdgcn_s_setprio(1); _Pragma("unroll") for (int m = 0; m < 4; ++m) _Pragma("unroll") for (int n = 0; n < 2; ++n) _Pragma("unroll") for (int k = 0; k < 2; ++k) \
;         acc[ai][bj][m][n] = __builtin_amdgcn_mfma_f32_16x16x32_bf16(Bt[n][k], At[m][k], acc[ai][bj][m][n], 0, 0, 0); __builtin_amdgcn_s_setprio(0); } while (0)
; #define PG8_WAIT_V(n) asm volatile("s_waitcnt vmcnt(" #n ")" ::: "memory")
; #define PG8_WAIT_L(n) asm volatile("s_waitcnt lgkmcnt(" #n ")" ::: "memory")
; #define PG8_BAR __builtin_amdgcn_s_barrier()
; #define PG8_SCHED __builtin_amdgcn_sched_barrier(0)
; template <class Epi, class Sched, bool ALIGN_EPI = false, bool SP2 = false>
; __device__ __forceinline__ void gemm_phase(PG8_LAS unsigned char* lds, const Gemm g, const Sched& S, const Epi& E) {
;     ...
;             PG8_LDB(B0, 1, 0); PG8_LDB(B1, 1, 1); PG8_SCHED; PG8_LDA(At, 1, 0); PG8_STAGE(PG8_SA(0, 1), a2 + hstepA, voffA);
;             PG8_WAIT_V(8); PG8_WAIT_L(0); PG8_BAR; PG8_MMA(0, 0, At, B0); PG8_MMA(0, 1, At, B1); PG8_BAR; PG8_SCHED;
;             PG8_LDA(At, 1, 1); PG8_STAGE(PG8_SB(1, 0), b3, voffB); PG8_STAGE(PG8_SB(1, 1), b3 + hstepB, voffB); PG8_STAGE(PG8_SA(1, 0), a3, voffA);
;             PG8_WAIT_V(8); PG8_WAIT_L(0); PG8_BAR; PG8_MMA(1, 0, At, B0); PG8_MMA(1, 1, At, B1); PG8_BAR; PG8_SCHED;
;     ...
;         if constexpr (ALIGN_EPI) { if (wr == 0) PG8_BAR; }
	s_setprio 1
	s_add_i32 s72, 0, 0x18000
	v_add_u32_e32 v163, s72, v151
	s_add_i32 s73, 0, 0x1c000
	ds_read_b128 v[156:159], v163
	ds_read_b128 v[166:169], v163 offset:1024
	ds_read_b128 v[170:173], v163 offset:2048
	ds_read_b128 v[174:177], v163 offset:3072
	v_add_u32_e32 v163, s73, v151
	ds_read_b128 v[178:181], v163
	ds_read_b128 v[182:185], v163 offset:1024
	ds_read_b128 v[186:189], v163 offset:2048
	ds_read_b128 v[190:193], v163 offset:3072
	s_add_u32 s56, s56, 0x80000
	s_addc_u32 s57, s57, 0
	s_mov_b32 m0, s31
	ds_read_b128 v[194:197], v155 offset:32768
	ds_read_b128 v[198:201], v155 offset:33792
	ds_read_b128 v[202:205], v155 offset:34816
	ds_read_b128 v[206:209], v155 offset:35840
	ds_read_b128 v[210:213], v155 offset:36864
	ds_read_b128 v[214:217], v155 offset:37888
	ds_read_b128 v[218:221], v155 offset:38912
	ds_read_b128 v[222:225], v155 offset:39936
	global_load_lds_dwordx4 v128, s[56:57]
	s_mov_b32 m0, s33
	s_nop 0
	global_load_lds_dwordx4 v132, s[56:57]
	s_waitcnt vmcnt(8)
	s_waitcnt lgkmcnt(0)
	s_setprio 0
	s_barrier
	v_mfma_f32_16x16x32_bf16 v[124:127], v[156:159], v[194:197], v[124:127]
	v_mfma_f32_16x16x32_bf16 v[120:123], v[170:173], v[194:197], v[120:123]
	v_mfma_f32_16x16x32_bf16 v[116:119], v[156:159], v[202:205], v[116:119]
	v_mfma_f32_16x16x32_bf16 v[108:111], v[170:173], v[202:205], v[108:111]
	v_mfma_f32_16x16x32_bf16 v[100:103], v[156:159], v[210:213], v[100:103]
	v_mfma_f32_16x16x32_bf16 v[92:95], v[170:173], v[210:213], v[92:95]
	v_mfma_f32_16x16x32_bf16 v[84:87], v[156:159], v[218:221], v[84:87]
	v_mfma_f32_16x16x32_bf16 v[76:79], v[170:173], v[218:221], v[76:79]
	v_mfma_f32_16x16x32_bf16 v[124:127], v[166:169], v[198:201], v[124:127]
	v_mfma_f32_16x16x32_bf16 v[120:123], v[174:177], v[198:201], v[120:123]
	v_mfma_f32_16x16x32_bf16 v[116:119], v[166:169], v[206:209], v[116:119]
	v_mfma_f32_16x16x32_bf16 v[108:111], v[174:177], v[206:209], v[108:111]
	v_mfma_f32_16x16x32_bf16 v[100:103], v[166:169], v[214:217], v[100:103]
	v_mfma_f32_16x16x32_bf16 v[92:95], v[174:177], v[214:217], v[92:95]
	v_mfma_f32_16x16x32_bf16 v[84:87], v[166:169], v[222:225], v[84:87]
	v_mfma_f32_16x16x32_bf16 v[76:79], v[174:177], v[222:225], v[76:79]
	v_mfma_f32_16x16x32_bf16 v[112:115], v[178:181], v[194:197], v[112:115]
	v_mfma_f32_16x16x32_bf16 v[104:107], v[186:189], v[194:197], v[104:107]
	v_mfma_f32_16x16x32_bf16 v[96:99], v[178:181], v[202:205], v[96:99]
	v_mfma_f32_16x16x32_bf16 v[88:91], v[186:189], v[202:205], v[88:91]
	v_mfma_f32_16x16x32_bf16 v[80:83], v[178:181], v[210:213], v[80:83]
	v_mfma_f32_16x16x32_bf16 v[72:75], v[186:189], v[210:213], v[72:75]
	v_mfma_f32_16x16x32_bf16 v[68:71], v[178:181], v[218:221], v[68:71]
	v_mfma_f32_16x16x32_bf16 v[64:67], v[186:189], v[218:221], v[64:67]
	v_mfma_f32_16x16x32_bf16 v[112:115], v[182:185], v[198:201], v[112:115]
	v_mfma_f32_16x16x32_bf16 v[104:107], v[190:193], v[198:201], v[104:107]
	v_mfma_f32_16x16x32_bf16 v[96:99], v[182:185], v[206:209], v[96:99]
	v_mfma_f32_16x16x32_bf16 v[88:91], v[190:193], v[206:209], v[88:91]
	v_mfma_f32_16x16x32_bf16 v[80:83], v[182:185], v[214:217], v[80:83]
	v_mfma_f32_16x16x32_bf16 v[72:75], v[190:193], v[214:217], v[72:75]
	v_mfma_f32_16x16x32_bf16 v[68:71], v[182:185], v[222:225], v[68:71]
	v_mfma_f32_16x16x32_bf16 v[64:67], v[190:193], v[222:225], v[64:67]
	s_barrier
	s_setprio 1
	s_add_i32 s56, s72, s28
	s_mov_b32 m0, s56
	ds_read_b128 v[194:197], v155 offset:49152
	ds_read_b128 v[198:201], v155 offset:50176
	ds_read_b128 v[202:205], v155 offset:51200
	ds_read_b128 v[206:209], v155 offset:52224
	ds_read_b128 v[210:213], v155 offset:53248
	ds_read_b128 v[214:217], v155 offset:54272
	ds_read_b128 v[218:221], v155 offset:55296
	ds_read_b128 v[222:225], v155 offset:56320
	global_load_lds_dwordx4 v130, s[98:99]
	s_add_i32 m0, s56, 0x2000
	s_add_u32 s54, s54, 0x80080
	s_addc_u32 s55, s55, 0
	s_add_i32 s56, s73, s28
	global_load_lds_dwordx4 v134, s[98:99]
	s_mov_b32 m0, s56
	s_nop 0
	global_load_lds_dwordx4 v130, s[54:55]
	s_add_i32 m0, s56, 0x2000
	s_nop 0
	global_load_lds_dwordx4 v134, s[54:55]
	s_mov_b32 m0, s35
	s_nop 0
	global_load_lds_dwordx4 v128, s[100:101]
	s_mov_b32 m0, s51
	s_nop 0
	global_load_lds_dwordx4 v132, s[100:101]
	s_waitcnt vmcnt(8)
	s_waitcnt lgkmcnt(0)
	s_setprio 0
	s_barrier
	v_mfma_f32_16x16x32_bf16 v[60:63], v[156:159], v[194:197], v[60:63]
	v_mfma_f32_16x16x32_bf16 v[56:59], v[170:173], v[194:197], v[56:59]
	v_mfma_f32_16x16x32_bf16 v[52:55], v[156:159], v[202:205], v[52:55]
	v_mfma_f32_16x16x32_bf16 v[44:47], v[170:173], v[202:205], v[44:47]
	v_mfma_f32_16x16x32_bf16 v[36:39], v[156:159], v[210:213], v[36:39]
	v_mfma_f32_16x16x32_bf16 v[28:31], v[170:173], v[210:213], v[28:31]
	v_mfma_f32_16x16x32_bf16 v[20:23], v[156:159], v[218:221], v[20:23]
	v_mfma_f32_16x16x32_bf16 v[12:15], v[170:173], v[218:221], v[12:15]
	v_mfma_f32_16x16x32_bf16 v[60:63], v[166:169], v[198:201], v[60:63]
	v_mfma_f32_16x16x32_bf16 v[56:59], v[174:177], v[198:201], v[56:59]
	v_mfma_f32_16x16x32_bf16 v[52:55], v[166:169], v[206:209], v[52:55]
	v_mfma_f32_16x16x32_bf16 v[44:47], v[174:177], v[206:209], v[44:47]
	v_mfma_f32_16x16x32_bf16 v[36:39], v[166:169], v[214:217], v[36:39]
	v_mfma_f32_16x16x32_bf16 v[28:31], v[174:177], v[214:217], v[28:31]
	v_mfma_f32_16x16x32_bf16 v[20:23], v[166:169], v[222:225], v[20:23]
	v_mfma_f32_16x16x32_bf16 v[12:15], v[174:177], v[222:225], v[12:15]
	v_mfma_f32_16x16x32_bf16 v[48:51], v[178:181], v[194:197], v[48:51]
	v_mfma_f32_16x16x32_bf16 v[40:43], v[186:189], v[194:197], v[40:43]
	v_mfma_f32_16x16x32_bf16 v[32:35], v[178:181], v[202:205], v[32:35]
	v_mfma_f32_16x16x32_bf16 v[24:27], v[186:189], v[202:205], v[24:27]
	v_mfma_f32_16x16x32_bf16 v[16:19], v[178:181], v[210:213], v[16:19]
	v_mfma_f32_16x16x32_bf16 v[8:11], v[186:189], v[210:213], v[8:11]
	v_mfma_f32_16x16x32_bf16 v[4:7], v[178:181], v[218:221], v[4:7]
	v_mfma_f32_16x16x32_bf16 v[0:3], v[186:189], v[218:221], v[0:3]
	v_mfma_f32_16x16x32_bf16 v[48:51], v[182:185], v[198:201], v[48:51]
	v_mfma_f32_16x16x32_bf16 v[40:43], v[190:193], v[198:201], v[40:43]
	v_mfma_f32_16x16x32_bf16 v[32:35], v[182:185], v[206:209], v[32:35]
	v_mfma_f32_16x16x32_bf16 v[24:27], v[190:193], v[206:209], v[24:27]
	v_mfma_f32_16x16x32_bf16 v[16:19], v[182:185], v[214:217], v[16:19]
	v_mfma_f32_16x16x32_bf16 v[8:11], v[190:193], v[214:217], v[8:11]
	v_mfma_f32_16x16x32_bf16 v[4:7], v[182:185], v[222:225], v[4:7]
	v_mfma_f32_16x16x32_bf16 v[0:3], v[190:193], v[222:225], v[0:3]
	s_barrier
	s_setprio 1
	s_add_i32 s71, s71, 2
	s_add_u32 s52, s52, 0x100
	s_addc_u32 s53, s53, 0
	s_add_u32 s69, s69, 0x100
	s_addc_u32 s70, s70, 0
	s_cmp_gt_u32 s71, 29
	s_cbranch_scc0 .LBB0_927
	s_and_b64 vcc, exec, s[18:19]
	s_cbranch_vccz .LBB0_930
	s_barrier

; #define PG8_STAGE(bufoff, gbase, voff) do { _Pragma("unroll") for (int _i = 0; _i < 2; ++_i) \
;         __builtin_amdgcn_global_load_lds((const unsigned*)((const char*)(gbase) + (voff)[_i]), (PG8_LAS unsigned*)(lds + (bufoff) + ldsw + _i * 8192), 16, 0, 0); } while (0)
; #define PG8_LDA(dst, b, h) do { _Pragma("unroll") for (int m = 0; m < 4; ++m) _Pragma("unroll") for (int k = 0; k < 2; ++k) dst[m][k] = *(const PG8_LAS bf16x8*)(lds + PG8_SA(b, h) + aoff + m * 2048 + k * 1024); } while (0)
; #define PG8_LDB(dst, b, h) do { _Pragma("unroll") for (int n = 0; n < 2; ++n) _Pragma("unroll") for (int k = 0; k < 2; ++k) dst[n][k] = *(const PG8_LAS bf16x8*)(lds + PG8_SB(b, h) + boff + n * 2048 + k * 1024); } while (0)
; #define PG8_MMA(ai, bj, At, Bt) do { __builtin_amdgcn_s_setprio(1); _Pragma("unroll") for (int m = 0; m < 4; ++m) _Pragma("unroll") for (int n = 0; n < 2; ++n) _Pragma("unroll") for (int k = 0; k < 2; ++k) \
;         acc[ai][bj][m][n] = __builtin_amdgcn_mfma_f32_16x16x32_bf16(Bt[n][k], At[m][k], acc[ai][bj][m][n], 0, 0, 0); __builtin_amdgcn_s_setprio(0); } while (0)
; #define PG8_WAIT_V(n) asm volatile("s_waitcnt vmcnt(" #n ")" ::: "memory")
; #define PG8_WAIT_L(n) asm volatile("s_waitcnt lgkmcnt(" #n ")" ::: "memory")
; #define PG8_BAR __builtin_amdgcn_s_barrier()
; #define PG8_SCHED __builtin_amdgcn_sched_barrier(0)
; template <class Epi, class Sched, bool ALIGN_EPI = false, bool SP2 = false>
; __device__ __forceinline__ void gemm_phase(PG8_LAS unsigned char* lds, const Gemm g, const Sched& S, const Epi& E) {
;     ...
;             const bool last = (t == nt - 2);
;             const char* a1 = cA + (size_t)(t + 1) * kstep;
;             const char* a2 = last ? nA : cA + (size_t)(t + 2) * kstep; const char* b2 = last ? nB : cB + (size_t)(t + 2) * kstep;
;             const char* a3 = a2 + kstep; const char* b3 = b2 + kstep;
;             if (last && has_next) S.a_ready(nxt);
;             if constexpr (SP2) {
;             PG8_LDB(B0, 0, 0); PG8_LDB(B1, 0, 1); PG8_SCHED; PG8_LDA(At, 0, 0); PG8_STAGE(PG8_SA(1, 1), a1 + hstepA, voffA);
;             PG8_WAIT_V(8); PG8_WAIT_L(0); PG8_BAR; PG8_MMA(0, 0, At, B0); PG8_MMA(0, 1, At, B1); PG8_BAR; PG8_SCHED;
;             PG8_LDA(At, 0, 1); PG8_STAGE(PG8_SB(0, 0), b2, voffB); PG8_STAGE(PG8_SB(0, 1), b2 + hstepB, voffB); PG8_STAGE(PG8_SA(0, 0), a2, voffA);
.LBB0_947:
	s_add_u32 s45, s50, s19
	s_addc_u32 s47, s51, 0
	s_add_u32 s49, s45, 0x100
	s_addc_u32 s60, s47, 0
	s_and_b64 s[58:59], s[56:57], exec
	s_cselect_b32 s61, s1, s60
	s_cselect_b32 s60, s0, s49
	s_add_u32 s19, s42, s19
	s_addc_u32 s49, s43, 0
	s_add_u32 s19, s19, 0x100
	s_addc_u32 s49, s49, 0
	s_and_b64 s[56:57], s[56:57], exec
	s_cselect_b32 s63, s53, s49
	s_cselect_b32 s62, s52, s19
	s_add_u32 s68, s45, 0x80080
	ds_read_b128 v[146:149], v143
	ds_read_b128 v[150:153], v143 offset:1024
	ds_read_b128 v[154:157], v143 offset:2048
	ds_read_b128 v[158:161], v143 offset:3072
	ds_read_b128 v[166:169], v144
	ds_read_b128 v[170:173], v144 offset:1024
	ds_read_b128 v[174:177], v144 offset:2048
	ds_read_b128 v[178:181], v144 offset:3072
	s_addc_u32 s69, s47, 0
	s_add_u32 s64, s62, 0x80000
	s_addc_u32 s65, s63, 0
	s_add_i32 s79, s71, s30
	s_add_i32 s78, s79, 0x2000
	s_add_i32 s77, 0, 0x18000
	s_add_i32 s76, 0, 0x1c000
	s_add_u32 s58, s60, 0x80000
	s_addc_u32 s59, s61, 0
	s_add_i32 s49, s77, s30
	s_add_i32 s45, s49, 0x2000
	s_add_u32 s56, s62, 0x80080
	s_addc_u32 s57, s63, 0
	s_add_i32 s47, s76, s30
	s_add_i32 s19, s47, 0x2000
	s_mov_b32 m0, s72
	ds_read_b128 v[182:185], v145
	ds_read_b128 v[186:189], v145 offset:1024
	ds_read_b128 v[190:193], v145 offset:2048
	ds_read_b128 v[194:197], v145 offset:3072
	ds_read_b128 v[198:201], v145 offset:4096
	ds_read_b128 v[202:205], v145 offset:5120
	ds_read_b128 v[206:209], v145 offset:6144
	ds_read_b128 v[210:213], v145 offset:7168
	global_load_lds_dwordx4 v128, s[68:69]
	s_mov_b32 m0, s73
	s_nop 0
	global_load_lds_dwordx4 v132, s[68:69]
	s_waitcnt vmcnt(8)
	s_waitcnt lgkmcnt(0)
	s_setprio 0
	s_barrier
	v_mfma_f32_16x16x32_bf16 v[124:127], v[146:149], v[182:185], v[124:127]
	v_mfma_f32_16x16x32_bf16 v[120:123], v[154:157], v[182:185], v[120:123]
	v_mfma_f32_16x16x32_bf16 v[116:119], v[146:149], v[190:193], v[116:119]
	v_mfma_f32_16x16x32_bf16 v[112:115], v[154:157], v[190:193], v[112:115]
	v_mfma_f32_16x16x32_bf16 v[100:103], v[146:149], v[198:201], v[100:103]
	v_mfma_f32_16x16x32_bf16 v[96:99], v[154:157], v[198:201], v[96:99]
	v_mfma_f32_16x16x32_bf16 v[84:87], v[146:149], v[206:209], v[84:87]
	v_mfma_f32_16x16x32_bf16 v[80:83], v[154:157], v[206:209], v[80:83]
	v_mfma_f32_16x16x32_bf16 v[124:127], v[150:153], v[186:189], v[124:127]
	v_mfma_f32_16x16x32_bf16 v[120:123], v[158:161], v[186:189], v[120:123]
	v_mfma_f32_16x16x32_bf16 v[116:119], v[150:153], v[194:197], v[116:119]
	v_mfma_f32_16x16x32_bf16 v[112:115], v[158:161], v[194:197], v[112:115]
	v_mfma_f32_16x16x32_bf16 v[100:103], v[150:153], v[202:205], v[100:103]
	v_mfma_f32_16x16x32_bf16 v[96:99], v[158:161], v[202:205], v[96:99]
	v_mfma_f32_16x16x32_bf16 v[84:87], v[150:153], v[210:213], v[84:87]
	v_mfma_f32_16x16x32_bf16 v[80:83], v[158:161], v[210:213], v[80:83]
	v_mfma_f32_16x16x32_bf16 v[108:111], v[166:169], v[182:185], v[108:111]
	v_mfma_f32_16x16x32_bf16 v[104:107], v[174:177], v[182:185], v[104:107]
	v_mfma_f32_16x16x32_bf16 v[92:95], v[166:169], v[190:193], v[92:95]
	v_mfma_f32_16x16x32_bf16 v[88:91], v[174:177], v[190:193], v[88:91]
	v_mfma_f32_16x16x32_bf16 v[76:79], v[166:169], v[198:201], v[76:79]
	v_mfma_f32_16x16x32_bf16 v[72:75], v[174:177], v[198:201], v[72:75]
	v_mfma_f32_16x16x32_bf16 v[68:71], v[166:169], v[206:209], v[68:71]
	v_mfma_f32_16x16x32_bf16 v[64:67], v[174:177], v[206:209], v[64:67]
	v_mfma_f32_16x16x32_bf16 v[108:111], v[170:173], v[186:189], v[108:111]
	v_mfma_f32_16x16x32_bf16 v[104:107], v[178:181], v[186:189], v[104:107]
	v_mfma_f32_16x16x32_bf16 v[92:95], v[170:173], v[194:197], v[92:95]
	v_mfma_f32_16x16x32_bf16 v[88:91], v[178:181], v[194:197], v[88:91]
	v_mfma_f32_16x16x32_bf16 v[76:79], v[170:173], v[202:205], v[76:79]
	v_mfma_f32_16x16x32_bf16 v[72:75], v[178:181], v[202:205], v[72:75]
	v_mfma_f32_16x16x32_bf16 v[68:71], v[170:173], v[210:213], v[68:71]
	v_mfma_f32_16x16x32_bf16 v[64:67], v[178:181], v[210:213], v[64:67]
	s_barrier
	s_setprio 1
	s_add_u32 s98, s62, s16
	s_addc_u32 s99, s63, s17
	s_add_u32 s100, s60, s16
	s_addc_u32 s101, s61, s17
	s_mov_b32 m0, s74
	ds_read_b128 v[182:185], v145 offset:16384
	ds_read_b128 v[186:189], v145 offset:17408
	ds_read_b128 v[190:193], v145 offset:18432
	ds_read_b128 v[194:197], v145 offset:19456
	ds_read_b128 v[198:201], v145 offset:20480
	ds_read_b128 v[202:205], v145 offset:21504
	ds_read_b128 v[206:209], v145 offset:22528
	ds_read_b128 v[210:213], v145 offset:23552
	global_load_lds_dwordx4 v130, s[62:63]
	s_mov_b32 m0, s75
	s_nop 0
	global_load_lds_dwordx4 v134, s[62:63]
	s_mov_b32 m0, s79
	s_nop 0
	global_load_lds_dwordx4 v130, s[64:65]
	s_mov_b32 m0, s78
	s_nop 0
	global_load_lds_dwordx4 v134, s[64:65]
	s_mov_b32 m0, s21
	s_nop 0
	global_load_lds_dwordx4 v128, s[60:61]
	s_mov_b32 m0, s23
	s_nop 0
	global_load_lds_dwordx4 v132, s[60:61]
	s_waitcnt vmcnt(8)
	s_waitcnt lgkmcnt(0)
	s_setprio 0
	s_barrier
; #define PG8_STAGE(bufoff, gbase, voff) do { _Pragma("unroll") for (int _i = 0; _i < 2; ++_i) \
;         __builtin_amdgcn_global_load_lds((const unsigned*)((const char*)(gbase) + (voff)[_i]), (PG8_LAS unsigned*)(lds + (bufoff) + ldsw + _i * 8192), 16, 0, 0); } while (0)
; #define PG8_LDA(dst, b, h) do { _Pragma("unroll") for (int m = 0; m < 4; ++m) _Pragma("unroll") for (int k = 0; k < 2; ++k) dst[m][k] = *(const PG8_LAS bf16x8*)(lds + PG8_SA(b, h) + aoff + m * 2048 + k * 1024); } while (0)
; #define PG8_LDB(dst, b, h) do { _Pragma("unroll") for (int n = 0; n < 2; ++n) _Pragma("unroll") for (int k = 0; k < 2; ++k) dst[n][k] = *(const PG8_LAS bf16x8*)(lds + PG8_SB(b, h) + boff + n * 2048 + k * 1024); } while (0)
; #define PG8_MMA(ai, bj, At, Bt) do { __builtin_amdgcn_s_setprio(1); _Pragma("unroll") for (int m = 0; m < 4; ++m) _Pragma("unroll") for (int n = 0; n < 2; ++n) _Pragma("unroll") for (int k = 0; k < 2; ++k) \
;         acc[ai][bj][m][n] = __builtin_amdgcn_mfma_f32_16x16x32_bf16(Bt[n][k], At[m][k], acc[ai][bj][m][n], 0, 0, 0); __builtin_amdgcn_s_setprio(0); } while (0)
; #define PG8_WAIT_V(n) asm volatile("s_waitcnt vmcnt(" #n ")" ::: "memory")
; #define PG8_WAIT_L(n) asm volatile("s_waitcnt lgkmcnt(" #n ")" ::: "memory")
; #define PG8_BAR __builtin_amdgcn_s_barrier()
; #define PG8_SCHED __builtin_amdgcn_sched_barrier(0)
; template <class Epi, class Sched, bool ALIGN_EPI = false, bool SP2 = false>
; __device__ __forceinline__ void gemm_phase(PG8_LAS unsigned char* lds, const Gemm g, const Sched& S, const Epi& E) {
;     ...
;             PG8_WAIT_V(8); PG8_WAIT_L(0); PG8_BAR; PG8_MMA(1, 0, At, B0); PG8_MMA(1, 1, At, B1); PG8_BAR; PG8_SCHED;
;             PG8_LDB(B0, 1, 0); PG8_LDB(B1, 1, 1); PG8_SCHED; PG8_LDA(At, 1, 0); PG8_STAGE(PG8_SA(0, 1), a2 + hstepA, voffA);
;             PG8_WAIT_V(8); PG8_WAIT_L(0); PG8_BAR; PG8_MMA(0, 0, At, B0); PG8_MMA(0, 1, At, B1); PG8_BAR; PG8_SCHED;
	v_mfma_f32_16x16x32_bf16 v[60:63], v[146:149], v[182:185], v[60:63]
	v_mfma_f32_16x16x32_bf16 v[56:59], v[154:157], v[182:185], v[56:59]
	v_mfma_f32_16x16x32_bf16 v[52:55], v[146:149], v[190:193], v[52:55]
	v_mfma_f32_16x16x32_bf16 v[48:51], v[154:157], v[190:193], v[48:51]
	v_mfma_f32_16x16x32_bf16 v[36:39], v[146:149], v[198:201], v[36:39]
	v_mfma_f32_16x16x32_bf16 v[32:35], v[154:157], v[198:201], v[32:35]
	v_mfma_f32_16x16x32_bf16 v[20:23], v[146:149], v[206:209], v[20:23]
	v_mfma_f32_16x16x32_bf16 v[16:19], v[154:157], v[206:209], v[16:19]
	v_mfma_f32_16x16x32_bf16 v[60:63], v[150:153], v[186:189], v[60:63]
	v_mfma_f32_16x16x32_bf16 v[56:59], v[158:161], v[186:189], v[56:59]
	v_mfma_f32_16x16x32_bf16 v[52:55], v[150:153], v[194:197], v[52:55]
	v_mfma_f32_16x16x32_bf16 v[48:51], v[158:161], v[194:197], v[48:51]
	v_mfma_f32_16x16x32_bf16 v[36:39], v[150:153], v[202:205], v[36:39]
	v_mfma_f32_16x16x32_bf16 v[32:35], v[158:161], v[202:205], v[32:35]
	v_mfma_f32_16x16x32_bf16 v[20:23], v[150:153], v[210:213], v[20:23]
	v_mfma_f32_16x16x32_bf16 v[16:19], v[158:161], v[210:213], v[16:19]
	v_mfma_f32_16x16x32_bf16 v[44:47], v[166:169], v[182:185], v[44:47]
	v_mfma_f32_16x16x32_bf16 v[40:43], v[174:177], v[182:185], v[40:43]
	v_mfma_f32_16x16x32_bf16 v[28:31], v[166:169], v[190:193], v[28:31]
	v_mfma_f32_16x16x32_bf16 v[24:27], v[174:177], v[190:193], v[24:27]
	v_mfma_f32_16x16x32_bf16 v[12:15], v[166:169], v[198:201], v[12:15]
	v_mfma_f32_16x16x32_bf16 v[8:11], v[174:177], v[198:201], v[8:11]
	v_mfma_f32_16x16x32_bf16 v[4:7], v[166:169], v[206:209], v[4:7]
	v_mfma_f32_16x16x32_bf16 v[0:3], v[174:177], v[206:209], v[0:3]
	v_mfma_f32_16x16x32_bf16 v[44:47], v[170:173], v[186:189], v[44:47]
	v_mfma_f32_16x16x32_bf16 v[40:43], v[178:181], v[186:189], v[40:43]
	v_mfma_f32_16x16x32_bf16 v[28:31], v[170:173], v[194:197], v[28:31]
	v_mfma_f32_16x16x32_bf16 v[24:27], v[178:181], v[194:197], v[24:27]
	v_mfma_f32_16x16x32_bf16 v[12:15], v[170:173], v[202:205], v[12:15]
	v_mfma_f32_16x16x32_bf16 v[8:11], v[178:181], v[202:205], v[8:11]
	v_mfma_f32_16x16x32_bf16 v[4:7], v[170:173], v[210:213], v[4:7]
	v_mfma_f32_16x16x32_bf16 v[0:3], v[178:181], v[210:213], v[0:3]
	s_barrier
	s_setprio 1
	v_add_u32_e32 v158, s77, v141
	v_add_u32_e32 v163, s76, v141
	ds_read_b128 v[146:149], v158
	ds_read_b128 v[150:153], v158 offset:1024
	ds_read_b128 v[154:157], v158 offset:2048
	ds_read_b128 v[158:161], v158 offset:3072
	ds_read_b128 v[166:169], v163
	ds_read_b128 v[170:173], v163 offset:1024
	ds_read_b128 v[174:177], v163 offset:2048
	ds_read_b128 v[178:181], v163 offset:3072
	s_mov_b32 m0, s31
	ds_read_b128 v[182:185], v145 offset:32768
	ds_read_b128 v[186:189], v145 offset:33792
	ds_read_b128 v[190:193], v145 offset:34816
	ds_read_b128 v[194:197], v145 offset:35840
	ds_read_b128 v[198:201], v145 offset:36864
	ds_read_b128 v[202:205], v145 offset:37888
	ds_read_b128 v[206:209], v145 offset:38912
	ds_read_b128 v[210:213], v145 offset:39936
	global_load_lds_dwordx4 v128, s[58:59]
	s_mov_b32 m0, s33
	s_nop 0
	global_load_lds_dwordx4 v132, s[58:59]
	s_waitcnt vmcnt(8)
	s_waitcnt lgkmcnt(0)
	s_setprio 0
	s_barrier
	v_mfma_f32_16x16x32_bf16 v[124:127], v[146:149], v[182:185], v[124:127]
	v_mfma_f32_16x16x32_bf16 v[120:123], v[154:157], v[182:185], v[120:123]
	v_mfma_f32_16x16x32_bf16 v[116:119], v[146:149], v[190:193], v[116:119]
	v_mfma_f32_16x16x32_bf16 v[112:115], v[154:157], v[190:193], v[112:115]
	v_mfma_f32_16x16x32_bf16 v[100:103], v[146:149], v[198:201], v[100:103]
	v_mfma_f32_16x16x32_bf16 v[96:99], v[154:157], v[198:201], v[96:99]
	v_mfma_f32_16x16x32_bf16 v[84:87], v[146:149], v[206:209], v[84:87]
	v_mfma_f32_16x16x32_bf16 v[80:83], v[154:157], v[206:209], v[80:83]
	v_mfma_f32_16x16x32_bf16 v[124:127], v[150:153], v[186:189], v[124:127]
	v_mfma_f32_16x16x32_bf16 v[120:123], v[158:161], v[186:189], v[120:123]
	v_mfma_f32_16x16x32_bf16 v[116:119], v[150:153], v[194:197], v[116:119]
	v_mfma_f32_16x16x32_bf16 v[112:115], v[158:161], v[194:197], v[112:115]
	v_mfma_f32_16x16x32_bf16 v[100:103], v[150:153], v[202:205], v[100:103]
	v_mfma_f32_16x16x32_bf16 v[96:99], v[158:161], v[202:205], v[96:99]
	v_mfma_f32_16x16x32_bf16 v[84:87], v[150:153], v[210:213], v[84:87]
	v_mfma_f32_16x16x32_bf16 v[80:83], v[158:161], v[210:213], v[80:83]
	v_mfma_f32_16x16x32_bf16 v[108:111], v[166:169], v[182:185], v[108:111]
	v_mfma_f32_16x16x32_bf16 v[104:107], v[174:177], v[182:185], v[104:107]
	v_mfma_f32_16x16x32_bf16 v[92:95], v[166:169], v[190:193], v[92:95]
	v_mfma_f32_16x16x32_bf16 v[88:91], v[174:177], v[190:193], v[88:91]
	v_mfma_f32_16x16x32_bf16 v[76:79], v[166:169], v[198:201], v[76:79]
	v_mfma_f32_16x16x32_bf16 v[72:75], v[174:177], v[198:201], v[72:75]
	v_mfma_f32_16x16x32_bf16 v[68:71], v[166:169], v[206:209], v[68:71]
	v_mfma_f32_16x16x32_bf16 v[64:67], v[174:177], v[206:209], v[64:67]
	v_mfma_f32_16x16x32_bf16 v[108:111], v[170:173], v[186:189], v[108:111]
	v_mfma_f32_16x16x32_bf16 v[104:107], v[178:181], v[186:189], v[104:107]
	v_mfma_f32_16x16x32_bf16 v[92:95], v[170:173], v[194:197], v[92:95]
	v_mfma_f32_16x16x32_bf16 v[88:91], v[178:181], v[194:197], v[88:91]
	v_mfma_f32_16x16x32_bf16 v[76:79], v[170:173], v[202:205], v[76:79]
	v_mfma_f32_16x16x32_bf16 v[72:75], v[178:181], v[202:205], v[72:75]
	v_mfma_f32_16x16x32_bf16 v[68:71], v[170:173], v[210:213], v[68:71]
	v_mfma_f32_16x16x32_bf16 v[64:67], v[178:181], v[210:213], v[64:67]
	s_barrier
; #define PG8_STAGE(bufoff, gbase, voff) do { _Pragma("unroll") for (int _i = 0; _i < 2; ++_i) \
;         __builtin_amdgcn_global_load_lds((const unsigned*)((const char*)(gbase) + (voff)[_i]), (PG8_LAS unsigned*)(lds + (bufoff) + ldsw + _i * 8192), 16, 0, 0); } while (0)
; #define PG8_LDA(dst, b, h) do { _Pragma("unroll") for (int m = 0; m < 4; ++m) _Pragma("unroll") for (int k = 0; k < 2; ++k) dst[m][k] = *(const PG8_LAS bf16x8*)(lds + PG8_SA(b, h) + aoff + m * 2048 + k * 1024); } while (0)
; #define PG8_MMA(ai, bj, At, Bt) do { __builtin_amdgcn_s_setprio(1); _Pragma("unroll") for (int m = 0; m < 4; ++m) _Pragma("unroll") for (int n = 0; n < 2; ++n) _Pragma("unroll") for (int k = 0; k < 2; ++k) \
;         acc[ai][bj][m][n] = __builtin_amdgcn_mfma_f32_16x16x32_bf16(Bt[n][k], At[m][k], acc[ai][bj][m][n], 0, 0, 0); __builtin_amdgcn_s_setprio(0); } while (0)
; #define PG8_WAIT_V(n) asm volatile("s_waitcnt vmcnt(" #n ")" ::: "memory")
; #define PG8_WAIT_L(n) asm volatile("s_waitcnt lgkmcnt(" #n ")" ::: "memory")
; #define PG8_BAR __builtin_amdgcn_s_barrier()
; #define PG8_SCHED __builtin_amdgcn_sched_barrier(0)
; template <class Epi, class Sched, bool ALIGN_EPI = false, bool SP2 = false>
; __device__ __forceinline__ void gemm_phase(PG8_LAS unsigned char* lds, const Gemm g, const Sched& S, const Epi& E) {
;     ...
;             PG8_LDA(At, 1, 1); PG8_STAGE(PG8_SB(1, 0), b3, voffB); PG8_STAGE(PG8_SB(1, 1), b3 + hstepB, voffB); PG8_STAGE(PG8_SA(1, 0), a3, voffA);
;             PG8_WAIT_V(8); PG8_WAIT_L(0); PG8_BAR; PG8_MMA(1, 0, At, B0); PG8_MMA(1, 1, At, B1); PG8_BAR; PG8_SCHED;
;     ...
;         if constexpr (ALIGN_EPI) { if (wr == 0) PG8_BAR; }
	s_setprio 1
	s_mov_b32 m0, s49
	ds_read_b128 v[182:185], v145 offset:49152
	ds_read_b128 v[186:189], v145 offset:50176
	ds_read_b128 v[190:193], v145 offset:51200
	ds_read_b128 v[194:197], v145 offset:52224
	ds_read_b128 v[198:201], v145 offset:53248
	ds_read_b128 v[202:205], v145 offset:54272
	ds_read_b128 v[206:209], v145 offset:55296
	ds_read_b128 v[210:213], v145 offset:56320
	global_load_lds_dwordx4 v130, s[98:99]
	s_mov_b32 m0, s45
	s_nop 0
	global_load_lds_dwordx4 v134, s[98:99]
	s_mov_b32 m0, s47
	s_nop 0
	global_load_lds_dwordx4 v130, s[56:57]
	s_mov_b32 m0, s19
	s_nop 0
	global_load_lds_dwordx4 v134, s[56:57]
	s_mov_b32 m0, s35
	s_nop 0
	global_load_lds_dwordx4 v128, s[100:101]
	s_mov_b32 m0, s70
	s_nop 0
	global_load_lds_dwordx4 v132, s[100:101]
	s_waitcnt vmcnt(8)
	s_waitcnt lgkmcnt(0)
	s_setprio 0
	s_barrier
	v_mfma_f32_16x16x32_bf16 v[60:63], v[146:149], v[182:185], v[60:63]
	v_mfma_f32_16x16x32_bf16 v[56:59], v[154:157], v[182:185], v[56:59]
	v_mfma_f32_16x16x32_bf16 v[52:55], v[146:149], v[190:193], v[52:55]
	v_mfma_f32_16x16x32_bf16 v[48:51], v[154:157], v[190:193], v[48:51]
	v_mfma_f32_16x16x32_bf16 v[36:39], v[146:149], v[198:201], v[36:39]
	v_mfma_f32_16x16x32_bf16 v[32:35], v[154:157], v[198:201], v[32:35]
	v_mfma_f32_16x16x32_bf16 v[20:23], v[146:149], v[206:209], v[20:23]
	v_mfma_f32_16x16x32_bf16 v[16:19], v[154:157], v[206:209], v[16:19]
	v_mfma_f32_16x16x32_bf16 v[60:63], v[150:153], v[186:189], v[60:63]
	v_mfma_f32_16x16x32_bf16 v[56:59], v[158:161], v[186:189], v[56:59]
	v_mfma_f32_16x16x32_bf16 v[52:55], v[150:153], v[194:197], v[52:55]
	v_mfma_f32_16x16x32_bf16 v[48:51], v[158:161], v[194:197], v[48:51]
	v_mfma_f32_16x16x32_bf16 v[36:39], v[150:153], v[202:205], v[36:39]
	v_mfma_f32_16x16x32_bf16 v[32:35], v[158:161], v[202:205], v[32:35]
	v_mfma_f32_16x16x32_bf16 v[20:23], v[150:153], v[210:213], v[20:23]
	v_mfma_f32_16x16x32_bf16 v[16:19], v[158:161], v[210:213], v[16:19]
	v_mfma_f32_16x16x32_bf16 v[44:47], v[166:169], v[182:185], v[44:47]
	v_mfma_f32_16x16x32_bf16 v[40:43], v[174:177], v[182:185], v[40:43]
	v_mfma_f32_16x16x32_bf16 v[28:31], v[166:169], v[190:193], v[28:31]
	v_mfma_f32_16x16x32_bf16 v[24:27], v[174:177], v[190:193], v[24:27]
	v_mfma_f32_16x16x32_bf16 v[12:15], v[166:169], v[198:201], v[12:15]
	v_mfma_f32_16x16x32_bf16 v[8:11], v[174:177], v[198:201], v[8:11]
	v_mfma_f32_16x16x32_bf16 v[4:7], v[166:169], v[206:209], v[4:7]
	v_mfma_f32_16x16x32_bf16 v[0:3], v[174:177], v[206:209], v[0:3]
	v_mfma_f32_16x16x32_bf16 v[44:47], v[170:173], v[186:189], v[44:47]
	v_mfma_f32_16x16x32_bf16 v[40:43], v[178:181], v[186:189], v[40:43]
	v_mfma_f32_16x16x32_bf16 v[28:31], v[170:173], v[194:197], v[28:31]
	v_mfma_f32_16x16x32_bf16 v[24:27], v[178:181], v[194:197], v[24:27]
	v_mfma_f32_16x16x32_bf16 v[12:15], v[170:173], v[202:205], v[12:15]
	v_mfma_f32_16x16x32_bf16 v[8:11], v[178:181], v[202:205], v[8:11]
	v_mfma_f32_16x16x32_bf16 v[4:7], v[170:173], v[210:213], v[4:7]
	v_mfma_f32_16x16x32_bf16 v[0:3], v[178:181], v[210:213], v[0:3]
	s_barrier
	s_setprio 1
	s_movk_i32 s19, 0x100
	s_andn2_b64 vcc, exec, s[54:55]
	s_mov_b64 s[56:57], -1
	s_mov_b64 s[54:55], 0
	s_cbranch_vccz .LBB0_947
	s_and_b64 vcc, exec, s[40:41]
	s_cbranch_vccz .LBB0_950
	s_barrier

; #define PG8_STAGE(bufoff, gbase, voff) do { _Pragma("unroll") for (int _i = 0; _i < 2; ++_i) \
;         __builtin_amdgcn_global_load_lds((const unsigned*)((const char*)(gbase) + (voff)[_i]), (PG8_LAS unsigned*)(lds + (bufoff) + ldsw + _i * 8192), 16, 0, 0); } while (0)
; #define PG8_LDA(dst, b, h) do { _Pragma("unroll") for (int m = 0; m < 4; ++m) _Pragma("unroll") for (int k = 0; k < 2; ++k) dst[m][k] = *(const PG8_LAS bf16x8*)(lds + PG8_SA(b, h) + aoff + m * 2048 + k * 1024); } while (0)
; #define PG8_LDB(dst, b, h) do { _Pragma("unroll") for (int n = 0; n < 2; ++n) _Pragma("unroll") for (int k = 0; k < 2; ++k) dst[n][k] = *(const PG8_LAS bf16x8*)(lds + PG8_SB(b, h) + boff + n * 2048 + k * 1024); } while (0)
; #define PG8_MMA(ai, bj, At, Bt) do { __builtin_amdgcn_s_setprio(1); _Pragma("unroll") for (int m = 0; m < 4; ++m) _Pragma("unroll") for (int n = 0; n < 2; ++n) _Pragma("unroll") for (int k = 0; k < 2; ++k) \
;         acc[ai][bj][m][n] = __builtin_amdgcn_mfma_f32_16x16x32_bf16(Bt[n][k], At[m][k], acc[ai][bj][m][n], 0, 0, 0); __builtin_amdgcn_s_setprio(0); } while (0)
; #define PG8_WAIT_V(n) asm volatile("s_waitcnt vmcnt(" #n ")" ::: "memory")
; #define PG8_WAIT_L(n) asm volatile("s_waitcnt lgkmcnt(" #n ")" ::: "memory")
; template <class Epi, class Sched, bool ALIGN_EPI = false, bool SP2 = false>
; __device__ __forceinline__ void gemm_phase(PG8_LAS unsigned char* lds, const Gemm g, const Sched& S, const Epi& E) {
;     ...
;             const bool last = (t == nt - 2);
;             const char* a1 = cA + (size_t)(t + 1) * kstep;
;             const char* a2 = last ? nA : cA + (size_t)(t + 2) * kstep; const char* b2 = last ? nB : cB + (size_t)(t + 2) * kstep;
;             const char* a3 = a2 + kstep; const char* b3 = b2 + kstep;
;             if (last && has_next) S.a_ready(nxt);
;             if constexpr (SP2) {
;             PG8_LDB(B0, 0, 0); PG8_LDB(B1, 0, 1); PG8_SCHED; PG8_LDA(At, 0, 0); PG8_STAGE(PG8_SA(1, 1), a1 + hstepA, voffA);
;             PG8_WAIT_V(8); PG8_WAIT_L(0); PG8_BAR; PG8_MMA(0, 0, At, B0); PG8_MMA(0, 1, At, B1); PG8_BAR; PG8_SCHED;
;             PG8_LDA(At, 0, 1); PG8_STAGE(PG8_SB(0, 0), b2, voffB); PG8_STAGE(PG8_SB(0, 1), b2 + hstepB, voffB); PG8_STAGE(PG8_SA(0, 0), a2, voffA);
;             PG8_WAIT_V(8); PG8_WAIT_L(0); PG8_BAR; PG8_MMA(1, 0, At, B0); PG8_MMA(1, 1, At, B1); PG8_BAR; PG8_SCHED;
.LBB0_1082:
	ds_read_b128 v[150:153], v147
	ds_read_b128 v[154:157], v147 offset:1024
	ds_read_b128 v[158:161], v147 offset:2048
	ds_read_b128 v[166:169], v147 offset:3072
	ds_read_b128 v[170:173], v148
	ds_read_b128 v[174:177], v148 offset:1024
	ds_read_b128 v[178:181], v148 offset:2048
	ds_read_b128 v[182:185], v148 offset:3072
	s_add_u32 s50, s48, 0xfff80080
	s_addc_u32 s51, s49, -1
	s_cmp_eq_u32 s66, 28
	s_cselect_b32 s53, s41, s51
	s_cselect_b32 s52, s62, s50
	s_cselect_b32 s51, s39, s65
	s_cselect_b32 s50, s63, s64
	s_add_i32 m0, s30, 0xc000
	ds_read_b128 v[186:189], v149
	ds_read_b128 v[190:193], v149 offset:1024
	ds_read_b128 v[194:197], v149 offset:2048
	ds_read_b128 v[198:201], v149 offset:3072
	ds_read_b128 v[202:205], v149 offset:4096
	ds_read_b128 v[206:209], v149 offset:5120
	ds_read_b128 v[210:213], v149 offset:6144
	ds_read_b128 v[214:217], v149 offset:7168
	global_load_lds_dwordx4 v136, s[48:49]
	s_add_i32 m0, s30, 0xe000
	s_nop 0
	global_load_lds_dwordx4 v138, s[48:49]
	s_waitcnt vmcnt(8)
	s_waitcnt lgkmcnt(0)
	s_setprio 0
	s_barrier
	v_mfma_f32_16x16x32_bf16 v[124:127], v[150:153], v[186:189], v[124:127]
	v_mfma_f32_16x16x32_bf16 v[120:123], v[158:161], v[186:189], v[120:123]
	v_mfma_f32_16x16x32_bf16 v[112:115], v[150:153], v[194:197], v[112:115]
	v_mfma_f32_16x16x32_bf16 v[104:107], v[158:161], v[194:197], v[104:107]
	v_mfma_f32_16x16x32_bf16 v[96:99], v[150:153], v[202:205], v[96:99]
	v_mfma_f32_16x16x32_bf16 v[88:91], v[158:161], v[202:205], v[88:91]
	v_mfma_f32_16x16x32_bf16 v[80:83], v[150:153], v[210:213], v[80:83]
	v_mfma_f32_16x16x32_bf16 v[72:75], v[158:161], v[210:213], v[72:75]
	v_mfma_f32_16x16x32_bf16 v[124:127], v[154:157], v[190:193], v[124:127]
	v_mfma_f32_16x16x32_bf16 v[120:123], v[166:169], v[190:193], v[120:123]
	v_mfma_f32_16x16x32_bf16 v[112:115], v[154:157], v[198:201], v[112:115]
	v_mfma_f32_16x16x32_bf16 v[104:107], v[166:169], v[198:201], v[104:107]
	v_mfma_f32_16x16x32_bf16 v[96:99], v[154:157], v[206:209], v[96:99]
	v_mfma_f32_16x16x32_bf16 v[88:91], v[166:169], v[206:209], v[88:91]
	v_mfma_f32_16x16x32_bf16 v[80:83], v[154:157], v[214:217], v[80:83]
	v_mfma_f32_16x16x32_bf16 v[72:75], v[166:169], v[214:217], v[72:75]
	v_mfma_f32_16x16x32_bf16 v[116:119], v[170:173], v[186:189], v[116:119]
	v_mfma_f32_16x16x32_bf16 v[108:111], v[178:181], v[186:189], v[108:111]
	v_mfma_f32_16x16x32_bf16 v[100:103], v[170:173], v[194:197], v[100:103]
	v_mfma_f32_16x16x32_bf16 v[92:95], v[178:181], v[194:197], v[92:95]
	v_mfma_f32_16x16x32_bf16 v[84:87], v[170:173], v[202:205], v[84:87]
	v_mfma_f32_16x16x32_bf16 v[76:79], v[178:181], v[202:205], v[76:79]
	v_mfma_f32_16x16x32_bf16 v[68:71], v[170:173], v[210:213], v[68:71]
	v_mfma_f32_16x16x32_bf16 v[64:67], v[178:181], v[210:213], v[64:67]
	v_mfma_f32_16x16x32_bf16 v[116:119], v[174:177], v[190:193], v[116:119]
	v_mfma_f32_16x16x32_bf16 v[108:111], v[182:185], v[190:193], v[108:111]
	v_mfma_f32_16x16x32_bf16 v[100:103], v[174:177], v[198:201], v[100:103]
	v_mfma_f32_16x16x32_bf16 v[92:95], v[182:185], v[198:201], v[92:95]
	v_mfma_f32_16x16x32_bf16 v[84:87], v[174:177], v[206:209], v[84:87]
	v_mfma_f32_16x16x32_bf16 v[76:79], v[182:185], v[206:209], v[76:79]
	v_mfma_f32_16x16x32_bf16 v[68:71], v[174:177], v[214:217], v[68:71]
	v_mfma_f32_16x16x32_bf16 v[64:67], v[182:185], v[214:217], v[64:67]
	s_barrier
	s_setprio 1
	s_add_u32 s98, s50, s10
	s_addc_u32 s99, s51, s11
	s_add_u32 s100, s52, s10
	s_addc_u32 s101, s53, s11
	s_add_i32 s67, s55, s28
	s_mov_b32 m0, s67
	ds_read_b128 v[186:189], v149 offset:16384
	ds_read_b128 v[190:193], v149 offset:17408
	ds_read_b128 v[194:197], v149 offset:18432
	ds_read_b128 v[198:201], v149 offset:19456
	ds_read_b128 v[202:205], v149 offset:20480
	ds_read_b128 v[206:209], v149 offset:21504
	ds_read_b128 v[210:213], v149 offset:22528
	ds_read_b128 v[214:217], v149 offset:23552
	global_load_lds_dwordx4 v132, s[50:51]
	s_add_i32 m0, s67, 0x2000
	s_add_u32 s68, s50, 0x80000
	s_addc_u32 s69, s51, 0
	s_add_i32 s67, s56, s28
	global_load_lds_dwordx4 v128, s[50:51]
	s_mov_b32 m0, s67
	s_nop 0
	global_load_lds_dwordx4 v132, s[68:69]
	s_add_i32 m0, s67, 0x2000
	s_nop 0
	global_load_lds_dwordx4 v128, s[68:69]
	s_mov_b32 m0, s30
	s_nop 0
	global_load_lds_dwordx4 v134, s[52:53]
	s_mov_b32 m0, s31
	s_nop 0
	global_load_lds_dwordx4 v130, s[52:53]
	s_waitcnt vmcnt(8)
	s_waitcnt lgkmcnt(0)
	s_setprio 0
	s_barrier
	v_mfma_f32_16x16x32_bf16 v[60:63], v[150:153], v[186:189], v[60:63]
	v_mfma_f32_16x16x32_bf16 v[56:59], v[158:161], v[186:189], v[56:59]
	v_mfma_f32_16x16x32_bf16 v[48:51], v[150:153], v[194:197], v[48:51]
	v_mfma_f32_16x16x32_bf16 v[40:43], v[158:161], v[194:197], v[40:43]
	v_mfma_f32_16x16x32_bf16 v[32:35], v[150:153], v[202:205], v[32:35]
	v_mfma_f32_16x16x32_bf16 v[24:27], v[158:161], v[202:205], v[24:27]
	v_mfma_f32_16x16x32_bf16 v[16:19], v[150:153], v[210:213], v[16:19]
	v_mfma_f32_16x16x32_bf16 v[8:11], v[158:161], v[210:213], v[8:11]
	v_mfma_f32_16x16x32_bf16 v[60:63], v[154:157], v[190:193], v[60:63]
	v_mfma_f32_16x16x32_bf16 v[56:59], v[166:169], v[190:193], v[56:59]
	v_mfma_f32_16x16x32_bf16 v[48:51], v[154:157], v[198:201], v[48:51]
	v_mfma_f32_16x16x32_bf16 v[40:43], v[166:169], v[198:201], v[40:43]
	v_mfma_f32_16x16x32_bf16 v[32:35], v[154:157], v[206:209], v[32:35]
	v_mfma_f32_16x16x32_bf16 v[24:27], v[166:169], v[206:209], v[24:27]
	v_mfma_f32_16x16x32_bf16 v[16:19], v[154:157], v[214:217], v[16:19]
	v_mfma_f32_16x16x32_bf16 v[8:11], v[166:169], v[214:217], v[8:11]
	v_mfma_f32_16x16x32_bf16 v[52:55], v[170:173], v[186:189], v[52:55]
	v_mfma_f32_16x16x32_bf16 v[44:47], v[178:181], v[186:189], v[44:47]
	v_mfma_f32_16x16x32_bf16 v[36:39], v[170:173], v[194:197], v[36:39]
	v_mfma_f32_16x16x32_bf16 v[28:31], v[178:181], v[194:197], v[28:31]
	v_mfma_f32_16x16x32_bf16 v[20:23], v[170:173], v[202:205], v[20:23]
	v_mfma_f32_16x16x32_bf16 v[12:15], v[178:181], v[202:205], v[12:15]
	v_mfma_f32_16x16x32_bf16 v[4:7], v[170:173], v[210:213], v[4:7]
	v_mfma_f32_16x16x32_bf16 v[0:3], v[178:181], v[210:213], v[0:3]
	v_mfma_f32_16x16x32_bf16 v[52:55], v[174:177], v[190:193], v[52:55]
	v_mfma_f32_16x16x32_bf16 v[44:47], v[182:185], v[190:193], v[44:47]
	v_mfma_f32_16x16x32_bf16 v[36:39], v[174:177], v[198:201], v[36:39]
	v_mfma_f32_16x16x32_bf16 v[28:31], v[182:185], v[198:201], v[28:31]
	v_mfma_f32_16x16x32_bf16 v[20:23], v[174:177], v[206:209], v[20:23]
	v_mfma_f32_16x16x32_bf16 v[12:15], v[182:185], v[206:209], v[12:15]
	v_mfma_f32_16x16x32_bf16 v[4:7], v[174:177], v[214:217], v[4:7]
	v_mfma_f32_16x16x32_bf16 v[0:3], v[182:185], v[214:217], v[0:3]
	s_barrier
; #define PG8_STAGE(bufoff, gbase, voff) do { _Pragma("unroll") for (int _i = 0; _i < 2; ++_i) \
;         __builtin_amdgcn_global_load_lds((const unsigned*)((const char*)(gbase) + (voff)[_i]), (PG8_LAS unsigned*)(lds + (bufoff) + ldsw + _i * 8192), 16, 0, 0); } while (0)
; #define PG8_LDA(dst, b, h) do { _Pragma("unroll") for (int m = 0; m < 4; ++m) _Pragma("unroll") for (int k = 0; k < 2; ++k) dst[m][k] = *(const PG8_LAS bf16x8*)(lds + PG8_SA(b, h) + aoff + m * 2048 + k * 1024); } while (0)
; #define PG8_LDB(dst, b, h) do { _Pragma("unroll") for (int n = 0; n < 2; ++n) _Pragma("unroll") for (int k = 0; k < 2; ++k) dst[n][k] = *(const PG8_LAS bf16x8*)(lds + PG8_SB(b, h) + boff + n * 2048 + k * 1024); } while (0)
; #define PG8_MMA(ai, bj, At, Bt) do { __builtin_amdgcn_s_setprio(1); _Pragma("unroll") for (int m = 0; m < 4; ++m) _Pragma("unroll") for (int n = 0; n < 2; ++n) _Pragma("unroll") for (int k = 0; k < 2; ++k) \
;         acc[ai][bj][m][n] = __builtin_amdgcn_mfma_f32_16x16x32_bf16(Bt[n][k], At[m][k], acc[ai][bj][m][n], 0, 0, 0); __builtin_amdgcn_s_setprio(0); } while (0)
; #define PG8_WAIT_V(n) asm volatile("s_waitcnt vmcnt(" #n ")" ::: "memory")
; #define PG8_WAIT_L(n) asm volatile("s_waitcnt lgkmcnt(" #n ")" ::: "memory")
; #define PG8_BAR __builtin_amdgcn_s_barrier()
; #define PG8_SCHED __builtin_amdgcn_sched_barrier(0)
; template <class Epi, class Sched, bool ALIGN_EPI = false, bool SP2 = false>
; __device__ __forceinline__ void gemm_phase(PG8_LAS unsigned char* lds, const Gemm g, const Sched& S, const Epi& E) {
;     ...
;             PG8_LDB(B0, 1, 0); PG8_LDB(B1, 1, 1); PG8_SCHED; PG8_LDA(At, 1, 0); PG8_STAGE(PG8_SA(0, 1), a2 + hstepA, voffA);
;             PG8_WAIT_V(8); PG8_WAIT_L(0); PG8_BAR; PG8_MMA(0, 0, At, B0); PG8_MMA(0, 1, At, B1); PG8_BAR; PG8_SCHED;
;             PG8_LDA(At, 1, 1); PG8_STAGE(PG8_SB(1, 0), b3, voffB); PG8_STAGE(PG8_SB(1, 1), b3 + hstepB, voffB); PG8_STAGE(PG8_SA(1, 0), a3, voffA);
;             PG8_WAIT_V(8); PG8_WAIT_L(0); PG8_BAR; PG8_MMA(1, 0, At, B0); PG8_MMA(1, 1, At, B1); PG8_BAR; PG8_SCHED;
	s_setprio 1
	s_add_i32 s67, 0, 0x18000
	v_add_u32_e32 v163, s67, v145
	s_add_i32 s68, 0, 0x1c000
	ds_read_b128 v[150:153], v163
	ds_read_b128 v[154:157], v163 offset:1024
	ds_read_b128 v[158:161], v163 offset:2048
	ds_read_b128 v[166:169], v163 offset:3072
	v_add_u32_e32 v163, s68, v145
	ds_read_b128 v[170:173], v163
	ds_read_b128 v[174:177], v163 offset:1024
	ds_read_b128 v[178:181], v163 offset:2048
	ds_read_b128 v[182:185], v163 offset:3072
	s_add_u32 s52, s52, 0x80000
	s_addc_u32 s53, s53, 0
	s_mov_b32 m0, s33
	ds_read_b128 v[186:189], v149 offset:32768
	ds_read_b128 v[190:193], v149 offset:33792
	ds_read_b128 v[194:197], v149 offset:34816
	ds_read_b128 v[198:201], v149 offset:35840
	ds_read_b128 v[202:205], v149 offset:36864
	ds_read_b128 v[206:209], v149 offset:37888
	ds_read_b128 v[210:213], v149 offset:38912
	ds_read_b128 v[214:217], v149 offset:39936
	global_load_lds_dwordx4 v134, s[52:53]
	s_mov_b32 m0, s34
	s_nop 0
	global_load_lds_dwordx4 v130, s[52:53]
	s_waitcnt vmcnt(8)
	s_waitcnt lgkmcnt(0)
	s_setprio 0
	s_barrier
	v_mfma_f32_16x16x32_bf16 v[124:127], v[150:153], v[186:189], v[124:127]
	v_mfma_f32_16x16x32_bf16 v[120:123], v[158:161], v[186:189], v[120:123]
	v_mfma_f32_16x16x32_bf16 v[112:115], v[150:153], v[194:197], v[112:115]
	v_mfma_f32_16x16x32_bf16 v[104:107], v[158:161], v[194:197], v[104:107]
	v_mfma_f32_16x16x32_bf16 v[96:99], v[150:153], v[202:205], v[96:99]
	v_mfma_f32_16x16x32_bf16 v[88:91], v[158:161], v[202:205], v[88:91]
	v_mfma_f32_16x16x32_bf16 v[80:83], v[150:153], v[210:213], v[80:83]
	v_mfma_f32_16x16x32_bf16 v[72:75], v[158:161], v[210:213], v[72:75]
	v_mfma_f32_16x16x32_bf16 v[124:127], v[154:157], v[190:193], v[124:127]
	v_mfma_f32_16x16x32_bf16 v[120:123], v[166:169], v[190:193], v[120:123]
	v_mfma_f32_16x16x32_bf16 v[112:115], v[154:157], v[198:201], v[112:115]
	v_mfma_f32_16x16x32_bf16 v[104:107], v[166:169], v[198:201], v[104:107]
	v_mfma_f32_16x16x32_bf16 v[96:99], v[154:157], v[206:209], v[96:99]
	v_mfma_f32_16x16x32_bf16 v[88:91], v[166:169], v[206:209], v[88:91]
	v_mfma_f32_16x16x32_bf16 v[80:83], v[154:157], v[214:217], v[80:83]
	v_mfma_f32_16x16x32_bf16 v[72:75], v[166:169], v[214:217], v[72:75]
	v_mfma_f32_16x16x32_bf16 v[116:119], v[170:173], v[186:189], v[116:119]
	v_mfma_f32_16x16x32_bf16 v[108:111], v[178:181], v[186:189], v[108:111]
	v_mfma_f32_16x16x32_bf16 v[100:103], v[170:173], v[194:197], v[100:103]
	v_mfma_f32_16x16x32_bf16 v[92:95], v[178:181], v[194:197], v[92:95]
	v_mfma_f32_16x16x32_bf16 v[84:87], v[170:173], v[202:205], v[84:87]
	v_mfma_f32_16x16x32_bf16 v[76:79], v[178:181], v[202:205], v[76:79]
	v_mfma_f32_16x16x32_bf16 v[68:71], v[170:173], v[210:213], v[68:71]
	v_mfma_f32_16x16x32_bf16 v[64:67], v[178:181], v[210:213], v[64:67]
	v_mfma_f32_16x16x32_bf16 v[116:119], v[174:177], v[190:193], v[116:119]
	v_mfma_f32_16x16x32_bf16 v[108:111], v[182:185], v[190:193], v[108:111]
	v_mfma_f32_16x16x32_bf16 v[100:103], v[174:177], v[198:201], v[100:103]
	v_mfma_f32_16x16x32_bf16 v[92:95], v[182:185], v[198:201], v[92:95]
	v_mfma_f32_16x16x32_bf16 v[84:87], v[174:177], v[206:209], v[84:87]
	v_mfma_f32_16x16x32_bf16 v[76:79], v[182:185], v[206:209], v[76:79]
	v_mfma_f32_16x16x32_bf16 v[68:71], v[174:177], v[214:217], v[68:71]
	v_mfma_f32_16x16x32_bf16 v[64:67], v[182:185], v[214:217], v[64:67]
	s_barrier
	s_setprio 1
	s_add_i32 s52, s67, s28
	s_mov_b32 m0, s52
	ds_read_b128 v[186:189], v149 offset:49152
	ds_read_b128 v[190:193], v149 offset:50176
	ds_read_b128 v[194:197], v149 offset:51200
	ds_read_b128 v[198:201], v149 offset:52224
	ds_read_b128 v[202:205], v149 offset:53248
	ds_read_b128 v[206:209], v149 offset:54272
	ds_read_b128 v[210:213], v149 offset:55296
	ds_read_b128 v[214:217], v149 offset:56320
	global_load_lds_dwordx4 v132, s[98:99]
	s_add_i32 m0, s52, 0x2000
	s_add_u32 s50, s50, 0x80080
	s_addc_u32 s51, s51, 0
	s_add_i32 s52, s68, s28
	global_load_lds_dwordx4 v128, s[98:99]
	s_mov_b32 m0, s52
	s_nop 0
	global_load_lds_dwordx4 v132, s[50:51]
	s_add_i32 m0, s52, 0x2000
	s_nop 0
	global_load_lds_dwordx4 v128, s[50:51]
	s_mov_b32 m0, s47
	s_nop 0
	global_load_lds_dwordx4 v134, s[100:101]
	s_mov_b32 m0, s54
	s_nop 0
	global_load_lds_dwordx4 v130, s[100:101]
	s_waitcnt vmcnt(8)
	s_waitcnt lgkmcnt(0)
	s_setprio 0
	s_barrier
	v_mfma_f32_16x16x32_bf16 v[60:63], v[150:153], v[186:189], v[60:63]
	v_mfma_f32_16x16x32_bf16 v[56:59], v[158:161], v[186:189], v[56:59]
	v_mfma_f32_16x16x32_bf16 v[48:51], v[150:153], v[194:197], v[48:51]
	v_mfma_f32_16x16x32_bf16 v[40:43], v[158:161], v[194:197], v[40:43]
	v_mfma_f32_16x16x32_bf16 v[32:35], v[150:153], v[202:205], v[32:35]
	v_mfma_f32_16x16x32_bf16 v[24:27], v[158:161], v[202:205], v[24:27]
	v_mfma_f32_16x16x32_bf16 v[16:19], v[150:153], v[210:213], v[16:19]
	v_mfma_f32_16x16x32_bf16 v[8:11], v[158:161], v[210:213], v[8:11]
	v_mfma_f32_16x16x32_bf16 v[60:63], v[154:157], v[190:193], v[60:63]
	v_mfma_f32_16x16x32_bf16 v[56:59], v[166:169], v[190:193], v[56:59]
	v_mfma_f32_16x16x32_bf16 v[48:51], v[154:157], v[198:201], v[48:51]
	v_mfma_f32_16x16x32_bf16 v[40:43], v[166:169], v[198:201], v[40:43]
	v_mfma_f32_16x16x32_bf16 v[32:35], v[154:157], v[206:209], v[32:35]
	v_mfma_f32_16x16x32_bf16 v[24:27], v[166:169], v[206:209], v[24:27]
	v_mfma_f32_16x16x32_bf16 v[16:19], v[154:157], v[214:217], v[16:19]
	v_mfma_f32_16x16x32_bf16 v[8:11], v[166:169], v[214:217], v[8:11]
	v_mfma_f32_16x16x32_bf16 v[52:55], v[170:173], v[186:189], v[52:55]
	v_mfma_f32_16x16x32_bf16 v[44:47], v[178:181], v[186:189], v[44:47]
	v_mfma_f32_16x16x32_bf16 v[36:39], v[170:173], v[194:197], v[36:39]
	v_mfma_f32_16x16x32_bf16 v[28:31], v[178:181], v[194:197], v[28:31]
	v_mfma_f32_16x16x32_bf16 v[20:23], v[170:173], v[202:205], v[20:23]
	v_mfma_f32_16x16x32_bf16 v[12:15], v[178:181], v[202:205], v[12:15]
	v_mfma_f32_16x16x32_bf16 v[4:7], v[170:173], v[210:213], v[4:7]
	v_mfma_f32_16x16x32_bf16 v[0:3], v[178:181], v[210:213], v[0:3]
	v_mfma_f32_16x16x32_bf16 v[52:55], v[174:177], v[190:193], v[52:55]
	v_mfma_f32_16x16x32_bf16 v[44:47], v[182:185], v[190:193], v[44:47]
	v_mfma_f32_16x16x32_bf16 v[36:39], v[174:177], v[198:201], v[36:39]
	v_mfma_f32_16x16x32_bf16 v[28:31], v[182:185], v[198:201], v[28:31]
	v_mfma_f32_16x16x32_bf16 v[20:23], v[174:177], v[206:209], v[20:23]
	v_mfma_f32_16x16x32_bf16 v[12:15], v[182:185], v[206:209], v[12:15]
	v_mfma_f32_16x16x32_bf16 v[4:7], v[174:177], v[214:217], v[4:7]
	v_mfma_f32_16x16x32_bf16 v[0:3], v[182:185], v[214:217], v[0:3]
	s_barrier
	s_setprio 1
	s_add_i32 s66, s66, 2
	s_add_u32 s48, s48, 0x100
	s_addc_u32 s49, s49, 0
	s_add_u32 s64, s64, 0x100
	s_addc_u32 s65, s65, 0
	s_cmp_gt_u32 s66, 29
	s_cbranch_scc0 .LBB0_1082
	s_and_b64 vcc, exec, s[16:17]
	s_cbranch_vccz .LBB0_1085
	s_barrier

; #define PG8_STAGE(bufoff, gbase, voff) do { _Pragma("unroll") for (int _i = 0; _i < 2; ++_i) \
;         __builtin_amdgcn_global_load_lds((const unsigned*)((const char*)(gbase) + (voff)[_i]), (PG8_LAS unsigned*)(lds + (bufoff) + ldsw + _i * 8192), 16, 0, 0); } while (0)
; #define PG8_LDA(dst, b, h) do { _Pragma("unroll") for (int m = 0; m < 4; ++m) _Pragma("unroll") for (int k = 0; k < 2; ++k) dst[m][k] = *(const PG8_LAS bf16x8*)(lds + PG8_SA(b, h) + aoff + m * 2048 + k * 1024); } while (0)
; #define PG8_LDB(dst, b, h) do { _Pragma("unroll") for (int n = 0; n < 2; ++n) _Pragma("unroll") for (int k = 0; k < 2; ++k) dst[n][k] = *(const PG8_LAS bf16x8*)(lds + PG8_SB(b, h) + boff + n * 2048 + k * 1024); } while (0)
; #define PG8_MMA(ai, bj, At, Bt) do { __builtin_amdgcn_s_setprio(1); _Pragma("unroll") for (int m = 0; m < 4; ++m) _Pragma("unroll") for (int n = 0; n < 2; ++n) _Pragma("unroll") for (int k = 0; k < 2; ++k) \
;         acc[ai][bj][m][n] = __builtin_amdgcn_mfma_f32_16x16x32_bf16(Bt[n][k], At[m][k], acc[ai][bj][m][n], 0, 0, 0); __builtin_amdgcn_s_setprio(0); } while (0)
; #define PG8_WAIT_V(n) asm volatile("s_waitcnt vmcnt(" #n ")" ::: "memory")
; #define PG8_WAIT_L(n) asm volatile("s_waitcnt lgkmcnt(" #n ")" ::: "memory")
; template <class Epi, class Sched, bool ALIGN_EPI = false, bool SP2 = false>
; __device__ __forceinline__ void gemm_phase(PG8_LAS unsigned char* lds, const Gemm g, const Sched& S, const Epi& E) {
;     ...
;             const bool last = (t == nt - 2);
;             const char* a1 = cA + (size_t)(t + 1) * kstep;
;             const char* a2 = last ? nA : cA + (size_t)(t + 2) * kstep; const char* b2 = last ? nB : cB + (size_t)(t + 2) * kstep;
;             const char* a3 = a2 + kstep; const char* b3 = b2 + kstep;
;             if (last && has_next) S.a_ready(nxt);
;             if constexpr (SP2) {
;             PG8_LDB(B0, 0, 0); PG8_LDB(B1, 0, 1); PG8_SCHED; PG8_LDA(At, 0, 0); PG8_STAGE(PG8_SA(1, 1), a1 + hstepA, voffA);
;             PG8_WAIT_V(8); PG8_WAIT_L(0); PG8_BAR; PG8_MMA(0, 0, At, B0); PG8_MMA(0, 1, At, B1); PG8_BAR; PG8_SCHED;
;             PG8_LDA(At, 0, 1); PG8_STAGE(PG8_SB(0, 0), b2, voffB); PG8_STAGE(PG8_SB(0, 1), b2 + hstepB, voffB); PG8_STAGE(PG8_SA(0, 0), a2, voffA);
;             PG8_WAIT_V(8); PG8_WAIT_L(0); PG8_BAR; PG8_MMA(1, 0, At, B0); PG8_MMA(1, 1, At, B1); PG8_BAR; PG8_SCHED;
.LBB0_1161:
	ds_read_b128 v[166:169], v157
	ds_read_b128 v[170:173], v157 offset:1024
	ds_read_b128 v[174:177], v157 offset:2048
	ds_read_b128 v[178:181], v157 offset:3072
	ds_read_b128 v[182:185], v158
	ds_read_b128 v[186:189], v158 offset:1024
	ds_read_b128 v[190:193], v158 offset:2048
	ds_read_b128 v[194:197], v158 offset:3072
	s_add_u32 s50, s48, 0xffe00080
	s_addc_u32 s51, s49, -1
	s_cmpk_eq_i32 s65, 0x7c
	s_cselect_b32 s53, s41, s51
	s_cselect_b32 s52, s61, s50
	s_cselect_b32 s51, s39, s64
	s_cselect_b32 s50, s62, s63
	s_add_i32 m0, s29, 0xc000
	ds_read_b128 v[198:201], v159
	ds_read_b128 v[202:205], v159 offset:1024
	ds_read_b128 v[206:209], v159 offset:2048
	ds_read_b128 v[210:213], v159 offset:3072
	ds_read_b128 v[214:217], v159 offset:4096
	ds_read_b128 v[218:221], v159 offset:5120
	ds_read_b128 v[222:225], v159 offset:6144
	ds_read_b128 v[226:229], v159 offset:7168
	global_load_lds_dwordx4 v136, s[48:49]
	s_add_i32 m0, s29, 0xe000
	s_nop 0
	global_load_lds_dwordx4 v138, s[48:49]
	s_waitcnt vmcnt(8)
	s_waitcnt lgkmcnt(0)
	s_setprio 0
	s_barrier
	v_mfma_f32_16x16x32_bf16 v[124:127], v[166:169], v[198:201], v[124:127]
	v_mfma_f32_16x16x32_bf16 v[120:123], v[174:177], v[198:201], v[120:123]
	v_mfma_f32_16x16x32_bf16 v[116:119], v[166:169], v[206:209], v[116:119]
	v_mfma_f32_16x16x32_bf16 v[108:111], v[174:177], v[206:209], v[108:111]
	v_mfma_f32_16x16x32_bf16 v[100:103], v[166:169], v[214:217], v[100:103]
	v_mfma_f32_16x16x32_bf16 v[92:95], v[174:177], v[214:217], v[92:95]
	v_mfma_f32_16x16x32_bf16 v[80:83], v[166:169], v[222:225], v[80:83]
	v_mfma_f32_16x16x32_bf16 v[72:75], v[174:177], v[222:225], v[72:75]
	v_mfma_f32_16x16x32_bf16 v[124:127], v[170:173], v[202:205], v[124:127]
	v_mfma_f32_16x16x32_bf16 v[120:123], v[178:181], v[202:205], v[120:123]
	v_mfma_f32_16x16x32_bf16 v[116:119], v[170:173], v[210:213], v[116:119]
	v_mfma_f32_16x16x32_bf16 v[108:111], v[178:181], v[210:213], v[108:111]
	v_mfma_f32_16x16x32_bf16 v[100:103], v[170:173], v[218:221], v[100:103]
	v_mfma_f32_16x16x32_bf16 v[92:95], v[178:181], v[218:221], v[92:95]
	v_mfma_f32_16x16x32_bf16 v[80:83], v[170:173], v[226:229], v[80:83]
	v_mfma_f32_16x16x32_bf16 v[72:75], v[178:181], v[226:229], v[72:75]
	v_mfma_f32_16x16x32_bf16 v[112:115], v[182:185], v[198:201], v[112:115]
	v_mfma_f32_16x16x32_bf16 v[104:107], v[190:193], v[198:201], v[104:107]
	v_mfma_f32_16x16x32_bf16 v[96:99], v[182:185], v[206:209], v[96:99]
	v_mfma_f32_16x16x32_bf16 v[88:91], v[190:193], v[206:209], v[88:91]
	v_mfma_f32_16x16x32_bf16 v[84:87], v[182:185], v[214:217], v[84:87]
	v_mfma_f32_16x16x32_bf16 v[76:79], v[190:193], v[214:217], v[76:79]
	v_mfma_f32_16x16x32_bf16 v[68:71], v[182:185], v[222:225], v[68:71]
	v_mfma_f32_16x16x32_bf16 v[64:67], v[190:193], v[222:225], v[64:67]
	v_mfma_f32_16x16x32_bf16 v[112:115], v[186:189], v[202:205], v[112:115]
	v_mfma_f32_16x16x32_bf16 v[104:107], v[194:197], v[202:205], v[104:107]
	v_mfma_f32_16x16x32_bf16 v[96:99], v[186:189], v[210:213], v[96:99]
	v_mfma_f32_16x16x32_bf16 v[88:91], v[194:197], v[210:213], v[88:91]
	v_mfma_f32_16x16x32_bf16 v[84:87], v[186:189], v[218:221], v[84:87]
	v_mfma_f32_16x16x32_bf16 v[76:79], v[194:197], v[218:221], v[76:79]
	v_mfma_f32_16x16x32_bf16 v[68:71], v[186:189], v[226:229], v[68:71]
	v_mfma_f32_16x16x32_bf16 v[64:67], v[194:197], v[226:229], v[64:67]
	s_barrier
	s_setprio 1
	s_add_u32 s98, s50, s10
	s_addc_u32 s99, s51, s11
	s_add_u32 s100, s52, s10
	s_addc_u32 s101, s53, s11
	s_add_i32 s66, s54, s28
	s_mov_b32 m0, s66
	ds_read_b128 v[198:201], v159 offset:16384
	ds_read_b128 v[202:205], v159 offset:17408
	ds_read_b128 v[206:209], v159 offset:18432
	ds_read_b128 v[210:213], v159 offset:19456
	ds_read_b128 v[214:217], v159 offset:20480
	ds_read_b128 v[218:221], v159 offset:21504
	ds_read_b128 v[222:225], v159 offset:22528
	ds_read_b128 v[226:229], v159 offset:23552
	global_load_lds_dwordx4 v130, s[50:51]
	s_add_i32 m0, s66, 0x2000
	s_add_u32 s66, s50, 0x200000
	s_addc_u32 s67, s51, 0
	s_add_i32 s68, s55, s28
	global_load_lds_dwordx4 v134, s[50:51]
	s_mov_b32 m0, s68
	s_nop 0
	global_load_lds_dwordx4 v130, s[66:67]
	s_add_i32 m0, s68, 0x2000
	s_nop 0
	global_load_lds_dwordx4 v134, s[66:67]
	s_mov_b32 m0, s29
	s_nop 0
	global_load_lds_dwordx4 v128, s[52:53]
	s_mov_b32 m0, s30
	s_nop 0
	global_load_lds_dwordx4 v132, s[52:53]
	s_waitcnt vmcnt(8)
	s_waitcnt lgkmcnt(0)
	s_setprio 0
	s_barrier
	v_mfma_f32_16x16x32_bf16 v[60:63], v[166:169], v[198:201], v[60:63]
	v_mfma_f32_16x16x32_bf16 v[56:59], v[174:177], v[198:201], v[56:59]
	v_mfma_f32_16x16x32_bf16 v[52:55], v[166:169], v[206:209], v[52:55]
	v_mfma_f32_16x16x32_bf16 v[44:47], v[174:177], v[206:209], v[44:47]
	v_mfma_f32_16x16x32_bf16 v[36:39], v[166:169], v[214:217], v[36:39]
	v_mfma_f32_16x16x32_bf16 v[28:31], v[174:177], v[214:217], v[28:31]
	v_mfma_f32_16x16x32_bf16 v[20:23], v[166:169], v[222:225], v[20:23]
	v_mfma_f32_16x16x32_bf16 v[12:15], v[174:177], v[222:225], v[12:15]
	v_mfma_f32_16x16x32_bf16 v[60:63], v[170:173], v[202:205], v[60:63]
	v_mfma_f32_16x16x32_bf16 v[56:59], v[178:181], v[202:205], v[56:59]
	v_mfma_f32_16x16x32_bf16 v[52:55], v[170:173], v[210:213], v[52:55]
	v_mfma_f32_16x16x32_bf16 v[44:47], v[178:181], v[210:213], v[44:47]
	v_mfma_f32_16x16x32_bf16 v[36:39], v[170:173], v[218:221], v[36:39]
	v_mfma_f32_16x16x32_bf16 v[28:31], v[178:181], v[218:221], v[28:31]
	v_mfma_f32_16x16x32_bf16 v[20:23], v[170:173], v[226:229], v[20:23]
	v_mfma_f32_16x16x32_bf16 v[12:15], v[178:181], v[226:229], v[12:15]
	v_mfma_f32_16x16x32_bf16 v[48:51], v[182:185], v[198:201], v[48:51]
	v_mfma_f32_16x16x32_bf16 v[40:43], v[190:193], v[198:201], v[40:43]
	v_mfma_f32_16x16x32_bf16 v[32:35], v[182:185], v[206:209], v[32:35]
	v_mfma_f32_16x16x32_bf16 v[24:27], v[190:193], v[206:209], v[24:27]
	v_mfma_f32_16x16x32_bf16 v[16:19], v[182:185], v[214:217], v[16:19]
	v_mfma_f32_16x16x32_bf16 v[8:11], v[190:193], v[214:217], v[8:11]
	v_mfma_f32_16x16x32_bf16 v[4:7], v[182:185], v[222:225], v[4:7]
	v_mfma_f32_16x16x32_bf16 v[0:3], v[190:193], v[222:225], v[0:3]
	v_mfma_f32_16x16x32_bf16 v[48:51], v[186:189], v[202:205], v[48:51]
	v_mfma_f32_16x16x32_bf16 v[40:43], v[194:197], v[202:205], v[40:43]
	v_mfma_f32_16x16x32_bf16 v[32:35], v[186:189], v[210:213], v[32:35]
	v_mfma_f32_16x16x32_bf16 v[24:27], v[194:197], v[210:213], v[24:27]
	v_mfma_f32_16x16x32_bf16 v[16:19], v[186:189], v[218:221], v[16:19]
	v_mfma_f32_16x16x32_bf16 v[8:11], v[194:197], v[218:221], v[8:11]
	v_mfma_f32_16x16x32_bf16 v[4:7], v[186:189], v[226:229], v[4:7]
	v_mfma_f32_16x16x32_bf16 v[0:3], v[194:197], v[226:229], v[0:3]
	s_barrier
; #define PG8_STAGE(bufoff, gbase, voff) do { _Pragma("unroll") for (int _i = 0; _i < 2; ++_i) \
;         __builtin_amdgcn_global_load_lds((const unsigned*)((const char*)(gbase) + (voff)[_i]), (PG8_LAS unsigned*)(lds + (bufoff) + ldsw + _i * 8192), 16, 0, 0); } while (0)
; #define PG8_LDA(dst, b, h) do { _Pragma("unroll") for (int m = 0; m < 4; ++m) _Pragma("unroll") for (int k = 0; k < 2; ++k) dst[m][k] = *(const PG8_LAS bf16x8*)(lds + PG8_SA(b, h) + aoff + m * 2048 + k * 1024); } while (0)
; #define PG8_LDB(dst, b, h) do { _Pragma("unroll") for (int n = 0; n < 2; ++n) _Pragma("unroll") for (int k = 0; k < 2; ++k) dst[n][k] = *(const PG8_LAS bf16x8*)(lds + PG8_SB(b, h) + boff + n * 2048 + k * 1024); } while (0)
; #define PG8_MMA(ai, bj, At, Bt) do { __builtin_amdgcn_s_setprio(1); _Pragma("unroll") for (int m = 0; m < 4; ++m) _Pragma("unroll") for (int n = 0; n < 2; ++n) _Pragma("unroll") for (int k = 0; k < 2; ++k) \
;         acc[ai][bj][m][n] = __builtin_amdgcn_mfma_f32_16x16x32_bf16(Bt[n][k], At[m][k], acc[ai][bj][m][n], 0, 0, 0); __builtin_amdgcn_s_setprio(0); } while (0)
; #define PG8_WAIT_V(n) asm volatile("s_waitcnt vmcnt(" #n ")" ::: "memory")
; #define PG8_WAIT_L(n) asm volatile("s_waitcnt lgkmcnt(" #n ")" ::: "memory")
; #define PG8_BAR __builtin_amdgcn_s_barrier()
; #define PG8_SCHED __builtin_amdgcn_sched_barrier(0)
; template <class Epi, class Sched, bool ALIGN_EPI = false, bool SP2 = false>
; __device__ __forceinline__ void gemm_phase(PG8_LAS unsigned char* lds, const Gemm g, const Sched& S, const Epi& E) {
;     ...
;             PG8_LDB(B0, 1, 0); PG8_LDB(B1, 1, 1); PG8_SCHED; PG8_LDA(At, 1, 0); PG8_STAGE(PG8_SA(0, 1), a2 + hstepA, voffA);
;             PG8_WAIT_V(8); PG8_WAIT_L(0); PG8_BAR; PG8_MMA(0, 0, At, B0); PG8_MMA(0, 1, At, B1); PG8_BAR; PG8_SCHED;
;             PG8_LDA(At, 1, 1); PG8_STAGE(PG8_SB(1, 0), b3, voffB); PG8_STAGE(PG8_SB(1, 1), b3 + hstepB, voffB); PG8_STAGE(PG8_SA(1, 0), a3, voffA);
;             PG8_WAIT_V(8); PG8_WAIT_L(0); PG8_BAR; PG8_MMA(1, 0, At, B0); PG8_MMA(1, 1, At, B1); PG8_BAR; PG8_SCHED;
	s_setprio 1
	s_add_i32 s66, 0, 0x18000
	v_add_u32_e32 v163, s66, v155
	s_add_i32 s67, 0, 0x1c000
	ds_read_b128 v[166:169], v163
	ds_read_b128 v[170:173], v163 offset:1024
	ds_read_b128 v[174:177], v163 offset:2048
	ds_read_b128 v[178:181], v163 offset:3072
	v_add_u32_e32 v163, s67, v155
	ds_read_b128 v[182:185], v163
	ds_read_b128 v[186:189], v163 offset:1024
	ds_read_b128 v[190:193], v163 offset:2048
	ds_read_b128 v[194:197], v163 offset:3072
	s_add_u32 s52, s52, 0x200000
	s_addc_u32 s53, s53, 0
	s_mov_b32 m0, s31
	ds_read_b128 v[198:201], v159 offset:32768
	ds_read_b128 v[202:205], v159 offset:33792
	ds_read_b128 v[206:209], v159 offset:34816
	ds_read_b128 v[210:213], v159 offset:35840
	ds_read_b128 v[214:217], v159 offset:36864
	ds_read_b128 v[218:221], v159 offset:37888
	ds_read_b128 v[222:225], v159 offset:38912
	ds_read_b128 v[226:229], v159 offset:39936
	global_load_lds_dwordx4 v128, s[52:53]
	s_mov_b32 m0, s33
	s_nop 0
	global_load_lds_dwordx4 v132, s[52:53]
	s_waitcnt vmcnt(8)
	s_waitcnt lgkmcnt(0)
	s_setprio 0
	s_barrier
	v_mfma_f32_16x16x32_bf16 v[124:127], v[166:169], v[198:201], v[124:127]
	v_mfma_f32_16x16x32_bf16 v[120:123], v[174:177], v[198:201], v[120:123]
	v_mfma_f32_16x16x32_bf16 v[116:119], v[166:169], v[206:209], v[116:119]
	v_mfma_f32_16x16x32_bf16 v[108:111], v[174:177], v[206:209], v[108:111]
	v_mfma_f32_16x16x32_bf16 v[100:103], v[166:169], v[214:217], v[100:103]
	v_mfma_f32_16x16x32_bf16 v[92:95], v[174:177], v[214:217], v[92:95]
	v_mfma_f32_16x16x32_bf16 v[80:83], v[166:169], v[222:225], v[80:83]
	v_mfma_f32_16x16x32_bf16 v[72:75], v[174:177], v[222:225], v[72:75]
	v_mfma_f32_16x16x32_bf16 v[124:127], v[170:173], v[202:205], v[124:127]
	v_mfma_f32_16x16x32_bf16 v[120:123], v[178:181], v[202:205], v[120:123]
	v_mfma_f32_16x16x32_bf16 v[116:119], v[170:173], v[210:213], v[116:119]
	v_mfma_f32_16x16x32_bf16 v[108:111], v[178:181], v[210:213], v[108:111]
	v_mfma_f32_16x16x32_bf16 v[100:103], v[170:173], v[218:221], v[100:103]
	v_mfma_f32_16x16x32_bf16 v[92:95], v[178:181], v[218:221], v[92:95]
	v_mfma_f32_16x16x32_bf16 v[80:83], v[170:173], v[226:229], v[80:83]
	v_mfma_f32_16x16x32_bf16 v[72:75], v[178:181], v[226:229], v[72:75]
	v_mfma_f32_16x16x32_bf16 v[112:115], v[182:185], v[198:201], v[112:115]
	v_mfma_f32_16x16x32_bf16 v[104:107], v[190:193], v[198:201], v[104:107]
	v_mfma_f32_16x16x32_bf16 v[96:99], v[182:185], v[206:209], v[96:99]
	v_mfma_f32_16x16x32_bf16 v[88:91], v[190:193], v[206:209], v[88:91]
	v_mfma_f32_16x16x32_bf16 v[84:87], v[182:185], v[214:217], v[84:87]
	v_mfma_f32_16x16x32_bf16 v[76:79], v[190:193], v[214:217], v[76:79]
	v_mfma_f32_16x16x32_bf16 v[68:71], v[182:185], v[222:225], v[68:71]
	v_mfma_f32_16x16x32_bf16 v[64:67], v[190:193], v[222:225], v[64:67]
	v_mfma_f32_16x16x32_bf16 v[112:115], v[186:189], v[202:205], v[112:115]
	v_mfma_f32_16x16x32_bf16 v[104:107], v[194:197], v[202:205], v[104:107]
	v_mfma_f32_16x16x32_bf16 v[96:99], v[186:189], v[210:213], v[96:99]
	v_mfma_f32_16x16x32_bf16 v[88:91], v[194:197], v[210:213], v[88:91]
	v_mfma_f32_16x16x32_bf16 v[84:87], v[186:189], v[218:221], v[84:87]
	v_mfma_f32_16x16x32_bf16 v[76:79], v[194:197], v[218:221], v[76:79]
	v_mfma_f32_16x16x32_bf16 v[68:71], v[186:189], v[226:229], v[68:71]
	v_mfma_f32_16x16x32_bf16 v[64:67], v[194:197], v[226:229], v[64:67]
	s_barrier
	s_setprio 1
	s_add_i32 s52, s66, s28
	s_mov_b32 m0, s52
	ds_read_b128 v[198:201], v159 offset:49152
	ds_read_b128 v[202:205], v159 offset:50176
	ds_read_b128 v[206:209], v159 offset:51200
	ds_read_b128 v[210:213], v159 offset:52224
	ds_read_b128 v[214:217], v159 offset:53248
	ds_read_b128 v[218:221], v159 offset:54272
	ds_read_b128 v[222:225], v159 offset:55296
	ds_read_b128 v[226:229], v159 offset:56320
	global_load_lds_dwordx4 v130, s[98:99]
	s_add_i32 m0, s52, 0x2000
	s_add_u32 s50, s50, 0x200080
	s_addc_u32 s51, s51, 0
	s_add_i32 s52, s67, s28
	global_load_lds_dwordx4 v134, s[98:99]
	s_mov_b32 m0, s52
	s_nop 0
	global_load_lds_dwordx4 v130, s[50:51]
	s_add_i32 m0, s52, 0x2000
	s_nop 0
	global_load_lds_dwordx4 v134, s[50:51]
	s_mov_b32 m0, s35
	s_nop 0
	global_load_lds_dwordx4 v128, s[100:101]
	s_mov_b32 m0, s47
	s_nop 0
	global_load_lds_dwordx4 v132, s[100:101]
	s_waitcnt vmcnt(8)
	s_waitcnt lgkmcnt(0)
	s_setprio 0
	s_barrier
	v_mfma_f32_16x16x32_bf16 v[60:63], v[166:169], v[198:201], v[60:63]
	v_mfma_f32_16x16x32_bf16 v[56:59], v[174:177], v[198:201], v[56:59]
	v_mfma_f32_16x16x32_bf16 v[52:55], v[166:169], v[206:209], v[52:55]
	v_mfma_f32_16x16x32_bf16 v[44:47], v[174:177], v[206:209], v[44:47]
	v_mfma_f32_16x16x32_bf16 v[36:39], v[166:169], v[214:217], v[36:39]
	v_mfma_f32_16x16x32_bf16 v[28:31], v[174:177], v[214:217], v[28:31]
	v_mfma_f32_16x16x32_bf16 v[20:23], v[166:169], v[222:225], v[20:23]
	v_mfma_f32_16x16x32_bf16 v[12:15], v[174:177], v[222:225], v[12:15]
	v_mfma_f32_16x16x32_bf16 v[60:63], v[170:173], v[202:205], v[60:63]
	v_mfma_f32_16x16x32_bf16 v[56:59], v[178:181], v[202:205], v[56:59]
	v_mfma_f32_16x16x32_bf16 v[52:55], v[170:173], v[210:213], v[52:55]
	v_mfma_f32_16x16x32_bf16 v[44:47], v[178:181], v[210:213], v[44:47]
	v_mfma_f32_16x16x32_bf16 v[36:39], v[170:173], v[218:221], v[36:39]
	v_mfma_f32_16x16x32_bf16 v[28:31], v[178:181], v[218:221], v[28:31]
	v_mfma_f32_16x16x32_bf16 v[20:23], v[170:173], v[226:229], v[20:23]
	v_mfma_f32_16x16x32_bf16 v[12:15], v[178:181], v[226:229], v[12:15]
	v_mfma_f32_16x16x32_bf16 v[48:51], v[182:185], v[198:201], v[48:51]
	v_mfma_f32_16x16x32_bf16 v[40:43], v[190:193], v[198:201], v[40:43]
	v_mfma_f32_16x16x32_bf16 v[32:35], v[182:185], v[206:209], v[32:35]
	v_mfma_f32_16x16x32_bf16 v[24:27], v[190:193], v[206:209], v[24:27]
	v_mfma_f32_16x16x32_bf16 v[16:19], v[182:185], v[214:217], v[16:19]
	v_mfma_f32_16x16x32_bf16 v[8:11], v[190:193], v[214:217], v[8:11]
	v_mfma_f32_16x16x32_bf16 v[4:7], v[182:185], v[222:225], v[4:7]
	v_mfma_f32_16x16x32_bf16 v[0:3], v[190:193], v[222:225], v[0:3]
	v_mfma_f32_16x16x32_bf16 v[48:51], v[186:189], v[202:205], v[48:51]
	v_mfma_f32_16x16x32_bf16 v[40:43], v[194:197], v[202:205], v[40:43]
	v_mfma_f32_16x16x32_bf16 v[32:35], v[186:189], v[210:213], v[32:35]
	v_mfma_f32_16x16x32_bf16 v[24:27], v[194:197], v[210:213], v[24:27]
	v_mfma_f32_16x16x32_bf16 v[16:19], v[186:189], v[218:221], v[16:19]
	v_mfma_f32_16x16x32_bf16 v[8:11], v[194:197], v[218:221], v[8:11]
	v_mfma_f32_16x16x32_bf16 v[4:7], v[186:189], v[226:229], v[4:7]
	v_mfma_f32_16x16x32_bf16 v[0:3], v[194:197], v[226:229], v[0:3]
	s_barrier
	s_setprio 1
	s_add_i32 s65, s65, 2
	s_add_u32 s48, s48, 0x100
	s_addc_u32 s49, s49, 0
	s_add_u32 s63, s63, 0x100
	s_addc_u32 s64, s64, 0
	s_cmpk_gt_u32 s65, 0x7d
	s_cbranch_scc0 .LBB0_1161
	s_and_b64 vcc, exec, s[16:17]
	s_cbranch_vccz .LBB0_1164
	s_barrier

; #define PG8_STAGE(bufoff, gbase, voff) do { _Pragma("unroll") for (int _i = 0; _i < 2; ++_i) \
;         __builtin_amdgcn_global_load_lds((const unsigned*)((const char*)(gbase) + (voff)[_i]), (PG8_LAS unsigned*)(lds + (bufoff) + ldsw + _i * 8192), 16, 0, 0); } while (0)
; #define PG8_LDA(dst, b, h) do { _Pragma("unroll") for (int m = 0; m < 4; ++m) _Pragma("unroll") for (int k = 0; k < 2; ++k) dst[m][k] = *(const PG8_LAS bf16x8*)(lds + PG8_SA(b, h) + aoff + m * 2048 + k * 1024); } while (0)
; #define PG8_LDB(dst, b, h) do { _Pragma("unroll") for (int n = 0; n < 2; ++n) _Pragma("unroll") for (int k = 0; k < 2; ++k) dst[n][k] = *(const PG8_LAS bf16x8*)(lds + PG8_SB(b, h) + boff + n * 2048 + k * 1024); } while (0)
; #define PG8_MMA(ai, bj, At, Bt) do { __builtin_amdgcn_s_setprio(1); _Pragma("unroll") for (int m = 0; m < 4; ++m) _Pragma("unroll") for (int n = 0; n < 2; ++n) _Pragma("unroll") for (int k = 0; k < 2; ++k) \
;         acc[ai][bj][m][n] = __builtin_amdgcn_mfma_f32_16x16x32_bf16(Bt[n][k], At[m][k], acc[ai][bj][m][n], 0, 0, 0); __builtin_amdgcn_s_setprio(0); } while (0)
; #define PG8_WAIT_V(n) asm volatile("s_waitcnt vmcnt(" #n ")" ::: "memory")
; #define PG8_WAIT_L(n) asm volatile("s_waitcnt lgkmcnt(" #n ")" ::: "memory")
; template <class Epi, class Sched, bool ALIGN_EPI = false, bool SP2 = false>
; __device__ __forceinline__ void gemm_phase(PG8_LAS unsigned char* lds, const Gemm g, const Sched& S, const Epi& E) {
;     ...
;             const bool last = (t == nt - 2);
;             const char* a1 = cA + (size_t)(t + 1) * kstep;
;             const char* a2 = last ? nA : cA + (size_t)(t + 2) * kstep; const char* b2 = last ? nB : cB + (size_t)(t + 2) * kstep;
;             const char* a3 = a2 + kstep; const char* b3 = b2 + kstep;
;             if (last && has_next) S.a_ready(nxt);
;             if constexpr (SP2) {
;             PG8_LDB(B0, 0, 0); PG8_LDB(B1, 0, 1); PG8_SCHED; PG8_LDA(At, 0, 0); PG8_STAGE(PG8_SA(1, 1), a1 + hstepA, voffA);
;             PG8_WAIT_V(8); PG8_WAIT_L(0); PG8_BAR; PG8_MMA(0, 0, At, B0); PG8_MMA(0, 1, At, B1); PG8_BAR; PG8_SCHED;
;             PG8_LDA(At, 0, 1); PG8_STAGE(PG8_SB(0, 0), b2, voffB); PG8_STAGE(PG8_SB(0, 1), b2 + hstepB, voffB); PG8_STAGE(PG8_SA(0, 0), a2, voffA);
;             PG8_WAIT_V(8); PG8_WAIT_L(0); PG8_BAR; PG8_MMA(1, 0, At, B0); PG8_MMA(1, 1, At, B1); PG8_BAR; PG8_SCHED;
.LBB0_1181:
	ds_read_b128 v[150:153], v146
	ds_read_b128 v[154:157], v146 offset:1024
	ds_read_b128 v[158:161], v146 offset:2048
	ds_read_b128 v[166:169], v146 offset:3072
	ds_read_b128 v[170:173], v147
	ds_read_b128 v[174:177], v147 offset:1024
	ds_read_b128 v[178:181], v147 offset:2048
	ds_read_b128 v[182:185], v147 offset:3072
	s_add_u32 s43, s46, 0xffe00080
	s_addc_u32 s48, s47, -1
	s_cmp_eq_u32 s41, 12
	s_cselect_b32 s51, s1, s48
	s_cselect_b32 s50, s0, s43
	s_cselect_b32 s49, s45, s39
	s_cselect_b32 s48, s44, s19
	s_mov_b32 m0, s55
	ds_read_b128 v[186:189], v148
	ds_read_b128 v[190:193], v148 offset:1024
	ds_read_b128 v[194:197], v148 offset:2048
	ds_read_b128 v[198:201], v148 offset:3072
	ds_read_b128 v[202:205], v148 offset:4096
	ds_read_b128 v[206:209], v148 offset:5120
	ds_read_b128 v[210:213], v148 offset:6144
	ds_read_b128 v[214:217], v148 offset:7168
	global_load_lds_dwordx4 v136, s[46:47]
	s_mov_b32 m0, s56
	s_nop 0
	global_load_lds_dwordx4 v138, s[46:47]
	s_waitcnt vmcnt(8)
	s_waitcnt lgkmcnt(0)
	s_setprio 0
	s_barrier
	v_mfma_f32_16x16x32_bf16 v[124:127], v[150:153], v[186:189], v[124:127]
	v_mfma_f32_16x16x32_bf16 v[120:123], v[158:161], v[186:189], v[120:123]
	v_mfma_f32_16x16x32_bf16 v[116:119], v[150:153], v[194:197], v[116:119]
	v_mfma_f32_16x16x32_bf16 v[112:115], v[158:161], v[194:197], v[112:115]
	v_mfma_f32_16x16x32_bf16 v[100:103], v[150:153], v[202:205], v[100:103]
	v_mfma_f32_16x16x32_bf16 v[96:99], v[158:161], v[202:205], v[96:99]
	v_mfma_f32_16x16x32_bf16 v[84:87], v[150:153], v[210:213], v[84:87]
	v_mfma_f32_16x16x32_bf16 v[80:83], v[158:161], v[210:213], v[80:83]
	v_mfma_f32_16x16x32_bf16 v[124:127], v[154:157], v[190:193], v[124:127]
	v_mfma_f32_16x16x32_bf16 v[120:123], v[166:169], v[190:193], v[120:123]
	v_mfma_f32_16x16x32_bf16 v[116:119], v[154:157], v[198:201], v[116:119]
	v_mfma_f32_16x16x32_bf16 v[112:115], v[166:169], v[198:201], v[112:115]
	v_mfma_f32_16x16x32_bf16 v[100:103], v[154:157], v[206:209], v[100:103]
	v_mfma_f32_16x16x32_bf16 v[96:99], v[166:169], v[206:209], v[96:99]
	v_mfma_f32_16x16x32_bf16 v[84:87], v[154:157], v[214:217], v[84:87]
	v_mfma_f32_16x16x32_bf16 v[80:83], v[166:169], v[214:217], v[80:83]
	v_mfma_f32_16x16x32_bf16 v[108:111], v[170:173], v[186:189], v[108:111]
	v_mfma_f32_16x16x32_bf16 v[104:107], v[178:181], v[186:189], v[104:107]
	v_mfma_f32_16x16x32_bf16 v[92:95], v[170:173], v[194:197], v[92:95]
	v_mfma_f32_16x16x32_bf16 v[88:91], v[178:181], v[194:197], v[88:91]
	v_mfma_f32_16x16x32_bf16 v[76:79], v[170:173], v[202:205], v[76:79]
	v_mfma_f32_16x16x32_bf16 v[72:75], v[178:181], v[202:205], v[72:75]
	v_mfma_f32_16x16x32_bf16 v[68:71], v[170:173], v[210:213], v[68:71]
	v_mfma_f32_16x16x32_bf16 v[64:67], v[178:181], v[210:213], v[64:67]
	v_mfma_f32_16x16x32_bf16 v[108:111], v[174:177], v[190:193], v[108:111]
	v_mfma_f32_16x16x32_bf16 v[104:107], v[182:185], v[190:193], v[104:107]
	v_mfma_f32_16x16x32_bf16 v[92:95], v[174:177], v[198:201], v[92:95]
	v_mfma_f32_16x16x32_bf16 v[88:91], v[182:185], v[198:201], v[88:91]
	v_mfma_f32_16x16x32_bf16 v[76:79], v[174:177], v[206:209], v[76:79]
	v_mfma_f32_16x16x32_bf16 v[72:75], v[182:185], v[206:209], v[72:75]
	v_mfma_f32_16x16x32_bf16 v[68:71], v[174:177], v[214:217], v[68:71]
	v_mfma_f32_16x16x32_bf16 v[64:67], v[182:185], v[214:217], v[64:67]
	s_barrier
	s_setprio 1
	s_add_u32 s98, s48, s16
	s_addc_u32 s99, s49, s17
	s_add_u32 s100, s50, s16
	s_addc_u32 s101, s51, s17
	s_add_i32 s43, s53, s30
	s_mov_b32 m0, s43
	ds_read_b128 v[186:189], v148 offset:16384
	ds_read_b128 v[190:193], v148 offset:17408
	ds_read_b128 v[194:197], v148 offset:18432
	ds_read_b128 v[198:201], v148 offset:19456
	ds_read_b128 v[202:205], v148 offset:20480
	ds_read_b128 v[206:209], v148 offset:21504
	ds_read_b128 v[210:213], v148 offset:22528
	ds_read_b128 v[214:217], v148 offset:23552
	global_load_lds_dwordx4 v130, s[48:49]
	s_add_i32 m0, s43, 0x2000
	s_add_u32 s58, s48, 0x200000
	s_addc_u32 s59, s49, 0
	s_add_i32 s43, s54, s30
	global_load_lds_dwordx4 v134, s[48:49]
	s_mov_b32 m0, s43
	s_nop 0
	global_load_lds_dwordx4 v130, s[58:59]
	s_add_i32 m0, s43, 0x2000
	s_nop 0
	global_load_lds_dwordx4 v134, s[58:59]
	s_mov_b32 m0, s21
	s_nop 0
	global_load_lds_dwordx4 v128, s[50:51]
	s_mov_b32 m0, s23
	s_nop 0
	global_load_lds_dwordx4 v132, s[50:51]
	s_waitcnt vmcnt(8)
	s_waitcnt lgkmcnt(0)
	s_setprio 0
	s_barrier
	v_mfma_f32_16x16x32_bf16 v[60:63], v[150:153], v[186:189], v[60:63]
	v_mfma_f32_16x16x32_bf16 v[56:59], v[158:161], v[186:189], v[56:59]
	v_mfma_f32_16x16x32_bf16 v[52:55], v[150:153], v[194:197], v[52:55]
	v_mfma_f32_16x16x32_bf16 v[48:51], v[158:161], v[194:197], v[48:51]
	v_mfma_f32_16x16x32_bf16 v[36:39], v[150:153], v[202:205], v[36:39]
	v_mfma_f32_16x16x32_bf16 v[32:35], v[158:161], v[202:205], v[32:35]
	v_mfma_f32_16x16x32_bf16 v[20:23], v[150:153], v[210:213], v[20:23]
	v_mfma_f32_16x16x32_bf16 v[16:19], v[158:161], v[210:213], v[16:19]
	v_mfma_f32_16x16x32_bf16 v[60:63], v[154:157], v[190:193], v[60:63]
	v_mfma_f32_16x16x32_bf16 v[56:59], v[166:169], v[190:193], v[56:59]
	v_mfma_f32_16x16x32_bf16 v[52:55], v[154:157], v[198:201], v[52:55]
	v_mfma_f32_16x16x32_bf16 v[48:51], v[166:169], v[198:201], v[48:51]
	v_mfma_f32_16x16x32_bf16 v[36:39], v[154:157], v[206:209], v[36:39]
	v_mfma_f32_16x16x32_bf16 v[32:35], v[166:169], v[206:209], v[32:35]
	v_mfma_f32_16x16x32_bf16 v[20:23], v[154:157], v[214:217], v[20:23]
	v_mfma_f32_16x16x32_bf16 v[16:19], v[166:169], v[214:217], v[16:19]
	v_mfma_f32_16x16x32_bf16 v[44:47], v[170:173], v[186:189], v[44:47]
	v_mfma_f32_16x16x32_bf16 v[40:43], v[178:181], v[186:189], v[40:43]
	v_mfma_f32_16x16x32_bf16 v[28:31], v[170:173], v[194:197], v[28:31]
	v_mfma_f32_16x16x32_bf16 v[24:27], v[178:181], v[194:197], v[24:27]
	v_mfma_f32_16x16x32_bf16 v[12:15], v[170:173], v[202:205], v[12:15]
	v_mfma_f32_16x16x32_bf16 v[8:11], v[178:181], v[202:205], v[8:11]
	v_mfma_f32_16x16x32_bf16 v[4:7], v[170:173], v[210:213], v[4:7]
	v_mfma_f32_16x16x32_bf16 v[0:3], v[178:181], v[210:213], v[0:3]
	v_mfma_f32_16x16x32_bf16 v[44:47], v[174:177], v[190:193], v[44:47]
	v_mfma_f32_16x16x32_bf16 v[40:43], v[182:185], v[190:193], v[40:43]
	v_mfma_f32_16x16x32_bf16 v[28:31], v[174:177], v[198:201], v[28:31]
	v_mfma_f32_16x16x32_bf16 v[24:27], v[182:185], v[198:201], v[24:27]
	v_mfma_f32_16x16x32_bf16 v[12:15], v[174:177], v[206:209], v[12:15]
	v_mfma_f32_16x16x32_bf16 v[8:11], v[182:185], v[206:209], v[8:11]
	v_mfma_f32_16x16x32_bf16 v[4:7], v[174:177], v[214:217], v[4:7]
	v_mfma_f32_16x16x32_bf16 v[0:3], v[182:185], v[214:217], v[0:3]
	s_barrier
; #define PG8_STAGE(bufoff, gbase, voff) do { _Pragma("unroll") for (int _i = 0; _i < 2; ++_i) \
;         __builtin_amdgcn_global_load_lds((const unsigned*)((const char*)(gbase) + (voff)[_i]), (PG8_LAS unsigned*)(lds + (bufoff) + ldsw + _i * 8192), 16, 0, 0); } while (0)
; #define PG8_LDA(dst, b, h) do { _Pragma("unroll") for (int m = 0; m < 4; ++m) _Pragma("unroll") for (int k = 0; k < 2; ++k) dst[m][k] = *(const PG8_LAS bf16x8*)(lds + PG8_SA(b, h) + aoff + m * 2048 + k * 1024); } while (0)
; #define PG8_LDB(dst, b, h) do { _Pragma("unroll") for (int n = 0; n < 2; ++n) _Pragma("unroll") for (int k = 0; k < 2; ++k) dst[n][k] = *(const PG8_LAS bf16x8*)(lds + PG8_SB(b, h) + boff + n * 2048 + k * 1024); } while (0)
; #define PG8_MMA(ai, bj, At, Bt) do { __builtin_amdgcn_s_setprio(1); _Pragma("unroll") for (int m = 0; m < 4; ++m) _Pragma("unroll") for (int n = 0; n < 2; ++n) _Pragma("unroll") for (int k = 0; k < 2; ++k) \
;         acc[ai][bj][m][n] = __builtin_amdgcn_mfma_f32_16x16x32_bf16(Bt[n][k], At[m][k], acc[ai][bj][m][n], 0, 0, 0); __builtin_amdgcn_s_setprio(0); } while (0)
; #define PG8_WAIT_V(n) asm volatile("s_waitcnt vmcnt(" #n ")" ::: "memory")
; #define PG8_WAIT_L(n) asm volatile("s_waitcnt lgkmcnt(" #n ")" ::: "memory")
; #define PG8_BAR __builtin_amdgcn_s_barrier()
; #define PG8_SCHED __builtin_amdgcn_sched_barrier(0)
; template <class Epi, class Sched, bool ALIGN_EPI = false, bool SP2 = false>
; __device__ __forceinline__ void gemm_phase(PG8_LAS unsigned char* lds, const Gemm g, const Sched& S, const Epi& E) {
;     ...
;             PG8_LDB(B0, 1, 0); PG8_LDB(B1, 1, 1); PG8_SCHED; PG8_LDA(At, 1, 0); PG8_STAGE(PG8_SA(0, 1), a2 + hstepA, voffA);
;             PG8_WAIT_V(8); PG8_WAIT_L(0); PG8_BAR; PG8_MMA(0, 0, At, B0); PG8_MMA(0, 1, At, B1); PG8_BAR; PG8_SCHED;
;             PG8_LDA(At, 1, 1); PG8_STAGE(PG8_SB(1, 0), b3, voffB); PG8_STAGE(PG8_SB(1, 1), b3 + hstepB, voffB); PG8_STAGE(PG8_SA(1, 0), a3, voffA);
;             PG8_WAIT_V(8); PG8_WAIT_L(0); PG8_BAR; PG8_MMA(1, 0, At, B0); PG8_MMA(1, 1, At, B1); PG8_BAR; PG8_SCHED;
	s_setprio 1
	s_add_i32 s43, 0, 0x18000
	v_add_u32_e32 v163, s43, v145
	s_add_i32 s57, 0, 0x1c000
	ds_read_b128 v[150:153], v163
	ds_read_b128 v[154:157], v163 offset:1024
	ds_read_b128 v[158:161], v163 offset:2048
	ds_read_b128 v[166:169], v163 offset:3072
	v_add_u32_e32 v163, s57, v145
	ds_read_b128 v[170:173], v163
	ds_read_b128 v[174:177], v163 offset:1024
	ds_read_b128 v[178:181], v163 offset:2048
	ds_read_b128 v[182:185], v163 offset:3072
	s_add_u32 s50, s50, 0x200000
	s_addc_u32 s51, s51, 0
	s_mov_b32 m0, s31
	ds_read_b128 v[186:189], v148 offset:32768
	ds_read_b128 v[190:193], v148 offset:33792
	ds_read_b128 v[194:197], v148 offset:34816
	ds_read_b128 v[198:201], v148 offset:35840
	ds_read_b128 v[202:205], v148 offset:36864
	ds_read_b128 v[206:209], v148 offset:37888
	ds_read_b128 v[210:213], v148 offset:38912
	ds_read_b128 v[214:217], v148 offset:39936
	global_load_lds_dwordx4 v128, s[50:51]
	s_mov_b32 m0, s33
	s_nop 0
	global_load_lds_dwordx4 v132, s[50:51]
	s_waitcnt vmcnt(8)
	s_waitcnt lgkmcnt(0)
	s_setprio 0
	s_barrier
	v_mfma_f32_16x16x32_bf16 v[124:127], v[150:153], v[186:189], v[124:127]
	v_mfma_f32_16x16x32_bf16 v[120:123], v[158:161], v[186:189], v[120:123]
	v_mfma_f32_16x16x32_bf16 v[116:119], v[150:153], v[194:197], v[116:119]
	v_mfma_f32_16x16x32_bf16 v[112:115], v[158:161], v[194:197], v[112:115]
	v_mfma_f32_16x16x32_bf16 v[100:103], v[150:153], v[202:205], v[100:103]
	v_mfma_f32_16x16x32_bf16 v[96:99], v[158:161], v[202:205], v[96:99]
	v_mfma_f32_16x16x32_bf16 v[84:87], v[150:153], v[210:213], v[84:87]
	v_mfma_f32_16x16x32_bf16 v[80:83], v[158:161], v[210:213], v[80:83]
	v_mfma_f32_16x16x32_bf16 v[124:127], v[154:157], v[190:193], v[124:127]
	v_mfma_f32_16x16x32_bf16 v[120:123], v[166:169], v[190:193], v[120:123]
	v_mfma_f32_16x16x32_bf16 v[116:119], v[154:157], v[198:201], v[116:119]
	v_mfma_f32_16x16x32_bf16 v[112:115], v[166:169], v[198:201], v[112:115]
	v_mfma_f32_16x16x32_bf16 v[100:103], v[154:157], v[206:209], v[100:103]
	v_mfma_f32_16x16x32_bf16 v[96:99], v[166:169], v[206:209], v[96:99]
	v_mfma_f32_16x16x32_bf16 v[84:87], v[154:157], v[214:217], v[84:87]
	v_mfma_f32_16x16x32_bf16 v[80:83], v[166:169], v[214:217], v[80:83]
	v_mfma_f32_16x16x32_bf16 v[108:111], v[170:173], v[186:189], v[108:111]
	v_mfma_f32_16x16x32_bf16 v[104:107], v[178:181], v[186:189], v[104:107]
	v_mfma_f32_16x16x32_bf16 v[92:95], v[170:173], v[194:197], v[92:95]
	v_mfma_f32_16x16x32_bf16 v[88:91], v[178:181], v[194:197], v[88:91]
	v_mfma_f32_16x16x32_bf16 v[76:79], v[170:173], v[202:205], v[76:79]
	v_mfma_f32_16x16x32_bf16 v[72:75], v[178:181], v[202:205], v[72:75]
	v_mfma_f32_16x16x32_bf16 v[68:71], v[170:173], v[210:213], v[68:71]
	v_mfma_f32_16x16x32_bf16 v[64:67], v[178:181], v[210:213], v[64:67]
	v_mfma_f32_16x16x32_bf16 v[108:111], v[174:177], v[190:193], v[108:111]
	v_mfma_f32_16x16x32_bf16 v[104:107], v[182:185], v[190:193], v[104:107]
	v_mfma_f32_16x16x32_bf16 v[92:95], v[174:177], v[198:201], v[92:95]
	v_mfma_f32_16x16x32_bf16 v[88:91], v[182:185], v[198:201], v[88:91]
	v_mfma_f32_16x16x32_bf16 v[76:79], v[174:177], v[206:209], v[76:79]
	v_mfma_f32_16x16x32_bf16 v[72:75], v[182:185], v[206:209], v[72:75]
	v_mfma_f32_16x16x32_bf16 v[68:71], v[174:177], v[214:217], v[68:71]
	v_mfma_f32_16x16x32_bf16 v[64:67], v[182:185], v[214:217], v[64:67]
	s_barrier
	s_setprio 1
	s_add_i32 s43, s43, s30
	s_mov_b32 m0, s43
	ds_read_b128 v[186:189], v148 offset:49152
	ds_read_b128 v[190:193], v148 offset:50176
	ds_read_b128 v[194:197], v148 offset:51200
	ds_read_b128 v[198:201], v148 offset:52224
	ds_read_b128 v[202:205], v148 offset:53248
	ds_read_b128 v[206:209], v148 offset:54272
	ds_read_b128 v[210:213], v148 offset:55296
	ds_read_b128 v[214:217], v148 offset:56320
	global_load_lds_dwordx4 v130, s[98:99]
	s_add_i32 m0, s43, 0x2000
	s_add_u32 s48, s48, 0x200080
	s_addc_u32 s49, s49, 0
	s_add_i32 s43, s57, s30
	global_load_lds_dwordx4 v134, s[98:99]
	s_mov_b32 m0, s43
	s_nop 0
	global_load_lds_dwordx4 v130, s[48:49]
	s_add_i32 m0, s43, 0x2000
	s_nop 0
	global_load_lds_dwordx4 v134, s[48:49]
	s_mov_b32 m0, s35
	s_nop 0
	global_load_lds_dwordx4 v128, s[100:101]
	s_mov_b32 m0, s52
	s_nop 0
	global_load_lds_dwordx4 v132, s[100:101]
	s_waitcnt vmcnt(8)
	s_waitcnt lgkmcnt(0)
	s_setprio 0
	s_barrier
	v_mfma_f32_16x16x32_bf16 v[60:63], v[150:153], v[186:189], v[60:63]
	v_mfma_f32_16x16x32_bf16 v[56:59], v[158:161], v[186:189], v[56:59]
	v_mfma_f32_16x16x32_bf16 v[52:55], v[150:153], v[194:197], v[52:55]
	v_mfma_f32_16x16x32_bf16 v[48:51], v[158:161], v[194:197], v[48:51]
	v_mfma_f32_16x16x32_bf16 v[36:39], v[150:153], v[202:205], v[36:39]
	v_mfma_f32_16x16x32_bf16 v[32:35], v[158:161], v[202:205], v[32:35]
	v_mfma_f32_16x16x32_bf16 v[20:23], v[150:153], v[210:213], v[20:23]
	v_mfma_f32_16x16x32_bf16 v[16:19], v[158:161], v[210:213], v[16:19]
	v_mfma_f32_16x16x32_bf16 v[60:63], v[154:157], v[190:193], v[60:63]
	v_mfma_f32_16x16x32_bf16 v[56:59], v[166:169], v[190:193], v[56:59]
	v_mfma_f32_16x16x32_bf16 v[52:55], v[154:157], v[198:201], v[52:55]
	v_mfma_f32_16x16x32_bf16 v[48:51], v[166:169], v[198:201], v[48:51]
	v_mfma_f32_16x16x32_bf16 v[36:39], v[154:157], v[206:209], v[36:39]
	v_mfma_f32_16x16x32_bf16 v[32:35], v[166:169], v[206:209], v[32:35]
	v_mfma_f32_16x16x32_bf16 v[20:23], v[154:157], v[214:217], v[20:23]
	v_mfma_f32_16x16x32_bf16 v[16:19], v[166:169], v[214:217], v[16:19]
	v_mfma_f32_16x16x32_bf16 v[44:47], v[170:173], v[186:189], v[44:47]
	v_mfma_f32_16x16x32_bf16 v[40:43], v[178:181], v[186:189], v[40:43]
	v_mfma_f32_16x16x32_bf16 v[28:31], v[170:173], v[194:197], v[28:31]
	v_mfma_f32_16x16x32_bf16 v[24:27], v[178:181], v[194:197], v[24:27]
	v_mfma_f32_16x16x32_bf16 v[12:15], v[170:173], v[202:205], v[12:15]
	v_mfma_f32_16x16x32_bf16 v[8:11], v[178:181], v[202:205], v[8:11]
	v_mfma_f32_16x16x32_bf16 v[4:7], v[170:173], v[210:213], v[4:7]
	v_mfma_f32_16x16x32_bf16 v[0:3], v[178:181], v[210:213], v[0:3]
	v_mfma_f32_16x16x32_bf16 v[44:47], v[174:177], v[190:193], v[44:47]
	v_mfma_f32_16x16x32_bf16 v[40:43], v[182:185], v[190:193], v[40:43]
	v_mfma_f32_16x16x32_bf16 v[28:31], v[174:177], v[198:201], v[28:31]
	v_mfma_f32_16x16x32_bf16 v[24:27], v[182:185], v[198:201], v[24:27]
	v_mfma_f32_16x16x32_bf16 v[12:15], v[174:177], v[206:209], v[12:15]
	v_mfma_f32_16x16x32_bf16 v[8:11], v[182:185], v[206:209], v[8:11]
	v_mfma_f32_16x16x32_bf16 v[4:7], v[174:177], v[214:217], v[4:7]
	v_mfma_f32_16x16x32_bf16 v[0:3], v[182:185], v[214:217], v[0:3]
	s_barrier
	s_setprio 1
	s_add_i32 s41, s41, 2
	s_add_u32 s46, s46, 0x100
	s_addc_u32 s47, s47, 0
	s_add_u32 s19, s19, 0x100
	s_addc_u32 s39, s39, 0
	s_cmp_gt_u32 s41, 13
	s_cbranch_scc0 .LBB0_1181
	s_and_b64 vcc, exec, s[36:37]
	s_cbranch_vccz .LBB0_1184
	s_barrier

; #define PG8_STAGE(bufoff, gbase, voff) do { _Pragma("unroll") for (int _i = 0; _i < 2; ++_i) \
;         __builtin_amdgcn_global_load_lds((const unsigned*)((const char*)(gbase) + (voff)[_i]), (PG8_LAS unsigned*)(lds + (bufoff) + ldsw + _i * 8192), 16, 0, 0); } while (0)
; #define PG8_LDA(dst, b, h) do { _Pragma("unroll") for (int m = 0; m < 4; ++m) _Pragma("unroll") for (int k = 0; k < 2; ++k) dst[m][k] = *(const PG8_LAS bf16x8*)(lds + PG8_SA(b, h) + aoff + m * 2048 + k * 1024); } while (0)
; #define PG8_LDB(dst, b, h) do { _Pragma("unroll") for (int n = 0; n < 2; ++n) _Pragma("unroll") for (int k = 0; k < 2; ++k) dst[n][k] = *(const PG8_LAS bf16x8*)(lds + PG8_SB(b, h) + boff + n * 2048 + k * 1024); } while (0)
; #define PG8_MMA(ai, bj, At, Bt) do { __builtin_amdgcn_s_setprio(1); _Pragma("unroll") for (int m = 0; m < 4; ++m) _Pragma("unroll") for (int n = 0; n < 2; ++n) _Pragma("unroll") for (int k = 0; k < 2; ++k) \
;         acc[ai][bj][m][n] = __builtin_amdgcn_mfma_f32_16x16x32_bf16(Bt[n][k], At[m][k], acc[ai][bj][m][n], 0, 0, 0); __builtin_amdgcn_s_setprio(0); } while (0)
; #define PG8_WAIT_V(n) asm volatile("s_waitcnt vmcnt(" #n ")" ::: "memory")
; #define PG8_WAIT_L(n) asm volatile("s_waitcnt lgkmcnt(" #n ")" ::: "memory")
; template <class Epi, class Sched, bool ALIGN_EPI = false, bool SP2 = false>
; __device__ __forceinline__ void gemm_phase(PG8_LAS unsigned char* lds, const Gemm g, const Sched& S, const Epi& E) {
;     ...
;             const bool last = (t == nt - 2);
;             const char* a1 = cA + (size_t)(t + 1) * kstep;
;             const char* a2 = last ? nA : cA + (size_t)(t + 2) * kstep; const char* b2 = last ? nB : cB + (size_t)(t + 2) * kstep;
;             const char* a3 = a2 + kstep; const char* b3 = b2 + kstep;
;             if (last && has_next) S.a_ready(nxt);
;             if constexpr (SP2) {
;             PG8_LDB(B0, 0, 0); PG8_LDB(B1, 0, 1); PG8_SCHED; PG8_LDA(At, 0, 0); PG8_STAGE(PG8_SA(1, 1), a1 + hstepA, voffA);
;             PG8_WAIT_V(8); PG8_WAIT_L(0); PG8_BAR; PG8_MMA(0, 0, At, B0); PG8_MMA(0, 1, At, B1); PG8_BAR; PG8_SCHED;
;             PG8_LDA(At, 0, 1); PG8_STAGE(PG8_SB(0, 0), b2, voffB); PG8_STAGE(PG8_SB(0, 1), b2 + hstepB, voffB); PG8_STAGE(PG8_SA(0, 0), a2, voffA);
;             PG8_WAIT_V(8); PG8_WAIT_L(0); PG8_BAR; PG8_MMA(1, 0, At, B0); PG8_MMA(1, 1, At, B1); PG8_BAR; PG8_SCHED;
.LBB0_1262:
	s_add_u32 s51, s44, s50
	s_addc_u32 s56, s45, 0
	s_add_u32 s54, s51, 0x100
	s_addc_u32 s55, s56, 0
	s_and_b64 s[52:53], s[48:49], exec
	s_cselect_b32 s53, s23, s55
	s_cselect_b32 s52, s69, s54
	s_add_u32 s50, s42, s50
	s_addc_u32 s54, s43, 0
	s_add_u32 s50, s50, 0x100
	s_addc_u32 s54, s54, 0
	s_and_b64 s[48:49], s[48:49], exec
	s_cselect_b32 s55, s21, s54
	s_cselect_b32 s54, s70, s50
	s_add_u32 s58, s51, 0x10080
	ds_read_b128 v[148:151], v145
	ds_read_b128 v[152:155], v145 offset:1024
	ds_read_b128 v[156:159], v145 offset:2048
	ds_read_b128 v[166:169], v145 offset:3072
	ds_read_b128 v[170:173], v146
	ds_read_b128 v[174:177], v146 offset:1024
	ds_read_b128 v[178:181], v146 offset:2048
	ds_read_b128 v[182:185], v146 offset:3072
	s_addc_u32 s59, s56, 0
	s_add_i32 s80, s63, s28
	s_add_i32 m0, s33, 0xc000
	s_add_i32 s81, s33, 0xe000
	s_add_i32 s77, s80, 0x2000
	s_add_u32 s56, s54, 0x10000
	s_addc_u32 s57, s55, 0
	s_add_i32 s79, s64, s28
	s_add_i32 s78, s79, 0x2000
	s_add_i32 s76, 0, 0x18000
	s_add_i32 s75, 0, 0x1c000
	s_add_u32 s50, s52, 0x10000
	s_addc_u32 s51, s53, 0
	s_add_i32 s74, s76, s28
	s_add_i32 s72, s74, 0x2000
	s_add_u32 s48, s54, 0x10080
	s_addc_u32 s49, s55, 0
	s_add_i32 s73, s75, s28
	s_add_i32 s71, s73, 0x2000
	ds_read_b128 v[186:189], v147
	ds_read_b128 v[190:193], v147 offset:1024
	ds_read_b128 v[194:197], v147 offset:2048
	ds_read_b128 v[198:201], v147 offset:3072
	ds_read_b128 v[202:205], v147 offset:4096
	ds_read_b128 v[206:209], v147 offset:5120
	ds_read_b128 v[210:213], v147 offset:6144
	ds_read_b128 v[214:217], v147 offset:7168
	global_load_lds_dwordx4 v134, s[58:59]
	s_mov_b32 m0, s81
	s_nop 0
	global_load_lds_dwordx4 v130, s[58:59]
	s_waitcnt vmcnt(8)
	s_waitcnt lgkmcnt(0)
	s_setprio 0
	s_barrier
	v_mfma_f32_16x16x32_bf16 v[124:127], v[148:151], v[186:189], v[124:127]
	v_mfma_f32_16x16x32_bf16 v[120:123], v[156:159], v[186:189], v[120:123]
	v_mfma_f32_16x16x32_bf16 v[116:119], v[148:151], v[194:197], v[116:119]
	v_mfma_f32_16x16x32_bf16 v[108:111], v[156:159], v[194:197], v[108:111]
	v_mfma_f32_16x16x32_bf16 v[100:103], v[148:151], v[202:205], v[100:103]
	v_mfma_f32_16x16x32_bf16 v[92:95], v[156:159], v[202:205], v[92:95]
	v_mfma_f32_16x16x32_bf16 v[84:87], v[148:151], v[210:213], v[84:87]
	v_mfma_f32_16x16x32_bf16 v[76:79], v[156:159], v[210:213], v[76:79]
	v_mfma_f32_16x16x32_bf16 v[124:127], v[152:155], v[190:193], v[124:127]
	v_mfma_f32_16x16x32_bf16 v[120:123], v[166:169], v[190:193], v[120:123]
	v_mfma_f32_16x16x32_bf16 v[116:119], v[152:155], v[198:201], v[116:119]
	v_mfma_f32_16x16x32_bf16 v[108:111], v[166:169], v[198:201], v[108:111]
	v_mfma_f32_16x16x32_bf16 v[100:103], v[152:155], v[206:209], v[100:103]
	v_mfma_f32_16x16x32_bf16 v[92:95], v[166:169], v[206:209], v[92:95]
	v_mfma_f32_16x16x32_bf16 v[84:87], v[152:155], v[214:217], v[84:87]
	v_mfma_f32_16x16x32_bf16 v[76:79], v[166:169], v[214:217], v[76:79]
	v_mfma_f32_16x16x32_bf16 v[112:115], v[170:173], v[186:189], v[112:115]
	v_mfma_f32_16x16x32_bf16 v[104:107], v[178:181], v[186:189], v[104:107]
	v_mfma_f32_16x16x32_bf16 v[96:99], v[170:173], v[194:197], v[96:99]
	v_mfma_f32_16x16x32_bf16 v[88:91], v[178:181], v[194:197], v[88:91]
	v_mfma_f32_16x16x32_bf16 v[80:83], v[170:173], v[202:205], v[80:83]
	v_mfma_f32_16x16x32_bf16 v[72:75], v[178:181], v[202:205], v[72:75]
	v_mfma_f32_16x16x32_bf16 v[68:71], v[170:173], v[210:213], v[68:71]
	v_mfma_f32_16x16x32_bf16 v[64:67], v[178:181], v[210:213], v[64:67]
	v_mfma_f32_16x16x32_bf16 v[112:115], v[174:177], v[190:193], v[112:115]
	v_mfma_f32_16x16x32_bf16 v[104:107], v[182:185], v[190:193], v[104:107]
	v_mfma_f32_16x16x32_bf16 v[96:99], v[174:177], v[198:201], v[96:99]
	v_mfma_f32_16x16x32_bf16 v[88:91], v[182:185], v[198:201], v[88:91]
	v_mfma_f32_16x16x32_bf16 v[80:83], v[174:177], v[206:209], v[80:83]
	v_mfma_f32_16x16x32_bf16 v[72:75], v[182:185], v[206:209], v[72:75]
	v_mfma_f32_16x16x32_bf16 v[68:71], v[174:177], v[214:217], v[68:71]
	v_mfma_f32_16x16x32_bf16 v[64:67], v[182:185], v[214:217], v[64:67]
	s_barrier
	s_setprio 1
	s_add_u32 s98, s54, s8
	s_addc_u32 s99, s55, s9
	s_add_u32 s100, s52, s8
	s_addc_u32 s101, s53, s9
	s_mov_b32 m0, s80
	ds_read_b128 v[186:189], v147 offset:16384
	ds_read_b128 v[190:193], v147 offset:17408
	ds_read_b128 v[194:197], v147 offset:18432
	ds_read_b128 v[198:201], v147 offset:19456
	ds_read_b128 v[202:205], v147 offset:20480
	ds_read_b128 v[206:209], v147 offset:21504
	ds_read_b128 v[210:213], v147 offset:22528
	ds_read_b128 v[214:217], v147 offset:23552
	global_load_lds_dwordx4 v132, s[54:55]
	s_mov_b32 m0, s77
	s_nop 0
	global_load_lds_dwordx4 v128, s[54:55]
	s_mov_b32 m0, s79
	s_nop 0
	global_load_lds_dwordx4 v132, s[56:57]
	s_mov_b32 m0, s78
	s_nop 0
	global_load_lds_dwordx4 v128, s[56:57]
	s_mov_b32 m0, s33
	s_nop 0
	global_load_lds_dwordx4 v134, s[52:53]
	s_mov_b32 m0, s34
	s_nop 0
	global_load_lds_dwordx4 v130, s[52:53]
	s_waitcnt vmcnt(8)
	s_waitcnt lgkmcnt(0)
	s_setprio 0
	s_barrier
; #define PG8_STAGE(bufoff, gbase, voff) do { _Pragma("unroll") for (int _i = 0; _i < 2; ++_i) \
;         __builtin_amdgcn_global_load_lds((const unsigned*)((const char*)(gbase) + (voff)[_i]), (PG8_LAS unsigned*)(lds + (bufoff) + ldsw + _i * 8192), 16, 0, 0); } while (0)
; #define PG8_LDA(dst, b, h) do { _Pragma("unroll") for (int m = 0; m < 4; ++m) _Pragma("unroll") for (int k = 0; k < 2; ++k) dst[m][k] = *(const PG8_LAS bf16x8*)(lds + PG8_SA(b, h) + aoff + m * 2048 + k * 1024); } while (0)
; #define PG8_LDB(dst, b, h) do { _Pragma("unroll") for (int n = 0; n < 2; ++n) _Pragma("unroll") for (int k = 0; k < 2; ++k) dst[n][k] = *(const PG8_LAS bf16x8*)(lds + PG8_SB(b, h) + boff + n * 2048 + k * 1024); } while (0)
; #define PG8_MMA(ai, bj, At, Bt) do { __builtin_amdgcn_s_setprio(1); _Pragma("unroll") for (int m = 0; m < 4; ++m) _Pragma("unroll") for (int n = 0; n < 2; ++n) _Pragma("unroll") for (int k = 0; k < 2; ++k) \
;         acc[ai][bj][m][n] = __builtin_amdgcn_mfma_f32_16x16x32_bf16(Bt[n][k], At[m][k], acc[ai][bj][m][n], 0, 0, 0); __builtin_amdgcn_s_setprio(0); } while (0)
; #define PG8_WAIT_V(n) asm volatile("s_waitcnt vmcnt(" #n ")" ::: "memory")
; #define PG8_WAIT_L(n) asm volatile("s_waitcnt lgkmcnt(" #n ")" ::: "memory")
; #define PG8_BAR __builtin_amdgcn_s_barrier()
; #define PG8_SCHED __builtin_amdgcn_sched_barrier(0)
; template <class Epi, class Sched, bool ALIGN_EPI = false, bool SP2 = false>
; __device__ __forceinline__ void gemm_phase(PG8_LAS unsigned char* lds, const Gemm g, const Sched& S, const Epi& E) {
;     ...
;             PG8_WAIT_V(8); PG8_WAIT_L(0); PG8_BAR; PG8_MMA(1, 0, At, B0); PG8_MMA(1, 1, At, B1); PG8_BAR; PG8_SCHED;
;             PG8_LDB(B0, 1, 0); PG8_LDB(B1, 1, 1); PG8_SCHED; PG8_LDA(At, 1, 0); PG8_STAGE(PG8_SA(0, 1), a2 + hstepA, voffA);
;             PG8_WAIT_V(8); PG8_WAIT_L(0); PG8_BAR; PG8_MMA(0, 0, At, B0); PG8_MMA(0, 1, At, B1); PG8_BAR; PG8_SCHED;
	v_mfma_f32_16x16x32_bf16 v[60:63], v[148:151], v[186:189], v[60:63]
	v_mfma_f32_16x16x32_bf16 v[56:59], v[156:159], v[186:189], v[56:59]
	v_mfma_f32_16x16x32_bf16 v[52:55], v[148:151], v[194:197], v[52:55]
	v_mfma_f32_16x16x32_bf16 v[44:47], v[156:159], v[194:197], v[44:47]
	v_mfma_f32_16x16x32_bf16 v[36:39], v[148:151], v[202:205], v[36:39]
	v_mfma_f32_16x16x32_bf16 v[28:31], v[156:159], v[202:205], v[28:31]
	v_mfma_f32_16x16x32_bf16 v[20:23], v[148:151], v[210:213], v[20:23]
	v_mfma_f32_16x16x32_bf16 v[12:15], v[156:159], v[210:213], v[12:15]
	v_mfma_f32_16x16x32_bf16 v[60:63], v[152:155], v[190:193], v[60:63]
	v_mfma_f32_16x16x32_bf16 v[56:59], v[166:169], v[190:193], v[56:59]
	v_mfma_f32_16x16x32_bf16 v[52:55], v[152:155], v[198:201], v[52:55]
	v_mfma_f32_16x16x32_bf16 v[44:47], v[166:169], v[198:201], v[44:47]
	v_mfma_f32_16x16x32_bf16 v[36:39], v[152:155], v[206:209], v[36:39]
	v_mfma_f32_16x16x32_bf16 v[28:31], v[166:169], v[206:209], v[28:31]
	v_mfma_f32_16x16x32_bf16 v[20:23], v[152:155], v[214:217], v[20:23]
	v_mfma_f32_16x16x32_bf16 v[12:15], v[166:169], v[214:217], v[12:15]
	v_mfma_f32_16x16x32_bf16 v[48:51], v[170:173], v[186:189], v[48:51]
	v_mfma_f32_16x16x32_bf16 v[40:43], v[178:181], v[186:189], v[40:43]
	v_mfma_f32_16x16x32_bf16 v[32:35], v[170:173], v[194:197], v[32:35]
	v_mfma_f32_16x16x32_bf16 v[24:27], v[178:181], v[194:197], v[24:27]
	v_mfma_f32_16x16x32_bf16 v[16:19], v[170:173], v[202:205], v[16:19]
	v_mfma_f32_16x16x32_bf16 v[8:11], v[178:181], v[202:205], v[8:11]
	v_mfma_f32_16x16x32_bf16 v[4:7], v[170:173], v[210:213], v[4:7]
	v_mfma_f32_16x16x32_bf16 v[0:3], v[178:181], v[210:213], v[0:3]
	v_mfma_f32_16x16x32_bf16 v[48:51], v[174:177], v[190:193], v[48:51]
	v_mfma_f32_16x16x32_bf16 v[40:43], v[182:185], v[190:193], v[40:43]
	v_mfma_f32_16x16x32_bf16 v[32:35], v[174:177], v[198:201], v[32:35]
	v_mfma_f32_16x16x32_bf16 v[24:27], v[182:185], v[198:201], v[24:27]
	v_mfma_f32_16x16x32_bf16 v[16:19], v[174:177], v[206:209], v[16:19]
	v_mfma_f32_16x16x32_bf16 v[8:11], v[182:185], v[206:209], v[8:11]
	v_mfma_f32_16x16x32_bf16 v[4:7], v[174:177], v[214:217], v[4:7]
	v_mfma_f32_16x16x32_bf16 v[0:3], v[182:185], v[214:217], v[0:3]
	s_barrier
	s_setprio 1
	v_add_u32_e32 v163, s76, v143
	ds_read_b128 v[148:151], v163
	ds_read_b128 v[152:155], v163 offset:1024
	ds_read_b128 v[156:159], v163 offset:2048
	ds_read_b128 v[166:169], v163 offset:3072
	v_add_u32_e32 v163, s75, v143
	ds_read_b128 v[170:173], v163
	ds_read_b128 v[174:177], v163 offset:1024
	ds_read_b128 v[178:181], v163 offset:2048
	ds_read_b128 v[182:185], v163 offset:3072
	s_mov_b32 m0, s35
	ds_read_b128 v[186:189], v147 offset:32768
	ds_read_b128 v[190:193], v147 offset:33792
	ds_read_b128 v[194:197], v147 offset:34816
	ds_read_b128 v[198:201], v147 offset:35840
	ds_read_b128 v[202:205], v147 offset:36864
	ds_read_b128 v[206:209], v147 offset:37888
	ds_read_b128 v[210:213], v147 offset:38912
	ds_read_b128 v[214:217], v147 offset:39936
	global_load_lds_dwordx4 v134, s[50:51]
	s_mov_b32 m0, s41
	s_nop 0
	global_load_lds_dwordx4 v130, s[50:51]
	s_waitcnt vmcnt(8)
	s_waitcnt lgkmcnt(0)
	s_setprio 0
	s_barrier
	v_mfma_f32_16x16x32_bf16 v[124:127], v[148:151], v[186:189], v[124:127]
	v_mfma_f32_16x16x32_bf16 v[120:123], v[156:159], v[186:189], v[120:123]
	v_mfma_f32_16x16x32_bf16 v[116:119], v[148:151], v[194:197], v[116:119]
	v_mfma_f32_16x16x32_bf16 v[108:111], v[156:159], v[194:197], v[108:111]
	v_mfma_f32_16x16x32_bf16 v[100:103], v[148:151], v[202:205], v[100:103]
	v_mfma_f32_16x16x32_bf16 v[92:95], v[156:159], v[202:205], v[92:95]
	v_mfma_f32_16x16x32_bf16 v[84:87], v[148:151], v[210:213], v[84:87]
	v_mfma_f32_16x16x32_bf16 v[76:79], v[156:159], v[210:213], v[76:79]
	v_mfma_f32_16x16x32_bf16 v[124:127], v[152:155], v[190:193], v[124:127]
	v_mfma_f32_16x16x32_bf16 v[120:123], v[166:169], v[190:193], v[120:123]
	v_mfma_f32_16x16x32_bf16 v[116:119], v[152:155], v[198:201], v[116:119]
	v_mfma_f32_16x16x32_bf16 v[108:111], v[166:169], v[198:201], v[108:111]
	v_mfma_f32_16x16x32_bf16 v[100:103], v[152:155], v[206:209], v[100:103]
	v_mfma_f32_16x16x32_bf16 v[92:95], v[166:169], v[206:209], v[92:95]
	v_mfma_f32_16x16x32_bf16 v[84:87], v[152:155], v[214:217], v[84:87]
	v_mfma_f32_16x16x32_bf16 v[76:79], v[166:169], v[214:217], v[76:79]
	v_mfma_f32_16x16x32_bf16 v[112:115], v[170:173], v[186:189], v[112:115]
	v_mfma_f32_16x16x32_bf16 v[104:107], v[178:181], v[186:189], v[104:107]
	v_mfma_f32_16x16x32_bf16 v[96:99], v[170:173], v[194:197], v[96:99]
	v_mfma_f32_16x16x32_bf16 v[88:91], v[178:181], v[194:197], v[88:91]
	v_mfma_f32_16x16x32_bf16 v[80:83], v[170:173], v[202:205], v[80:83]
	v_mfma_f32_16x16x32_bf16 v[72:75], v[178:181], v[202:205], v[72:75]
	v_mfma_f32_16x16x32_bf16 v[68:71], v[170:173], v[210:213], v[68:71]
	v_mfma_f32_16x16x32_bf16 v[64:67], v[178:181], v[210:213], v[64:67]
	v_mfma_f32_16x16x32_bf16 v[112:115], v[174:177], v[190:193], v[112:115]
	v_mfma_f32_16x16x32_bf16 v[104:107], v[182:185], v[190:193], v[104:107]
	v_mfma_f32_16x16x32_bf16 v[96:99], v[174:177], v[198:201], v[96:99]
	v_mfma_f32_16x16x32_bf16 v[88:91], v[182:185], v[198:201], v[88:91]
	v_mfma_f32_16x16x32_bf16 v[80:83], v[174:177], v[206:209], v[80:83]
	v_mfma_f32_16x16x32_bf16 v[72:75], v[182:185], v[206:209], v[72:75]
	v_mfma_f32_16x16x32_bf16 v[68:71], v[174:177], v[214:217], v[68:71]
	v_mfma_f32_16x16x32_bf16 v[64:67], v[182:185], v[214:217], v[64:67]
	s_barrier
; #define PG8_STAGE(bufoff, gbase, voff) do { _Pragma("unroll") for (int _i = 0; _i < 2; ++_i) \
;         __builtin_amdgcn_global_load_lds((const unsigned*)((const char*)(gbase) + (voff)[_i]), (PG8_LAS unsigned*)(lds + (bufoff) + ldsw + _i * 8192), 16, 0, 0); } while (0)
; #define PG8_LDA(dst, b, h) do { _Pragma("unroll") for (int m = 0; m < 4; ++m) _Pragma("unroll") for (int k = 0; k < 2; ++k) dst[m][k] = *(const PG8_LAS bf16x8*)(lds + PG8_SA(b, h) + aoff + m * 2048 + k * 1024); } while (0)
; #define PG8_MMA(ai, bj, At, Bt) do { __builtin_amdgcn_s_setprio(1); _Pragma("unroll") for (int m = 0; m < 4; ++m) _Pragma("unroll") for (int n = 0; n < 2; ++n) _Pragma("unroll") for (int k = 0; k < 2; ++k) \
;         acc[ai][bj][m][n] = __builtin_amdgcn_mfma_f32_16x16x32_bf16(Bt[n][k], At[m][k], acc[ai][bj][m][n], 0, 0, 0); __builtin_amdgcn_s_setprio(0); } while (0)
; #define PG8_WAIT_V(n) asm volatile("s_waitcnt vmcnt(" #n ")" ::: "memory")
; #define PG8_WAIT_L(n) asm volatile("s_waitcnt lgkmcnt(" #n ")" ::: "memory")
; #define PG8_BAR __builtin_amdgcn_s_barrier()
; #define PG8_SCHED __builtin_amdgcn_sched_barrier(0)
; template <class Epi, class Sched, bool ALIGN_EPI = false, bool SP2 = false>
; __device__ __forceinline__ void gemm_phase(PG8_LAS unsigned char* lds, const Gemm g, const Sched& S, const Epi& E) {
;     ...
;             PG8_LDA(At, 1, 1); PG8_STAGE(PG8_SB(1, 0), b3, voffB); PG8_STAGE(PG8_SB(1, 1), b3 + hstepB, voffB); PG8_STAGE(PG8_SA(1, 0), a3, voffA);
;             PG8_WAIT_V(8); PG8_WAIT_L(0); PG8_BAR; PG8_MMA(1, 0, At, B0); PG8_MMA(1, 1, At, B1); PG8_BAR; PG8_SCHED;
	s_setprio 1
	s_mov_b32 m0, s74
	ds_read_b128 v[186:189], v147 offset:49152
	ds_read_b128 v[190:193], v147 offset:50176
	ds_read_b128 v[194:197], v147 offset:51200
	ds_read_b128 v[198:201], v147 offset:52224
	ds_read_b128 v[202:205], v147 offset:53248
	ds_read_b128 v[206:209], v147 offset:54272
	ds_read_b128 v[210:213], v147 offset:55296
	ds_read_b128 v[214:217], v147 offset:56320
	global_load_lds_dwordx4 v132, s[98:99]
	s_mov_b32 m0, s72
	s_nop 0
	global_load_lds_dwordx4 v128, s[98:99]
	s_mov_b32 m0, s73
	s_nop 0
	global_load_lds_dwordx4 v132, s[48:49]
	s_mov_b32 m0, s71
	s_nop 0
	global_load_lds_dwordx4 v128, s[48:49]
	s_mov_b32 m0, s61
	s_nop 0
	global_load_lds_dwordx4 v134, s[100:101]
	s_mov_b32 m0, s62
	s_nop 0
	global_load_lds_dwordx4 v130, s[100:101]
	s_waitcnt vmcnt(8)
	s_waitcnt lgkmcnt(0)
	s_setprio 0
	s_barrier
	v_mfma_f32_16x16x32_bf16 v[60:63], v[148:151], v[186:189], v[60:63]
	v_mfma_f32_16x16x32_bf16 v[56:59], v[156:159], v[186:189], v[56:59]
	v_mfma_f32_16x16x32_bf16 v[52:55], v[148:151], v[194:197], v[52:55]
	v_mfma_f32_16x16x32_bf16 v[44:47], v[156:159], v[194:197], v[44:47]
	v_mfma_f32_16x16x32_bf16 v[36:39], v[148:151], v[202:205], v[36:39]
	v_mfma_f32_16x16x32_bf16 v[28:31], v[156:159], v[202:205], v[28:31]
	v_mfma_f32_16x16x32_bf16 v[20:23], v[148:151], v[210:213], v[20:23]
	v_mfma_f32_16x16x32_bf16 v[12:15], v[156:159], v[210:213], v[12:15]
	v_mfma_f32_16x16x32_bf16 v[60:63], v[152:155], v[190:193], v[60:63]
	v_mfma_f32_16x16x32_bf16 v[56:59], v[166:169], v[190:193], v[56:59]
	v_mfma_f32_16x16x32_bf16 v[52:55], v[152:155], v[198:201], v[52:55]
	v_mfma_f32_16x16x32_bf16 v[44:47], v[166:169], v[198:201], v[44:47]
	v_mfma_f32_16x16x32_bf16 v[36:39], v[152:155], v[206:209], v[36:39]
	v_mfma_f32_16x16x32_bf16 v[28:31], v[166:169], v[206:209], v[28:31]
	v_mfma_f32_16x16x32_bf16 v[20:23], v[152:155], v[214:217], v[20:23]
	v_mfma_f32_16x16x32_bf16 v[12:15], v[166:169], v[214:217], v[12:15]
	v_mfma_f32_16x16x32_bf16 v[48:51], v[170:173], v[186:189], v[48:51]
	v_mfma_f32_16x16x32_bf16 v[40:43], v[178:181], v[186:189], v[40:43]
	v_mfma_f32_16x16x32_bf16 v[32:35], v[170:173], v[194:197], v[32:35]
	v_mfma_f32_16x16x32_bf16 v[24:27], v[178:181], v[194:197], v[24:27]
	v_mfma_f32_16x16x32_bf16 v[16:19], v[170:173], v[202:205], v[16:19]
	v_mfma_f32_16x16x32_bf16 v[8:11], v[178:181], v[202:205], v[8:11]
	v_mfma_f32_16x16x32_bf16 v[4:7], v[170:173], v[210:213], v[4:7]
	v_mfma_f32_16x16x32_bf16 v[0:3], v[178:181], v[210:213], v[0:3]
	v_mfma_f32_16x16x32_bf16 v[48:51], v[174:177], v[190:193], v[48:51]
	v_mfma_f32_16x16x32_bf16 v[40:43], v[182:185], v[190:193], v[40:43]
	v_mfma_f32_16x16x32_bf16 v[32:35], v[174:177], v[198:201], v[32:35]
	v_mfma_f32_16x16x32_bf16 v[24:27], v[182:185], v[198:201], v[24:27]
	v_mfma_f32_16x16x32_bf16 v[16:19], v[174:177], v[206:209], v[16:19]
	v_mfma_f32_16x16x32_bf16 v[8:11], v[182:185], v[206:209], v[8:11]
	v_mfma_f32_16x16x32_bf16 v[4:7], v[174:177], v[214:217], v[4:7]
	v_mfma_f32_16x16x32_bf16 v[0:3], v[182:185], v[214:217], v[0:3]
	s_barrier
	s_setprio 1
	s_movk_i32 s50, 0x100
	s_andn2_b64 vcc, exec, s[46:47]
	s_mov_b64 s[48:49], -1
	s_mov_b64 s[46:47], 0
	s_cbranch_vccz .LBB0_1262
	s_and_b64 vcc, exec, s[10:11]
	s_cbranch_vccz .LBB0_1265
	s_barrier

; #define PG8_STAGE(bufoff, gbase, voff) do { _Pragma("unroll") for (int _i = 0; _i < 2; ++_i) \
;         __builtin_amdgcn_global_load_lds((const unsigned*)((const char*)(gbase) + (voff)[_i]), (PG8_LAS unsigned*)(lds + (bufoff) + ldsw + _i * 8192), 16, 0, 0); } while (0)
; #define PG8_LDA(dst, b, h) do { _Pragma("unroll") for (int m = 0; m < 4; ++m) _Pragma("unroll") for (int k = 0; k < 2; ++k) dst[m][k] = *(const PG8_LAS bf16x8*)(lds + PG8_SA(b, h) + aoff + m * 2048 + k * 1024); } while (0)
; #define PG8_LDB(dst, b, h) do { _Pragma("unroll") for (int n = 0; n < 2; ++n) _Pragma("unroll") for (int k = 0; k < 2; ++k) dst[n][k] = *(const PG8_LAS bf16x8*)(lds + PG8_SB(b, h) + boff + n * 2048 + k * 1024); } while (0)
; #define PG8_MMA(ai, bj, At, Bt) do { __builtin_amdgcn_s_setprio(1); _Pragma("unroll") for (int m = 0; m < 4; ++m) _Pragma("unroll") for (int n = 0; n < 2; ++n) _Pragma("unroll") for (int k = 0; k < 2; ++k) \
;         acc[ai][bj][m][n] = __builtin_amdgcn_mfma_f32_16x16x32_bf16(Bt[n][k], At[m][k], acc[ai][bj][m][n], 0, 0, 0); __builtin_amdgcn_s_setprio(0); } while (0)
; #define PG8_WAIT_V(n) asm volatile("s_waitcnt vmcnt(" #n ")" ::: "memory")
; #define PG8_WAIT_L(n) asm volatile("s_waitcnt lgkmcnt(" #n ")" ::: "memory")
; template <class Epi, class Sched, bool ALIGN_EPI = false, bool SP2 = false>
; __device__ __forceinline__ void gemm_phase(PG8_LAS unsigned char* lds, const Gemm g, const Sched& S, const Epi& E) {
;     ...
;             const bool last = (t == nt - 2);
;             const char* a1 = cA + (size_t)(t + 1) * kstep;
;             const char* a2 = last ? nA : cA + (size_t)(t + 2) * kstep; const char* b2 = last ? nB : cB + (size_t)(t + 2) * kstep;
;             const char* a3 = a2 + kstep; const char* b3 = b2 + kstep;
;             if (last && has_next) S.a_ready(nxt);
;             if constexpr (SP2) {
;             PG8_LDB(B0, 0, 0); PG8_LDB(B1, 0, 1); PG8_SCHED; PG8_LDA(At, 0, 0); PG8_STAGE(PG8_SA(1, 1), a1 + hstepA, voffA);
;             PG8_WAIT_V(8); PG8_WAIT_L(0); PG8_BAR; PG8_MMA(0, 0, At, B0); PG8_MMA(0, 1, At, B1); PG8_BAR; PG8_SCHED;
;             PG8_LDA(At, 0, 1); PG8_STAGE(PG8_SB(0, 0), b2, voffB); PG8_STAGE(PG8_SB(0, 1), b2 + hstepB, voffB); PG8_STAGE(PG8_SA(0, 0), a2, voffA);
;             PG8_WAIT_V(8); PG8_WAIT_L(0); PG8_BAR; PG8_MMA(1, 0, At, B0); PG8_MMA(1, 1, At, B1); PG8_BAR; PG8_SCHED;
.LBB0_1333:
	ds_read_b128 v[144:147], v153
	ds_read_b128 v[156:159], v153 offset:1024
	ds_read_b128 v[166:169], v153 offset:2048
	ds_read_b128 v[170:173], v153 offset:3072
	ds_read_b128 v[174:177], v154
	ds_read_b128 v[178:181], v154 offset:1024
	ds_read_b128 v[182:185], v154 offset:2048
	ds_read_b128 v[186:189], v154 offset:3072
	s_add_u32 s46, s44, 0xfff80080
	s_addc_u32 s47, s45, -1
	s_cmp_eq_u32 s62, 28
	s_cselect_b32 s49, s37, s47
	s_cselect_b32 s48, s58, s46
	s_cselect_b32 s47, s23, s61
	s_cselect_b32 s46, s59, s60
	s_add_i32 m0, s30, 0xc000
	ds_read_b128 v[190:193], v155
	ds_read_b128 v[194:197], v155 offset:1024
	ds_read_b128 v[198:201], v155 offset:2048
	ds_read_b128 v[202:205], v155 offset:3072
	ds_read_b128 v[206:209], v155 offset:4096
	ds_read_b128 v[210:213], v155 offset:5120
	ds_read_b128 v[214:217], v155 offset:6144
	ds_read_b128 v[218:221], v155 offset:7168
	global_load_lds_dwordx4 v136, s[44:45]
	s_add_i32 m0, s30, 0xe000
	s_nop 0
	global_load_lds_dwordx4 v138, s[44:45]
	s_waitcnt vmcnt(8)
	s_waitcnt lgkmcnt(0)
	s_setprio 0
	s_barrier
	v_mfma_f32_16x16x32_bf16 v[124:127], v[144:147], v[190:193], v[124:127]
	v_mfma_f32_16x16x32_bf16 v[120:123], v[166:169], v[190:193], v[120:123]
	v_mfma_f32_16x16x32_bf16 v[108:111], v[144:147], v[198:201], v[108:111]
	v_mfma_f32_16x16x32_bf16 v[104:107], v[166:169], v[198:201], v[104:107]
	v_mfma_f32_16x16x32_bf16 v[92:95], v[144:147], v[206:209], v[92:95]
	v_mfma_f32_16x16x32_bf16 v[88:91], v[166:169], v[206:209], v[88:91]
	v_mfma_f32_16x16x32_bf16 v[76:79], v[144:147], v[214:217], v[76:79]
	v_mfma_f32_16x16x32_bf16 v[72:75], v[166:169], v[214:217], v[72:75]
	v_mfma_f32_16x16x32_bf16 v[124:127], v[156:159], v[194:197], v[124:127]
	v_mfma_f32_16x16x32_bf16 v[120:123], v[170:173], v[194:197], v[120:123]
	v_mfma_f32_16x16x32_bf16 v[108:111], v[156:159], v[202:205], v[108:111]
	v_mfma_f32_16x16x32_bf16 v[104:107], v[170:173], v[202:205], v[104:107]
	v_mfma_f32_16x16x32_bf16 v[92:95], v[156:159], v[210:213], v[92:95]
	v_mfma_f32_16x16x32_bf16 v[88:91], v[170:173], v[210:213], v[88:91]
	v_mfma_f32_16x16x32_bf16 v[76:79], v[156:159], v[218:221], v[76:79]
	v_mfma_f32_16x16x32_bf16 v[72:75], v[170:173], v[218:221], v[72:75]
	v_mfma_f32_16x16x32_bf16 v[116:119], v[174:177], v[190:193], v[116:119]
	v_mfma_f32_16x16x32_bf16 v[112:115], v[182:185], v[190:193], v[112:115]
	v_mfma_f32_16x16x32_bf16 v[100:103], v[174:177], v[198:201], v[100:103]
	v_mfma_f32_16x16x32_bf16 v[96:99], v[182:185], v[198:201], v[96:99]
	v_mfma_f32_16x16x32_bf16 v[84:87], v[174:177], v[206:209], v[84:87]
	v_mfma_f32_16x16x32_bf16 v[80:83], v[182:185], v[206:209], v[80:83]
	v_mfma_f32_16x16x32_bf16 v[68:71], v[174:177], v[214:217], v[68:71]
	v_mfma_f32_16x16x32_bf16 v[64:67], v[182:185], v[214:217], v[64:67]
	v_mfma_f32_16x16x32_bf16 v[116:119], v[178:181], v[194:197], v[116:119]
	v_mfma_f32_16x16x32_bf16 v[112:115], v[186:189], v[194:197], v[112:115]
	v_mfma_f32_16x16x32_bf16 v[100:103], v[178:181], v[202:205], v[100:103]
	v_mfma_f32_16x16x32_bf16 v[96:99], v[186:189], v[202:205], v[96:99]
	v_mfma_f32_16x16x32_bf16 v[84:87], v[178:181], v[210:213], v[84:87]
	v_mfma_f32_16x16x32_bf16 v[80:83], v[186:189], v[210:213], v[80:83]
	v_mfma_f32_16x16x32_bf16 v[68:71], v[178:181], v[218:221], v[68:71]
	v_mfma_f32_16x16x32_bf16 v[64:67], v[186:189], v[218:221], v[64:67]
	s_barrier
	s_setprio 1
	s_add_u32 s98, s46, s10
	s_addc_u32 s99, s47, s11
	s_add_u32 s100, s48, s10
	s_addc_u32 s101, s49, s11
	s_add_i32 s63, s51, s28
	s_mov_b32 m0, s63
	ds_read_b128 v[190:193], v155 offset:16384
	ds_read_b128 v[194:197], v155 offset:17408
	ds_read_b128 v[198:201], v155 offset:18432
	ds_read_b128 v[202:205], v155 offset:19456
	ds_read_b128 v[206:209], v155 offset:20480
	ds_read_b128 v[210:213], v155 offset:21504
	ds_read_b128 v[214:217], v155 offset:22528
	ds_read_b128 v[218:221], v155 offset:23552
	global_load_lds_dwordx4 v132, s[46:47]
	s_add_i32 m0, s63, 0x2000
	s_add_u32 s64, s46, 0x80000
	s_addc_u32 s65, s47, 0
	s_add_i32 s63, s52, s28
	global_load_lds_dwordx4 v128, s[46:47]
	s_mov_b32 m0, s63
	s_nop 0
	global_load_lds_dwordx4 v132, s[64:65]
	s_add_i32 m0, s63, 0x2000
	s_nop 0
	global_load_lds_dwordx4 v128, s[64:65]
	s_mov_b32 m0, s30
	s_nop 0
	global_load_lds_dwordx4 v134, s[48:49]
	s_mov_b32 m0, s31
	s_nop 0
	global_load_lds_dwordx4 v130, s[48:49]
	s_waitcnt vmcnt(8)
	s_waitcnt lgkmcnt(0)
	s_setprio 0
	s_barrier
	v_mfma_f32_16x16x32_bf16 v[60:63], v[144:147], v[190:193], v[60:63]
	v_mfma_f32_16x16x32_bf16 v[56:59], v[166:169], v[190:193], v[56:59]
	v_mfma_f32_16x16x32_bf16 v[44:47], v[144:147], v[198:201], v[44:47]
	v_mfma_f32_16x16x32_bf16 v[40:43], v[166:169], v[198:201], v[40:43]
	v_mfma_f32_16x16x32_bf16 v[28:31], v[144:147], v[206:209], v[28:31]
	v_mfma_f32_16x16x32_bf16 v[24:27], v[166:169], v[206:209], v[24:27]
	v_mfma_f32_16x16x32_bf16 v[12:15], v[144:147], v[214:217], v[12:15]
	v_mfma_f32_16x16x32_bf16 v[8:11], v[166:169], v[214:217], v[8:11]
	v_mfma_f32_16x16x32_bf16 v[60:63], v[156:159], v[194:197], v[60:63]
	v_mfma_f32_16x16x32_bf16 v[56:59], v[170:173], v[194:197], v[56:59]
	v_mfma_f32_16x16x32_bf16 v[44:47], v[156:159], v[202:205], v[44:47]
	v_mfma_f32_16x16x32_bf16 v[40:43], v[170:173], v[202:205], v[40:43]
	v_mfma_f32_16x16x32_bf16 v[28:31], v[156:159], v[210:213], v[28:31]
	v_mfma_f32_16x16x32_bf16 v[24:27], v[170:173], v[210:213], v[24:27]
	v_mfma_f32_16x16x32_bf16 v[12:15], v[156:159], v[218:221], v[12:15]
	v_mfma_f32_16x16x32_bf16 v[8:11], v[170:173], v[218:221], v[8:11]
	v_mfma_f32_16x16x32_bf16 v[52:55], v[174:177], v[190:193], v[52:55]
	v_mfma_f32_16x16x32_bf16 v[48:51], v[182:185], v[190:193], v[48:51]
	v_mfma_f32_16x16x32_bf16 v[36:39], v[174:177], v[198:201], v[36:39]
	v_mfma_f32_16x16x32_bf16 v[32:35], v[182:185], v[198:201], v[32:35]
	v_mfma_f32_16x16x32_bf16 v[20:23], v[174:177], v[206:209], v[20:23]
	v_mfma_f32_16x16x32_bf16 v[16:19], v[182:185], v[206:209], v[16:19]
	v_mfma_f32_16x16x32_bf16 v[4:7], v[174:177], v[214:217], v[4:7]
	v_mfma_f32_16x16x32_bf16 v[0:3], v[182:185], v[214:217], v[0:3]
	v_mfma_f32_16x16x32_bf16 v[52:55], v[178:181], v[194:197], v[52:55]
	v_mfma_f32_16x16x32_bf16 v[48:51], v[186:189], v[194:197], v[48:51]
	v_mfma_f32_16x16x32_bf16 v[36:39], v[178:181], v[202:205], v[36:39]
	v_mfma_f32_16x16x32_bf16 v[32:35], v[186:189], v[202:205], v[32:35]
	v_mfma_f32_16x16x32_bf16 v[20:23], v[178:181], v[210:213], v[20:23]
	v_mfma_f32_16x16x32_bf16 v[16:19], v[186:189], v[210:213], v[16:19]
	v_mfma_f32_16x16x32_bf16 v[4:7], v[178:181], v[218:221], v[4:7]
	v_mfma_f32_16x16x32_bf16 v[0:3], v[186:189], v[218:221], v[0:3]
	s_barrier
; #define PG8_STAGE(bufoff, gbase, voff) do { _Pragma("unroll") for (int _i = 0; _i < 2; ++_i) \
;         __builtin_amdgcn_global_load_lds((const unsigned*)((const char*)(gbase) + (voff)[_i]), (PG8_LAS unsigned*)(lds + (bufoff) + ldsw + _i * 8192), 16, 0, 0); } while (0)
; #define PG8_LDA(dst, b, h) do { _Pragma("unroll") for (int m = 0; m < 4; ++m) _Pragma("unroll") for (int k = 0; k < 2; ++k) dst[m][k] = *(const PG8_LAS bf16x8*)(lds + PG8_SA(b, h) + aoff + m * 2048 + k * 1024); } while (0)
; #define PG8_LDB(dst, b, h) do { _Pragma("unroll") for (int n = 0; n < 2; ++n) _Pragma("unroll") for (int k = 0; k < 2; ++k) dst[n][k] = *(const PG8_LAS bf16x8*)(lds + PG8_SB(b, h) + boff + n * 2048 + k * 1024); } while (0)
; #define PG8_MMA(ai, bj, At, Bt) do { __builtin_amdgcn_s_setprio(1); _Pragma("unroll") for (int m = 0; m < 4; ++m) _Pragma("unroll") for (int n = 0; n < 2; ++n) _Pragma("unroll") for (int k = 0; k < 2; ++k) \
;         acc[ai][bj][m][n] = __builtin_amdgcn_mfma_f32_16x16x32_bf16(Bt[n][k], At[m][k], acc[ai][bj][m][n], 0, 0, 0); __builtin_amdgcn_s_setprio(0); } while (0)
; #define PG8_WAIT_V(n) asm volatile("s_waitcnt vmcnt(" #n ")" ::: "memory")
; #define PG8_WAIT_L(n) asm volatile("s_waitcnt lgkmcnt(" #n ")" ::: "memory")
; #define PG8_BAR __builtin_amdgcn_s_barrier()
; #define PG8_SCHED __builtin_amdgcn_sched_barrier(0)
; template <class Epi, class Sched, bool ALIGN_EPI = false, bool SP2 = false>
; __device__ __forceinline__ void gemm_phase(PG8_LAS unsigned char* lds, const Gemm g, const Sched& S, const Epi& E) {
;     ...
;             PG8_LDB(B0, 1, 0); PG8_LDB(B1, 1, 1); PG8_SCHED; PG8_LDA(At, 1, 0); PG8_STAGE(PG8_SA(0, 1), a2 + hstepA, voffA);
;             PG8_WAIT_V(8); PG8_WAIT_L(0); PG8_BAR; PG8_MMA(0, 0, At, B0); PG8_MMA(0, 1, At, B1); PG8_BAR; PG8_SCHED;
;             PG8_LDA(At, 1, 1); PG8_STAGE(PG8_SB(1, 0), b3, voffB); PG8_STAGE(PG8_SB(1, 1), b3 + hstepB, voffB); PG8_STAGE(PG8_SA(1, 0), a3, voffA);
;             PG8_WAIT_V(8); PG8_WAIT_L(0); PG8_BAR; PG8_MMA(1, 0, At, B0); PG8_MMA(1, 1, At, B1); PG8_BAR; PG8_SCHED;
	s_setprio 1
	s_add_i32 s63, 0, 0x18000
	v_add_u32_e32 v163, s63, v151
	s_add_i32 s64, 0, 0x1c000
	ds_read_b128 v[144:147], v163
	ds_read_b128 v[156:159], v163 offset:1024
	ds_read_b128 v[166:169], v163 offset:2048
	ds_read_b128 v[170:173], v163 offset:3072
	v_add_u32_e32 v163, s64, v151
	ds_read_b128 v[174:177], v163
	ds_read_b128 v[178:181], v163 offset:1024
	ds_read_b128 v[182:185], v163 offset:2048
	ds_read_b128 v[186:189], v163 offset:3072
	s_add_u32 s48, s48, 0x80000
	s_addc_u32 s49, s49, 0
	s_mov_b32 m0, s33
	ds_read_b128 v[190:193], v155 offset:32768
	ds_read_b128 v[194:197], v155 offset:33792
	ds_read_b128 v[198:201], v155 offset:34816
	ds_read_b128 v[202:205], v155 offset:35840
	ds_read_b128 v[206:209], v155 offset:36864
	ds_read_b128 v[210:213], v155 offset:37888
	ds_read_b128 v[214:217], v155 offset:38912
	ds_read_b128 v[218:221], v155 offset:39936
	global_load_lds_dwordx4 v134, s[48:49]
	s_mov_b32 m0, s34
	s_nop 0
	global_load_lds_dwordx4 v130, s[48:49]
	s_waitcnt vmcnt(8)
	s_waitcnt lgkmcnt(0)
	s_setprio 0
	s_barrier
	v_mfma_f32_16x16x32_bf16 v[124:127], v[144:147], v[190:193], v[124:127]
	v_mfma_f32_16x16x32_bf16 v[120:123], v[166:169], v[190:193], v[120:123]
	v_mfma_f32_16x16x32_bf16 v[108:111], v[144:147], v[198:201], v[108:111]
	v_mfma_f32_16x16x32_bf16 v[104:107], v[166:169], v[198:201], v[104:107]
	v_mfma_f32_16x16x32_bf16 v[92:95], v[144:147], v[206:209], v[92:95]
	v_mfma_f32_16x16x32_bf16 v[88:91], v[166:169], v[206:209], v[88:91]
	v_mfma_f32_16x16x32_bf16 v[76:79], v[144:147], v[214:217], v[76:79]
	v_mfma_f32_16x16x32_bf16 v[72:75], v[166:169], v[214:217], v[72:75]
	v_mfma_f32_16x16x32_bf16 v[124:127], v[156:159], v[194:197], v[124:127]
	v_mfma_f32_16x16x32_bf16 v[120:123], v[170:173], v[194:197], v[120:123]
	v_mfma_f32_16x16x32_bf16 v[108:111], v[156:159], v[202:205], v[108:111]
	v_mfma_f32_16x16x32_bf16 v[104:107], v[170:173], v[202:205], v[104:107]
	v_mfma_f32_16x16x32_bf16 v[92:95], v[156:159], v[210:213], v[92:95]
	v_mfma_f32_16x16x32_bf16 v[88:91], v[170:173], v[210:213], v[88:91]
	v_mfma_f32_16x16x32_bf16 v[76:79], v[156:159], v[218:221], v[76:79]
	v_mfma_f32_16x16x32_bf16 v[72:75], v[170:173], v[218:221], v[72:75]
	v_mfma_f32_16x16x32_bf16 v[116:119], v[174:177], v[190:193], v[116:119]
	v_mfma_f32_16x16x32_bf16 v[112:115], v[182:185], v[190:193], v[112:115]
	v_mfma_f32_16x16x32_bf16 v[100:103], v[174:177], v[198:201], v[100:103]
	v_mfma_f32_16x16x32_bf16 v[96:99], v[182:185], v[198:201], v[96:99]
	v_mfma_f32_16x16x32_bf16 v[84:87], v[174:177], v[206:209], v[84:87]
	v_mfma_f32_16x16x32_bf16 v[80:83], v[182:185], v[206:209], v[80:83]
	v_mfma_f32_16x16x32_bf16 v[68:71], v[174:177], v[214:217], v[68:71]
	v_mfma_f32_16x16x32_bf16 v[64:67], v[182:185], v[214:217], v[64:67]
	v_mfma_f32_16x16x32_bf16 v[116:119], v[178:181], v[194:197], v[116:119]
	v_mfma_f32_16x16x32_bf16 v[112:115], v[186:189], v[194:197], v[112:115]
	v_mfma_f32_16x16x32_bf16 v[100:103], v[178:181], v[202:205], v[100:103]
	v_mfma_f32_16x16x32_bf16 v[96:99], v[186:189], v[202:205], v[96:99]
	v_mfma_f32_16x16x32_bf16 v[84:87], v[178:181], v[210:213], v[84:87]
	v_mfma_f32_16x16x32_bf16 v[80:83], v[186:189], v[210:213], v[80:83]
	v_mfma_f32_16x16x32_bf16 v[68:71], v[178:181], v[218:221], v[68:71]
	v_mfma_f32_16x16x32_bf16 v[64:67], v[186:189], v[218:221], v[64:67]
	s_barrier
	s_setprio 1
	s_add_i32 s48, s63, s28
	s_mov_b32 m0, s48
	ds_read_b128 v[190:193], v155 offset:49152
	ds_read_b128 v[194:197], v155 offset:50176
	ds_read_b128 v[198:201], v155 offset:51200
	ds_read_b128 v[202:205], v155 offset:52224
	ds_read_b128 v[206:209], v155 offset:53248
	ds_read_b128 v[210:213], v155 offset:54272
	ds_read_b128 v[214:217], v155 offset:55296
	ds_read_b128 v[218:221], v155 offset:56320
	global_load_lds_dwordx4 v132, s[98:99]
	s_add_i32 m0, s48, 0x2000
	s_add_u32 s46, s46, 0x80080
	s_addc_u32 s47, s47, 0
	s_add_i32 s48, s64, s28
	global_load_lds_dwordx4 v128, s[98:99]
	s_mov_b32 m0, s48
	s_nop 0
	global_load_lds_dwordx4 v132, s[46:47]
	s_add_i32 m0, s48, 0x2000
	s_nop 0
	global_load_lds_dwordx4 v128, s[46:47]
	s_mov_b32 m0, s43
	s_nop 0
	global_load_lds_dwordx4 v134, s[100:101]
	s_mov_b32 m0, s50
	s_nop 0
	global_load_lds_dwordx4 v130, s[100:101]
	s_waitcnt vmcnt(8)
	s_waitcnt lgkmcnt(0)
	s_setprio 0
	s_barrier
	v_mfma_f32_16x16x32_bf16 v[60:63], v[144:147], v[190:193], v[60:63]
	v_mfma_f32_16x16x32_bf16 v[56:59], v[166:169], v[190:193], v[56:59]
	v_mfma_f32_16x16x32_bf16 v[44:47], v[144:147], v[198:201], v[44:47]
	v_mfma_f32_16x16x32_bf16 v[40:43], v[166:169], v[198:201], v[40:43]
	v_mfma_f32_16x16x32_bf16 v[28:31], v[144:147], v[206:209], v[28:31]
	v_mfma_f32_16x16x32_bf16 v[24:27], v[166:169], v[206:209], v[24:27]
	v_mfma_f32_16x16x32_bf16 v[12:15], v[144:147], v[214:217], v[12:15]
	v_mfma_f32_16x16x32_bf16 v[8:11], v[166:169], v[214:217], v[8:11]
	v_mfma_f32_16x16x32_bf16 v[60:63], v[156:159], v[194:197], v[60:63]
	v_mfma_f32_16x16x32_bf16 v[56:59], v[170:173], v[194:197], v[56:59]
	v_mfma_f32_16x16x32_bf16 v[44:47], v[156:159], v[202:205], v[44:47]
	v_mfma_f32_16x16x32_bf16 v[40:43], v[170:173], v[202:205], v[40:43]
	v_mfma_f32_16x16x32_bf16 v[28:31], v[156:159], v[210:213], v[28:31]
	v_mfma_f32_16x16x32_bf16 v[24:27], v[170:173], v[210:213], v[24:27]
	v_mfma_f32_16x16x32_bf16 v[12:15], v[156:159], v[218:221], v[12:15]
	v_mfma_f32_16x16x32_bf16 v[8:11], v[170:173], v[218:221], v[8:11]
	v_mfma_f32_16x16x32_bf16 v[52:55], v[174:177], v[190:193], v[52:55]
	v_mfma_f32_16x16x32_bf16 v[48:51], v[182:185], v[190:193], v[48:51]
	v_mfma_f32_16x16x32_bf16 v[36:39], v[174:177], v[198:201], v[36:39]
	v_mfma_f32_16x16x32_bf16 v[32:35], v[182:185], v[198:201], v[32:35]
	v_mfma_f32_16x16x32_bf16 v[20:23], v[174:177], v[206:209], v[20:23]
	v_mfma_f32_16x16x32_bf16 v[16:19], v[182:185], v[206:209], v[16:19]
	v_mfma_f32_16x16x32_bf16 v[4:7], v[174:177], v[214:217], v[4:7]
	v_mfma_f32_16x16x32_bf16 v[0:3], v[182:185], v[214:217], v[0:3]
	v_mfma_f32_16x16x32_bf16 v[52:55], v[178:181], v[194:197], v[52:55]
	v_mfma_f32_16x16x32_bf16 v[48:51], v[186:189], v[194:197], v[48:51]
	v_mfma_f32_16x16x32_bf16 v[36:39], v[178:181], v[202:205], v[36:39]
	v_mfma_f32_16x16x32_bf16 v[32:35], v[186:189], v[202:205], v[32:35]
	v_mfma_f32_16x16x32_bf16 v[20:23], v[178:181], v[210:213], v[20:23]
	v_mfma_f32_16x16x32_bf16 v[16:19], v[186:189], v[210:213], v[16:19]
	v_mfma_f32_16x16x32_bf16 v[4:7], v[178:181], v[218:221], v[4:7]
	v_mfma_f32_16x16x32_bf16 v[0:3], v[186:189], v[218:221], v[0:3]
	s_barrier
	s_setprio 1
	s_add_i32 s62, s62, 2
	s_add_u32 s44, s44, 0x100
	s_addc_u32 s45, s45, 0
	s_add_u32 s60, s60, 0x100
	s_addc_u32 s61, s61, 0
	s_cmp_gt_u32 s62, 29
	s_cbranch_scc0 .LBB0_1333
	s_and_b64 vcc, exec, s[14:15]
	s_cbranch_vccz .LBB0_1336
	s_barrier

; __global__ void __launch_bounds__(NTHR, 2) fwd_megakernel(Args args) {
	.amdhsa_kernel _Z14fwd_megakernel4Args
		.amdhsa_group_segment_fixed_size 0
		.amdhsa_private_segment_fixed_size 0
		.amdhsa_kernarg_size 464
		.amdhsa_user_sgpr_count 2
		.amdhsa_user_sgpr_dispatch_ptr 0
		.amdhsa_user_sgpr_queue_ptr 0
		.amdhsa_user_sgpr_kernarg_segment_ptr 1
		.amdhsa_user_sgpr_dispatch_id 0
		.amdhsa_user_sgpr_kernarg_preload_length 0
		.amdhsa_user_sgpr_kernarg_preload_offset 0
		.amdhsa_user_sgpr_private_segment_size 0
		.amdhsa_uses_dynamic_stack 0
		.amdhsa_enable_private_segment 0
		.amdhsa_system_sgpr_workgroup_id_x 1
		.amdhsa_system_sgpr_workgroup_id_y 0
		.amdhsa_system_sgpr_workgroup_id_z 0
		.amdhsa_system_sgpr_workgroup_info 0
		.amdhsa_system_vgpr_workitem_id 2
		.amdhsa_next_free_vgpr 241
		.amdhsa_next_free_sgpr 102
		.amdhsa_accum_offset 244
		.amdhsa_reserve_vcc 1
		.amdhsa_float_round_mode_32 0
		.amdhsa_float_round_mode_16_64 0
		.amdhsa_float_denorm_mode_32 3
		.amdhsa_float_denorm_mode_16_64 3
		.amdhsa_dx10_clamp 1
		.amdhsa_ieee_mode 1
		.amdhsa_fp16_overflow 0
		.amdhsa_tg_split 0
		.amdhsa_exception_fp_ieee_invalid_op 0
		.amdhsa_exception_fp_denorm_src 0
		.amdhsa_exception_fp_ieee_div_zero 0
		.amdhsa_exception_fp_ieee_overflow 0
		.amdhsa_exception_fp_ieee_underflow 0
		.amdhsa_exception_fp_ieee_inexact 0
		.amdhsa_exception_int_div_zero 0
	.end_amdhsa_kernel

; __global__ void __launch_bounds__(NTHR, 2) fwd_megakernel(Args args) {
amdhsa.kernels:
  - .agpr_count:     0
    .args:
      - .offset:         0
        .size:           208
        .value_kind:     by_value
      - .offset:         208
        .size:           4
        .value_kind:     hidden_block_count_x
      - .offset:         212
        .size:           4
        .value_kind:     hidden_block_count_y
      - .offset:         216
        .size:           4
        .value_kind:     hidden_block_count_z
      - .offset:         220
        .size:           2
        .value_kind:     hidden_group_size_x
      - .offset:         222
        .size:           2
        .value_kind:     hidden_group_size_y
      - .offset:         224
        .size:           2
        .value_kind:     hidden_group_size_z
      - .offset:         226
        .size:           2
        .value_kind:     hidden_remainder_x
      - .offset:         228
        .size:           2
        .value_kind:     hidden_remainder_y
      - .offset:         230
        .size:           2
        .value_kind:     hidden_remainder_z
      - .offset:         248
        .size:           8
        .value_kind:     hidden_global_offset_x
      - .offset:         256
        .size:           8
        .value_kind:     hidden_global_offset_y
      - .offset:         264
        .size:           8
        .value_kind:     hidden_global_offset_z
      - .offset:         272
        .size:           2
        .value_kind:     hidden_grid_dims
      - .offset:         296
        .size:           8
        .value_kind:     hidden_multigrid_sync_arg
      - .offset:         328
        .size:           4
        .value_kind:     hidden_dynamic_lds_size
    .group_segment_fixed_size: 0
    .kernarg_segment_align: 8
    .kernarg_segment_size: 464
    .language:       OpenCL C
    .language_version:
      - 2
      - 0
    .max_flat_workgroup_size: 512
    .name:           _Z14fwd_megakernel4Args
    .private_segment_fixed_size: 0
    .sgpr_count:     108
    .sgpr_spill_count: 42
    .symbol:         _Z14fwd_megakernel4Args.kd
    .uniform_work_group_size: 1
    .uses_dynamic_stack: false
    .vgpr_count:     241
    .vgpr_spill_count: 0
    .wavefront_size: 64
